# IN units: epilogue stores drain under the next unit's first 3 main-loop segments (A(1,1) tile pre-staged before the stores, unit-top vmcnt(0)->vmcnt(16), peeled first iteration without vmcnt waits)
# baseline (speedup 1.0000x reference)
; #define PG8_STAGE(bufoff, gbase) do { _Pragma("unroll") for (int _i = 0; _i < 2; ++_i) \
;         __builtin_amdgcn_global_load_lds((const unsigned*)((const char*)(gbase) + voffA[_i]), (LAS unsigned*)(lds + (bufoff) + ldsw + _i * 8192), 16, 0, 0); } while (0)
; #define PG8_LDA(dst, b, h) do { _Pragma("unroll") for (int m = 0; m < 4; ++m) _Pragma("unroll") for (int k = 0; k < 2; ++k) dst[m][k] = *(const LAS h16x8*)(lds + PG8_SA(b, h) + aoff + m * 2048 + k * 1024); } while (0)
; #define PG8_LDA1(dst, b) do { if constexpr (!HALFM) PG8_LDA(dst, b, 1); } while (0)
; #define PG8_BAR __builtin_amdgcn_s_barrier()
; template <class Epi, bool ALIGN_EPI, bool SP2, bool BF = false, bool HALFM = false, class Order = StaticOrder>
; __device__ __forceinline__ void gemm_phase(LAS unsigned char* lds, const int tid, const Gemm g, const Order& S, const Epi& E, const bool dry = false) {
;     ...
;     if constexpr (SP2) {
;         PG8_STAGE(PG8_SB(0, 0), cB); PG8_STAGE(PG8_SB(0, 1), cB + hstep); PG8_STAGE(PG8_SA(0, 0), cA); PG8_STAGE(PG8_SA(0, 1), cA + hstep);
;         if (wr == 1) PG8_BAR;
;         PG8_WAIT_V(2); PG8_BAR;
;         PG8_STAGE(PG8_SB(1, 0), cB + kstep); PG8_STAGE(PG8_SA(1, 0), cA + kstep); PG8_STAGE(PG8_SB(1, 1), cB + hstep + kstep);
;         PG8_WAIT_V(6); PG8_BAR;
;     } else {
;         PG8_STAGE(PG8_SB(0, 0), cB); PG8_STAGE(PG8_SA(0, 0), cA); PG8_STAGE(PG8_SB(0, 1), cB + hstep); PG8_STAGE(PG8_SA(0, 1), cA + hstep);
;         if (wr == 1) PG8_BAR;
;         PG8_WAIT_V(4); PG8_BAR;
;         PG8_STAGE(PG8_SB(1, 0), cB + kstep); PG8_STAGE(PG8_SA(1, 0), cA + kstep); PG8_STAGE(PG8_SB(1, 1), cB + hstep + kstep);
;         PG8_WAIT_V(6); PG8_BAR;
;     }
;     ...
;             PG8_LDB(B0, 0, 0); PG8_LDB(B1, 0, 1); PG8_SCHED; PG8_LDA(At, 0, 0); PG8_STAGE(PG8_SA(1, 1), a1 + hstep);
;             PG8_WAIT_V(8); PG8_WAIT_L(0); PG8_BAR; PG8_MMA(0, 0, At, B0); PG8_MMA(0, 1, At, B1); PG8_BAR; PG8_SCHED;
;             PG8_LDA1(At, 0); PG8_STAGE(PG8_SB(0, 0), b2); PG8_STAGE(PG8_SB(0, 1), b2 + hstep); PG8_STAGE(PG8_SA(0, 0), a2);
;             PG8_WAIT_V(8); PG8_WAIT_L(0); PG8_BAR; PG8_MMA1(At, B0, B1); PG8_BAR; PG8_SCHED;
;             PG8_LDB(B0, 1, 0); PG8_LDB(B1, 1, 1); PG8_SCHED; PG8_LDA(At, 1, 0); PG8_STAGE(PG8_SA(0, 1), a2 + hstep);
;             PG8_WAIT_V(8); PG8_WAIT_L(0); PG8_BAR; PG8_MMA(0, 0, At, B0); PG8_MMA(0, 1, At, B1); PG8_BAR; PG8_SCHED;
.LBB0_555:
	s_lshl_b32 s12, s66, 4
	s_mul_i32 s3, s66, 0x3b800
	s_lshl_b32 s0, s66, 6
	s_ashr_i32 s13, s12, 31
	v_readlane_b32 s56, v252, 28
	s_ashr_i32 s1, s0, 31
	s_lshl_b64 s[12:13], s[12:13], 2
	v_readlane_b32 s64, v252, 36
	v_bfe_u32 v197, v246, 4, 2
	v_readlane_b32 s65, v252, 37
	s_add_u32 s12, s64, s12
	v_and_b32_e32 v196, 15, v246
	v_lshlrev_b32_e32 v16, 4, v197
	v_lshlrev_b32_e32 v17, 2, v246
	s_addc_u32 s13, s65, s13
	s_and_b32 s76, s10, 3
	v_lshl_or_b32 v16, v196, 6, v16
	s_lshl_b32 s5, s11, 13
	v_and_b32_e32 v17, 32, v17
	s_add_i32 s79, s74, 0x18000
	v_bitop3_b32 v18, v16, s5, v17 bitop3:0xde
	s_lshl_b32 s5, s76, 12
	s_add_i32 s80, s79, s9
	s_lshl_b32 s77, s11, 6
	v_bitop3_b32 v198, s5, v16, v17 bitop3:0xf6
	s_add_i32 s5, s74, 0x20400
	v_lshl_add_u64 v[8:9], v[8:9], 0, s[94:95]
	s_mov_b32 m0, s80
	s_add_i32 s81, s80, 0x2000
	s_add_i32 s82, s52, 0x8000
	s_add_i32 s83, s52, 0xa000
	s_waitcnt vmcnt(2)
	s_barrier
	global_load_lds_dwordx4 v[8:9], off
	v_lshl_add_u64 v[6:7], v[6:7], 0, s[94:95]
	s_mov_b32 m0, s81
	s_add_u32 s10, s36, 0x40080
	global_load_lds_dwordx4 v[6:7], off
	v_lshl_add_u64 v[2:3], v[2:3], 0, s[94:95]
	s_mov_b32 m0, s82
	s_addc_u32 s11, s37, 0
	s_add_i32 s84, s74, 0x1c000
	global_load_lds_dwordx4 v[2:3], off
	v_lshl_add_u64 v[2:3], v[4:5], 0, s[94:95]
	s_mov_b32 m0, s83
	s_add_i32 s85, s84, s9
	global_load_lds_dwordx4 v[2:3], off
	v_lshl_add_u64 v[2:3], s[10:11], 0, v[0:1]
	s_mov_b32 m0, s85
	s_add_i32 s86, s85, 0x2000
	global_load_lds_dwordx4 v[2:3], off
	v_lshl_add_u64 v[2:3], s[10:11], 0, v[164:165]
	s_mov_b32 m0, s86
	v_writelane_b32 v253, s12, 5
	global_load_lds_dwordx4 v[2:3], off
	v_lshlrev_b32_e32 v2, 14, v13
	v_and_b32_e32 v2, 0xffff8000, v2
	v_writelane_b32 v253, s13, 6
	v_lshl_add_u32 v2, v14, 11, v2
	v_and_b32_e32 v3, 1, v13
	v_writelane_b32 v253, s5, 7
	v_lshl_or_b32 v2, v3, 6, v2
	s_cmpk_lt_u32 s8, 0x100
	v_readlane_b32 s8, v253, 0
	v_lshl_add_u32 v166, v15, 1, v2
	v_lshlrev_b32_e32 v2, 14, v10
	s_cselect_b64 s[12:13], -1, 0
	s_lshl_b32 s5, s76, 7
	s_ashr_i32 s87, s73, 31
	v_readlane_b32 s9, v253, 1
	v_and_b32_e32 v2, 0xffff8000, v2
	v_readlane_b32 s70, v252, 42
	v_readlane_b32 s71, v252, 43
	s_waitcnt vmcnt(6)
	s_cmp_eq_u64 s[8:9], 0
	v_lshl_add_u32 v2, v11, 11, v2
	v_and_b32_e32 v3, 1, v10
	s_cselect_b64 s[14:15], -1, 0
	s_or_b32 s96, s3, s5
	s_add_i32 s3, s74, 0x21400
	v_lshl_or_b32 v2, v3, 6, v2
	v_readlane_b32 s70, v252, 58
	s_add_i32 s96, s96, 0x2680000
	v_writelane_b32 v253, s3, 8
	v_mov_b32_e32 v167, v1
	v_lshl_add_u32 v168, v12, 1, v2
	v_mov_b32_e32 v169, v1
	s_mov_b32 s10, 0
	v_add_u32_e32 v199, s74, v18
	s_lshl_b64 s[16:17], s[0:1], 2
	v_readlane_b32 s71, v252, 59
	v_readlane_b32 s57, v252, 29
	v_readlane_b32 s58, v252, 30
	v_readlane_b32 s59, v252, 31
	v_readlane_b32 s60, v252, 32
	v_readlane_b32 s61, v252, 33
	v_readlane_b32 s62, v252, 34
	v_readlane_b32 s63, v252, 35
	v_readlane_b32 s66, v252, 38
	v_readlane_b32 s67, v252, 39
	v_readlane_b32 s68, v252, 40
	v_readlane_b32 s69, v252, 41
	s_barrier
	s_mov_b32 s100, 0
	s_branch .LBB0_558
.Lin_peel:
	v_add_u32_e32 v144, s46, v198
	v_add_u32_e32 v160, s49, v198
	ds_read_b128 v[132:135], v144
	ds_read_b128 v[136:139], v144 offset:1024
	ds_read_b128 v[140:143], v144 offset:2048
	ds_read_b128 v[144:147], v144 offset:3072
	ds_read_b128 v[148:151], v160
	ds_read_b128 v[152:155], v160 offset:1024
	ds_read_b128 v[156:159], v160 offset:2048
	ds_read_b128 v[160:163], v160 offset:3072
	s_add_u32 s38, s36, 0xfffc0080
	s_addc_u32 s39, s37, -1
	s_cmp_eq_u32 s21, 12
	s_cselect_b32 s43, s3, s39
	s_cselect_b32 s42, s5, s38
	s_cselect_b32 s39, s8, s19
	s_cselect_b32 s38, s9, s11
	v_lshl_add_u64 v[194:195], s[36:37], 0, v[168:169]
	s_add_i32 m0, s52, 0xc000
	ds_read_b128 v[170:173], v199
	ds_read_b128 v[174:177], v199 offset:1024
	ds_read_b128 v[178:181], v199 offset:2048
	ds_read_b128 v[182:185], v199 offset:3072
	ds_read_b128 v[186:189], v199 offset:4096
	ds_read_b128 v[190:193], v199 offset:5120
	ds_read_b128 v[200:203], v199 offset:6144
	ds_read_b128 v[204:207], v199 offset:7168
	s_nop 0
	v_lshl_add_u64 v[194:195], s[36:37], 0, v[166:167]
	s_add_i32 m0, s52, 0xe000
	s_nop 0
	s_nop 0
	s_nop 0
	s_waitcnt lgkmcnt(0)
	s_barrier
	s_waitcnt lgkmcnt(0)
	v_mfma_f32_16x16x32_f16 v[70:73], v[132:135], v[170:173], v[70:73]
	v_mfma_f32_16x16x32_f16 v[66:69], v[140:143], v[170:173], v[66:69]
	v_mfma_f32_16x16x32_f16 v[50:53], v[132:135], v[178:181], v[50:53]
	v_mfma_f32_16x16x32_f16 v[46:49], v[140:143], v[178:181], v[46:49]
	v_mfma_f32_16x16x32_f16 v[54:57], v[132:135], v[186:189], v[54:57]
	v_mfma_f32_16x16x32_f16 v[42:45], v[140:143], v[186:189], v[42:45]
	v_mfma_f32_16x16x32_f16 v[38:41], v[132:135], v[200:203], v[38:41]
	v_mfma_f32_16x16x32_f16 v[34:37], v[140:143], v[200:203], v[34:37]
	v_mfma_f32_16x16x32_f16 v[70:73], v[136:139], v[174:177], v[70:73]
	v_mfma_f32_16x16x32_f16 v[66:69], v[144:147], v[174:177], v[66:69]
	v_mfma_f32_16x16x32_f16 v[50:53], v[136:139], v[182:185], v[50:53]
	v_mfma_f32_16x16x32_f16 v[46:49], v[144:147], v[182:185], v[46:49]
	v_mfma_f32_16x16x32_f16 v[54:57], v[136:139], v[190:193], v[54:57]
	v_mfma_f32_16x16x32_f16 v[42:45], v[144:147], v[190:193], v[42:45]
	v_mfma_f32_16x16x32_f16 v[38:41], v[136:139], v[204:207], v[38:41]
	v_mfma_f32_16x16x32_f16 v[34:37], v[144:147], v[204:207], v[34:37]
	v_mfma_f32_16x16x32_f16 v[126:129], v[148:151], v[170:173], v[126:129]
	v_mfma_f32_16x16x32_f16 v[122:125], v[156:159], v[170:173], v[122:125]
	v_mfma_f32_16x16x32_f16 v[118:121], v[148:151], v[178:181], v[118:121]
	v_mfma_f32_16x16x32_f16 v[114:117], v[156:159], v[178:181], v[114:117]
	v_mfma_f32_16x16x32_f16 v[110:113], v[148:151], v[186:189], v[110:113]
	v_mfma_f32_16x16x32_f16 v[106:109], v[156:159], v[186:189], v[106:109]
	v_mfma_f32_16x16x32_f16 v[102:105], v[148:151], v[200:203], v[102:105]
	v_mfma_f32_16x16x32_f16 v[98:101], v[156:159], v[200:203], v[98:101]
	v_mfma_f32_16x16x32_f16 v[126:129], v[152:155], v[174:177], v[126:129]
	v_mfma_f32_16x16x32_f16 v[122:125], v[160:163], v[174:177], v[122:125]
	v_mfma_f32_16x16x32_f16 v[118:121], v[152:155], v[182:185], v[118:121]
	v_mfma_f32_16x16x32_f16 v[114:117], v[160:163], v[182:185], v[114:117]
	v_mfma_f32_16x16x32_f16 v[110:113], v[152:155], v[190:193], v[110:113]
	v_mfma_f32_16x16x32_f16 v[106:109], v[160:163], v[190:193], v[106:109]
	v_mfma_f32_16x16x32_f16 v[102:105], v[152:155], v[204:207], v[102:105]
	v_mfma_f32_16x16x32_f16 v[98:101], v[160:163], v[204:207], v[98:101]
	s_barrier
; #define PG8_STAGE(bufoff, gbase) do { _Pragma("unroll") for (int _i = 0; _i < 2; ++_i) \
;         __builtin_amdgcn_global_load_lds((const unsigned*)((const char*)(gbase) + voffA[_i]), (LAS unsigned*)(lds + (bufoff) + ldsw + _i * 8192), 16, 0, 0); } while (0)
; #define PG8_LDA(dst, b, h) do { _Pragma("unroll") for (int m = 0; m < 4; ++m) _Pragma("unroll") for (int k = 0; k < 2; ++k) dst[m][k] = *(const LAS h16x8*)(lds + PG8_SA(b, h) + aoff + m * 2048 + k * 1024); } while (0)
; #define PG8_LDB(dst, b, h) do { _Pragma("unroll") for (int n = 0; n < 2; ++n) _Pragma("unroll") for (int k = 0; k < 2; ++k) dst[n][k] = *(const LAS h16x8*)(lds + PG8_SB(b, h) + boff + n * 2048 + k * 1024); } while (0)
; #define PG8_LDA1(dst, b) do { if constexpr (!HALFM) PG8_LDA(dst, b, 1); } while (0)
; #define PG8_MMA1(At, B0, B1) do { if constexpr (!HALFM) { PG8_MMA(1, 0, At, B0); PG8_MMA(1, 1, At, B1); } } while (0)
; #define PG8_WAIT_V(n) asm volatile("s_waitcnt vmcnt(" #n ")" ::: "memory")
; #define PG8_WAIT_L(n) asm volatile("s_waitcnt lgkmcnt(" #n ")" ::: "memory")
; #define PG8_BAR __builtin_amdgcn_s_barrier()
; #define PG8_SCHED __builtin_amdgcn_sched_barrier(0)
; template <class Epi, bool ALIGN_EPI, bool SP2, bool BF = false, bool HALFM = false, class Order = StaticOrder>
; __device__ __forceinline__ void gemm_phase(LAS unsigned char* lds, const int tid, const Gemm g, const Order& S, const Epi& E, const bool dry = false) {
;     ...
;             PG8_LDA1(At, 0); PG8_STAGE(PG8_SB(0, 0), b2); PG8_STAGE(PG8_SB(0, 1), b2 + hstep); PG8_STAGE(PG8_SA(0, 0), a2);
;             PG8_WAIT_V(8); PG8_WAIT_L(0); PG8_BAR; PG8_MMA1(At, B0, B1); PG8_BAR; PG8_SCHED;
;             PG8_LDB(B0, 1, 0); PG8_LDB(B1, 1, 1); PG8_SCHED; PG8_LDA(At, 1, 0); PG8_STAGE(PG8_SA(0, 1), a2 + hstep);
;             PG8_WAIT_V(8); PG8_WAIT_L(0); PG8_BAR; PG8_MMA(0, 0, At, B0); PG8_MMA(0, 1, At, B1); PG8_BAR; PG8_SCHED;
;             PG8_LDA1(At, 1); PG8_STAGE(PG8_SB(1, 0), b3); PG8_STAGE(PG8_SB(1, 1), b3 + hstep); PG8_STAGE(PG8_SA(1, 0), a3);
;             PG8_WAIT_V(8); PG8_WAIT_L(0); PG8_BAR; PG8_MMA1(At, B0, B1); PG8_BAR; PG8_SCHED;
	s_mov_b32 m0, s47
	v_lshl_add_u64 v[194:195], s[38:39], 0, v[0:1]
	s_add_u32 vcc_lo, s38, 0x40000
	ds_read_b128 v[170:173], v199 offset:16384
	ds_read_b128 v[174:177], v199 offset:17408
	ds_read_b128 v[178:181], v199 offset:18432
	ds_read_b128 v[182:185], v199 offset:19456
	ds_read_b128 v[186:189], v199 offset:20480
	ds_read_b128 v[190:193], v199 offset:21504
	ds_read_b128 v[200:203], v199 offset:22528
	ds_read_b128 v[204:207], v199 offset:23552
	global_load_lds_dwordx4 v[194:195], off
	v_lshl_add_u64 v[214:215], s[38:39], 0, v[164:165]
	s_mov_b32 m0, s48
	s_addc_u32 vcc_hi, s39, 0
	global_load_lds_dwordx4 v[214:215], off
	v_lshl_add_u64 v[216:217], vcc, 0, v[0:1]
	s_mov_b32 m0, s50
	v_lshl_add_u64 v[218:219], s[42:43], 0, v[164:165]
	global_load_lds_dwordx4 v[216:217], off
	v_lshl_add_u64 v[216:217], vcc, 0, v[164:165]
	s_mov_b32 m0, s51
	s_nop 0
	global_load_lds_dwordx4 v[216:217], off
	v_lshl_add_u64 v[216:217], s[42:43], 0, v[0:1]
	s_mov_b32 m0, s52
	s_nop 0
	global_load_lds_dwordx4 v[216:217], off
	s_mov_b32 m0, s53
	s_nop 0
	global_load_lds_dwordx4 v[218:219], off
	s_nop 0
	s_waitcnt lgkmcnt(0)
	s_barrier
	s_waitcnt lgkmcnt(0)
	v_mfma_f32_16x16x32_f16 v[30:33], v[132:135], v[170:173], v[30:33]
	v_mfma_f32_16x16x32_f16 v[26:29], v[140:143], v[170:173], v[26:29]
	v_mfma_f32_16x16x32_f16 v[22:25], v[132:135], v[178:181], v[22:25]
	v_mfma_f32_16x16x32_f16 v[18:21], v[140:143], v[178:181], v[18:21]
	v_mfma_f32_16x16x32_f16 v[14:17], v[132:135], v[186:189], v[14:17]
	v_mfma_f32_16x16x32_f16 v[10:13], v[140:143], v[186:189], v[10:13]
	v_mfma_f32_16x16x32_f16 v[6:9], v[132:135], v[200:203], v[6:9]
	v_mfma_f32_16x16x32_f16 v[2:5], v[140:143], v[200:203], v[2:5]
	v_mfma_f32_16x16x32_f16 v[30:33], v[136:139], v[174:177], v[30:33]
	v_mfma_f32_16x16x32_f16 v[26:29], v[144:147], v[174:177], v[26:29]
	v_mfma_f32_16x16x32_f16 v[22:25], v[136:139], v[182:185], v[22:25]
	v_mfma_f32_16x16x32_f16 v[18:21], v[144:147], v[182:185], v[18:21]
	v_mfma_f32_16x16x32_f16 v[14:17], v[136:139], v[190:193], v[14:17]
	v_mfma_f32_16x16x32_f16 v[10:13], v[144:147], v[190:193], v[10:13]
	v_mfma_f32_16x16x32_f16 v[6:9], v[136:139], v[204:207], v[6:9]
	v_mfma_f32_16x16x32_f16 v[2:5], v[144:147], v[204:207], v[2:5]
	v_mfma_f32_16x16x32_f16 v[94:97], v[148:151], v[170:173], v[94:97]
	v_mfma_f32_16x16x32_f16 v[90:93], v[156:159], v[170:173], v[90:93]
	v_mfma_f32_16x16x32_f16 v[86:89], v[148:151], v[178:181], v[86:89]
	v_mfma_f32_16x16x32_f16 v[82:85], v[156:159], v[178:181], v[82:85]
	v_mfma_f32_16x16x32_f16 v[78:81], v[148:151], v[186:189], v[78:81]
	v_mfma_f32_16x16x32_f16 v[74:77], v[156:159], v[186:189], v[74:77]
	v_mfma_f32_16x16x32_f16 v[62:65], v[148:151], v[200:203], v[62:65]
	v_mfma_f32_16x16x32_f16 v[58:61], v[156:159], v[200:203], v[58:61]
	v_mfma_f32_16x16x32_f16 v[94:97], v[152:155], v[174:177], v[94:97]
	v_mfma_f32_16x16x32_f16 v[90:93], v[160:163], v[174:177], v[90:93]
	v_mfma_f32_16x16x32_f16 v[86:89], v[152:155], v[182:185], v[86:89]
	v_mfma_f32_16x16x32_f16 v[82:85], v[160:163], v[182:185], v[82:85]
	v_mfma_f32_16x16x32_f16 v[78:81], v[152:155], v[190:193], v[78:81]
	v_mfma_f32_16x16x32_f16 v[74:77], v[160:163], v[190:193], v[74:77]
	v_mfma_f32_16x16x32_f16 v[62:65], v[152:155], v[204:207], v[62:65]
	v_mfma_f32_16x16x32_f16 v[58:61], v[160:163], v[204:207], v[58:61]
	s_barrier
	v_add_u32_e32 v144, s79, v198
	v_add_u32_e32 v160, s84, v198
	ds_read_b128 v[132:135], v144
	ds_read_b128 v[136:139], v144 offset:1024
	ds_read_b128 v[140:143], v144 offset:2048
	ds_read_b128 v[144:147], v144 offset:3072
	ds_read_b128 v[148:151], v160
	ds_read_b128 v[152:155], v160 offset:1024
	ds_read_b128 v[156:159], v160 offset:2048
	ds_read_b128 v[160:163], v160 offset:3072
	s_add_u32 s42, s42, 0x40000
	s_addc_u32 s43, s43, 0
	s_mov_b32 m0, s54
	v_lshl_add_u64 v[220:221], s[42:43], 0, v[0:1]
	ds_read_b128 v[170:173], v199 offset:32768
	ds_read_b128 v[174:177], v199 offset:33792
	ds_read_b128 v[178:181], v199 offset:34816
	ds_read_b128 v[182:185], v199 offset:35840
	ds_read_b128 v[186:189], v199 offset:36864
	ds_read_b128 v[190:193], v199 offset:37888
	ds_read_b128 v[200:203], v199 offset:38912
	ds_read_b128 v[204:207], v199 offset:39936
	global_load_lds_dwordx4 v[220:221], off
	v_lshl_add_u64 v[220:221], s[42:43], 0, v[164:165]
	s_mov_b32 m0, s55
	s_nop 0
	global_load_lds_dwordx4 v[220:221], off
	s_nop 0
	s_waitcnt lgkmcnt(0)
	s_barrier
	s_waitcnt lgkmcnt(0)
	v_mfma_f32_16x16x32_f16 v[70:73], v[132:135], v[170:173], v[70:73]
	v_mfma_f32_16x16x32_f16 v[66:69], v[140:143], v[170:173], v[66:69]
	v_mfma_f32_16x16x32_f16 v[50:53], v[132:135], v[178:181], v[50:53]
	v_mfma_f32_16x16x32_f16 v[46:49], v[140:143], v[178:181], v[46:49]
	v_mfma_f32_16x16x32_f16 v[54:57], v[132:135], v[186:189], v[54:57]
	v_mfma_f32_16x16x32_f16 v[42:45], v[140:143], v[186:189], v[42:45]
	v_mfma_f32_16x16x32_f16 v[38:41], v[132:135], v[200:203], v[38:41]
	v_mfma_f32_16x16x32_f16 v[34:37], v[140:143], v[200:203], v[34:37]
	v_mfma_f32_16x16x32_f16 v[70:73], v[136:139], v[174:177], v[70:73]
	v_mfma_f32_16x16x32_f16 v[66:69], v[144:147], v[174:177], v[66:69]
	v_mfma_f32_16x16x32_f16 v[50:53], v[136:139], v[182:185], v[50:53]
	v_mfma_f32_16x16x32_f16 v[46:49], v[144:147], v[182:185], v[46:49]
	v_mfma_f32_16x16x32_f16 v[54:57], v[136:139], v[190:193], v[54:57]
	v_mfma_f32_16x16x32_f16 v[42:45], v[144:147], v[190:193], v[42:45]
	v_mfma_f32_16x16x32_f16 v[38:41], v[136:139], v[204:207], v[38:41]
	v_mfma_f32_16x16x32_f16 v[34:37], v[144:147], v[204:207], v[34:37]
	v_mfma_f32_16x16x32_f16 v[126:129], v[148:151], v[170:173], v[126:129]
	v_mfma_f32_16x16x32_f16 v[122:125], v[156:159], v[170:173], v[122:125]
	v_mfma_f32_16x16x32_f16 v[118:121], v[148:151], v[178:181], v[118:121]
	v_mfma_f32_16x16x32_f16 v[114:117], v[156:159], v[178:181], v[114:117]
	v_mfma_f32_16x16x32_f16 v[110:113], v[148:151], v[186:189], v[110:113]
	v_mfma_f32_16x16x32_f16 v[106:109], v[156:159], v[186:189], v[106:109]
	v_mfma_f32_16x16x32_f16 v[102:105], v[148:151], v[200:203], v[102:105]
	v_mfma_f32_16x16x32_f16 v[98:101], v[156:159], v[200:203], v[98:101]
	v_mfma_f32_16x16x32_f16 v[126:129], v[152:155], v[174:177], v[126:129]
	v_mfma_f32_16x16x32_f16 v[122:125], v[160:163], v[174:177], v[122:125]
	v_mfma_f32_16x16x32_f16 v[118:121], v[152:155], v[182:185], v[118:121]
	v_mfma_f32_16x16x32_f16 v[114:117], v[160:163], v[182:185], v[114:117]
	v_mfma_f32_16x16x32_f16 v[110:113], v[152:155], v[190:193], v[110:113]
	v_mfma_f32_16x16x32_f16 v[106:109], v[160:163], v[190:193], v[106:109]
	v_mfma_f32_16x16x32_f16 v[102:105], v[152:155], v[204:207], v[102:105]
	v_mfma_f32_16x16x32_f16 v[98:101], v[160:163], v[204:207], v[98:101]
	s_barrier
	s_branch .Lin_seg4

; #define PG8_BAR __builtin_amdgcn_s_barrier()
; template <class Epi, bool ALIGN_EPI, bool SP2, bool BF = false, bool HALFM = false, class Order = StaticOrder>
; __device__ __forceinline__ void gemm_phase(LAS unsigned char* lds, const int tid, const Gemm g, const Order& S, const Epi& E, const bool dry = false) {
;     ...
;         if (!has_next) break;
; #pragma unroll
;         for (int a = 0; a < 2; ++a)
; #pragma unroll
;             for (int b = 0; b < 2; ++b)
; #pragma unroll
;                 for (int m = 0; m < 4; ++m)
; #pragma unroll
;                     for (int n = 0; n < 2; ++n) acc[a][b][m][n] = (f32x4){0.f, 0.f, 0.f, 0.f};
;         cur = nxt; cA = nA; cB = nB; ++ui;
;         if constexpr (ALIGN_EPI) { if (wr == 1) PG8_BAR; }
.LBB0_560:
	s_ashr_i32 s21, s20, 31
	s_lshl_b64 s[8:9], s[20:21], 19
	s_add_u32 s22, s44, s8
	s_addc_u32 s23, s45, s9
	s_and_b64 s[8:9], s[0:1], exec
	s_cselect_b32 s3, s23, s39
	s_cselect_b32 s5, s22, s38
	s_ashr_i32 s19, s18, 31
	s_lshl_b64 s[8:9], s[18:19], 19
	s_add_u32 s24, s29, s8
	s_addc_u32 s25, s41, s9
	s_and_b64 s[8:9], s[0:1], exec
	s_cselect_b32 s8, s25, s37
	s_cselect_b32 s9, s24, s36
	s_add_u32 s11, s36, 0x100
	s_addc_u32 s19, s37, 0
	s_add_u32 s36, s38, 0x40080
	s_addc_u32 s37, s39, 0
	s_cmp_eq_u32 s100, 2
	s_cbranch_scc1 .Lin_w16
	s_waitcnt vmcnt(0)
	s_branch .Lin_wd

; #define PG8_BAR __builtin_amdgcn_s_barrier()
; template <class Epi, bool ALIGN_EPI, bool SP2, bool BF = false, bool HALFM = false, class Order = StaticOrder>
; __device__ __forceinline__ void gemm_phase(LAS unsigned char* lds, const int tid, const Gemm g, const Order& S, const Epi& E, const bool dry = false) {
;     ...
; #pragma unroll
;         for (int a = 0; a < 2; ++a)
; #pragma unroll
;             for (int b = 0; b < 2; ++b)
; #pragma unroll
;                 for (int m = 0; m < 4; ++m)
; #pragma unroll
;                     for (int n = 0; n < 2; ++n) acc[a][b][m][n] = (f32x4){0.f, 0.f, 0.f, 0.f};
;         cur = nxt; cA = nA; cB = nB; ++ui;
;         if constexpr (ALIGN_EPI) { if (wr == 1) PG8_BAR; }
.Lin_wd:
	v_mov_b32_e32 v58, 0
	s_mov_b32 s21, -2
	v_mov_b32_e32 v59, v58
	v_mov_b32_e32 v60, v58
	v_mov_b32_e32 v61, v58
	v_mov_b32_e32 v62, v58
	v_mov_b32_e32 v63, v58
	v_mov_b32_e32 v64, v58
	v_mov_b32_e32 v65, v58
	v_mov_b32_e32 v74, v58
	v_mov_b32_e32 v75, v58
	v_mov_b32_e32 v76, v58
	v_mov_b32_e32 v77, v58
	v_mov_b32_e32 v78, v58
	v_mov_b32_e32 v79, v58
	v_mov_b32_e32 v80, v58
	v_mov_b32_e32 v81, v58
	v_mov_b32_e32 v82, v58
	v_mov_b32_e32 v83, v58
	v_mov_b32_e32 v84, v58
	v_mov_b32_e32 v85, v58
	v_mov_b32_e32 v86, v58
	v_mov_b32_e32 v87, v58
	v_mov_b32_e32 v88, v58
	v_mov_b32_e32 v89, v58
	v_mov_b32_e32 v90, v58
	v_mov_b32_e32 v91, v58
	v_mov_b32_e32 v92, v58
	v_mov_b32_e32 v93, v58
	v_mov_b32_e32 v94, v58
	v_mov_b32_e32 v95, v58
	v_mov_b32_e32 v96, v58
	v_mov_b32_e32 v97, v58
	v_mov_b32_e32 v2, v58
	v_mov_b32_e32 v3, v58
	v_mov_b32_e32 v4, v58
	v_mov_b32_e32 v5, v58
	v_mov_b32_e32 v6, v58
	v_mov_b32_e32 v7, v58
	v_mov_b32_e32 v8, v58
	v_mov_b32_e32 v9, v58
	v_mov_b32_e32 v10, v58
	v_mov_b32_e32 v11, v58
	v_mov_b32_e32 v12, v58
	v_mov_b32_e32 v13, v58
	v_mov_b32_e32 v14, v58
	v_mov_b32_e32 v15, v58
	v_mov_b32_e32 v16, v58
	v_mov_b32_e32 v17, v58
	v_mov_b32_e32 v18, v58
	v_mov_b32_e32 v19, v58
	v_mov_b32_e32 v20, v58
	v_mov_b32_e32 v21, v58
	v_mov_b32_e32 v22, v58
	v_mov_b32_e32 v23, v58
	v_mov_b32_e32 v24, v58
	v_mov_b32_e32 v25, v58
	v_mov_b32_e32 v26, v58
	v_mov_b32_e32 v27, v58
	v_mov_b32_e32 v28, v58
	v_mov_b32_e32 v29, v58
	v_mov_b32_e32 v30, v58
	v_mov_b32_e32 v31, v58
	v_mov_b32_e32 v32, v58
	v_mov_b32_e32 v33, v58
	v_mov_b32_e32 v98, v58
	v_mov_b32_e32 v99, v58
	v_mov_b32_e32 v100, v58
	v_mov_b32_e32 v101, v58
	v_mov_b32_e32 v102, v58
	v_mov_b32_e32 v103, v58
	v_mov_b32_e32 v104, v58
	v_mov_b32_e32 v105, v58
	v_mov_b32_e32 v106, v58
	v_mov_b32_e32 v107, v58
	v_mov_b32_e32 v108, v58
	v_mov_b32_e32 v109, v58
	v_mov_b32_e32 v110, v58
	v_mov_b32_e32 v111, v58
	v_mov_b32_e32 v112, v58
	v_mov_b32_e32 v113, v58
	v_mov_b32_e32 v114, v58
	v_mov_b32_e32 v115, v58
	v_mov_b32_e32 v116, v58
	v_mov_b32_e32 v117, v58
	v_mov_b32_e32 v118, v58
	v_mov_b32_e32 v119, v58
	v_mov_b32_e32 v120, v58
	v_mov_b32_e32 v121, v58
	v_mov_b32_e32 v122, v58
	v_mov_b32_e32 v123, v58
	v_mov_b32_e32 v124, v58
	v_mov_b32_e32 v125, v58
	v_mov_b32_e32 v126, v58
	v_mov_b32_e32 v127, v58
	v_mov_b32_e32 v128, v58
	v_mov_b32_e32 v129, v58
	v_mov_b32_e32 v34, v58
	v_mov_b32_e32 v35, v58
	v_mov_b32_e32 v36, v58
	v_mov_b32_e32 v37, v58
	v_mov_b32_e32 v38, v58
	v_mov_b32_e32 v39, v58
	v_mov_b32_e32 v40, v58
	v_mov_b32_e32 v41, v58
	v_mov_b32_e32 v42, v58
	v_mov_b32_e32 v43, v58
	v_mov_b32_e32 v44, v58
	v_mov_b32_e32 v45, v58
	v_mov_b32_e32 v54, v58
	v_mov_b32_e32 v55, v58
	v_mov_b32_e32 v56, v58
	v_mov_b32_e32 v57, v58
	v_mov_b32_e32 v46, v58
	v_mov_b32_e32 v47, v58
	v_mov_b32_e32 v48, v58
	v_mov_b32_e32 v49, v58
	v_mov_b32_e32 v50, v58
	v_mov_b32_e32 v51, v58
	v_mov_b32_e32 v52, v58
	v_mov_b32_e32 v53, v58
	v_mov_b32_e32 v66, v58
	v_mov_b32_e32 v67, v58
	v_mov_b32_e32 v68, v58
	v_mov_b32_e32 v69, v58
	v_mov_b32_e32 v70, v58
	v_mov_b32_e32 v71, v58
	v_mov_b32_e32 v72, v58
	v_mov_b32_e32 v73, v58
	s_cmp_lg_u32 s100, 0
	s_cbranch_scc1 .Lin_peel

; #define PG8_LDA1(dst, b) do { if constexpr (!HALFM) PG8_LDA(dst, b, 1); } while (0)
; #define PG8_MMA1(At, B0, B1) do { if constexpr (!HALFM) { PG8_MMA(1, 0, At, B0); PG8_MMA(1, 1, At, B1); } } while (0)
; template <class Epi, bool ALIGN_EPI, bool SP2, bool BF = false, bool HALFM = false, class Order = StaticOrder>
; __device__ __forceinline__ void gemm_phase(LAS unsigned char* lds, const int tid, const Gemm g, const Order& S, const Epi& E, const bool dry = false) {
;     ...
;         for (int t = 0; t < nt; t += 2) {
;             const bool last = (t == nt - 2);
;             const char* a1 = cA + (size_t)(t + 1) * kstep;
;             const char* a2 = last ? nA : cA + (size_t)(t + 2) * kstep; const char* b2 = last ? nB : cB + (size_t)(t + 2) * kstep;
;             const char* a3 = a2 + kstep; const char* b3 = b2 + kstep;
;             if constexpr (SP2) {
;             PG8_LDB(B0, 0, 0); PG8_LDB(B1, 0, 1); PG8_SCHED; PG8_LDA(At, 0, 0); PG8_STAGE(PG8_SA(1, 1), a1 + hstep);
;             PG8_WAIT_V(8); PG8_WAIT_L(0); PG8_BAR; PG8_MMA(0, 0, At, B0); PG8_MMA(0, 1, At, B1); PG8_BAR; PG8_SCHED;
;             PG8_LDA1(At, 0); PG8_STAGE(PG8_SB(0, 0), b2); PG8_STAGE(PG8_SB(0, 1), b2 + hstep); PG8_STAGE(PG8_SA(0, 0), a2);
;             PG8_WAIT_V(8); PG8_WAIT_L(0); PG8_BAR; PG8_MMA1(At, B0, B1); PG8_BAR; PG8_SCHED;
;             PG8_LDB(B0, 1, 0); PG8_LDB(B1, 1, 1); PG8_SCHED; PG8_LDA(At, 1, 0); PG8_STAGE(PG8_SA(0, 1), a2 + hstep);
;             PG8_WAIT_V(8); PG8_WAIT_L(0); PG8_BAR; PG8_MMA(0, 0, At, B0); PG8_MMA(0, 1, At, B1); PG8_BAR; PG8_SCHED;
;             PG8_LDA1(At, 1); PG8_STAGE(PG8_SB(1, 0), b3); PG8_STAGE(PG8_SB(1, 1), b3 + hstep); PG8_STAGE(PG8_SA(1, 0), a3);
;             PG8_WAIT_V(8); PG8_WAIT_L(0); PG8_BAR; PG8_MMA1(At, B0, B1); PG8_BAR; PG8_SCHED;
;     ...
;         if constexpr (ALIGN_EPI) { if (wr == 0) PG8_BAR; }
;         if (!dry) { int fr2 = fr, fq2 = fq; asm volatile("" : "+v"(fr2), "+v"(fq2)); E(acc, cur, wr, wc, fr2, fq2); }
;     __device__ __forceinline__ void operator()(const f32x4 (&acc)[2][2][4][2], const pg8::Unit& u, int wr, int wc, int fr, int fq) const {
;         const int s = u.pn * 4 + wc;
;         if (s >= 53) return;
;         unsigned char* ws = ws_; asm volatile("" : "+s"(ws)); unsigned char* wst = wst_ ? ws : nullptr;
;         const bool lat = u.pm < 128; const int b = lat ? (u.pm >> 3) : (u.pm - 128); const int bb = lat ? b : 16;
.Lin_seg4:
	s_mov_b32 m0, s80
	v_lshl_add_u64 v[194:195], v[194:195], 0, s[94:95]
	s_add_u32 s38, s38, 0x40080
	ds_read_b128 v[170:173], v199 offset:49152
	ds_read_b128 v[174:177], v199 offset:50176
	ds_read_b128 v[178:181], v199 offset:51200
	ds_read_b128 v[182:185], v199 offset:52224
	ds_read_b128 v[186:189], v199 offset:53248
	ds_read_b128 v[190:193], v199 offset:54272
	ds_read_b128 v[200:203], v199 offset:55296
	ds_read_b128 v[204:207], v199 offset:56320
	global_load_lds_dwordx4 v[194:195], off
	v_lshl_add_u64 v[194:195], v[214:215], 0, s[94:95]
	s_mov_b32 m0, s81
	s_addc_u32 s39, s39, 0
	global_load_lds_dwordx4 v[194:195], off
	v_lshl_add_u64 v[194:195], s[38:39], 0, v[0:1]
	s_mov_b32 m0, s85
	s_nop 0
	global_load_lds_dwordx4 v[194:195], off
	v_lshl_add_u64 v[194:195], s[38:39], 0, v[164:165]
	s_mov_b32 m0, s86
	s_nop 0
	global_load_lds_dwordx4 v[194:195], off
	v_lshl_add_u64 v[194:195], v[216:217], 0, s[94:95]
	s_mov_b32 m0, s82
	s_nop 0
	global_load_lds_dwordx4 v[194:195], off
	v_lshl_add_u64 v[194:195], v[218:219], 0, s[94:95]
	s_mov_b32 m0, s83
	s_nop 0
	global_load_lds_dwordx4 v[194:195], off
	s_waitcnt vmcnt(8)
	s_waitcnt lgkmcnt(0)
	s_barrier
	s_waitcnt lgkmcnt(0)
	v_mfma_f32_16x16x32_f16 v[30:33], v[132:135], v[170:173], v[30:33]
	v_mfma_f32_16x16x32_f16 v[26:29], v[140:143], v[170:173], v[26:29]
	v_mfma_f32_16x16x32_f16 v[22:25], v[132:135], v[178:181], v[22:25]
	v_mfma_f32_16x16x32_f16 v[18:21], v[140:143], v[178:181], v[18:21]
	v_mfma_f32_16x16x32_f16 v[14:17], v[132:135], v[186:189], v[14:17]
	v_mfma_f32_16x16x32_f16 v[10:13], v[140:143], v[186:189], v[10:13]
	v_mfma_f32_16x16x32_f16 v[6:9], v[132:135], v[200:203], v[6:9]
	v_mfma_f32_16x16x32_f16 v[2:5], v[140:143], v[200:203], v[2:5]
	v_mfma_f32_16x16x32_f16 v[30:33], v[136:139], v[174:177], v[30:33]
	v_mfma_f32_16x16x32_f16 v[26:29], v[144:147], v[174:177], v[26:29]
	v_mfma_f32_16x16x32_f16 v[22:25], v[136:139], v[182:185], v[22:25]
	v_mfma_f32_16x16x32_f16 v[18:21], v[144:147], v[182:185], v[18:21]
	v_mfma_f32_16x16x32_f16 v[14:17], v[136:139], v[190:193], v[14:17]
	v_mfma_f32_16x16x32_f16 v[10:13], v[144:147], v[190:193], v[10:13]
	v_mfma_f32_16x16x32_f16 v[6:9], v[136:139], v[204:207], v[6:9]
	v_mfma_f32_16x16x32_f16 v[2:5], v[144:147], v[204:207], v[2:5]
	v_mfma_f32_16x16x32_f16 v[94:97], v[148:151], v[170:173], v[94:97]
	v_mfma_f32_16x16x32_f16 v[90:93], v[156:159], v[170:173], v[90:93]
	v_mfma_f32_16x16x32_f16 v[86:89], v[148:151], v[178:181], v[86:89]
	v_mfma_f32_16x16x32_f16 v[82:85], v[156:159], v[178:181], v[82:85]
	v_mfma_f32_16x16x32_f16 v[78:81], v[148:151], v[186:189], v[78:81]
	v_mfma_f32_16x16x32_f16 v[74:77], v[156:159], v[186:189], v[74:77]
	v_mfma_f32_16x16x32_f16 v[62:65], v[148:151], v[200:203], v[62:65]
	v_mfma_f32_16x16x32_f16 v[58:61], v[156:159], v[200:203], v[58:61]
	v_mfma_f32_16x16x32_f16 v[94:97], v[152:155], v[174:177], v[94:97]
	v_mfma_f32_16x16x32_f16 v[90:93], v[160:163], v[174:177], v[90:93]
	v_mfma_f32_16x16x32_f16 v[86:89], v[152:155], v[182:185], v[86:89]
	v_mfma_f32_16x16x32_f16 v[82:85], v[160:163], v[182:185], v[82:85]
	v_mfma_f32_16x16x32_f16 v[78:81], v[152:155], v[190:193], v[78:81]
	v_mfma_f32_16x16x32_f16 v[74:77], v[160:163], v[190:193], v[74:77]
	v_mfma_f32_16x16x32_f16 v[62:65], v[152:155], v[204:207], v[62:65]
	v_mfma_f32_16x16x32_f16 v[58:61], v[160:163], v[204:207], v[58:61]
	s_barrier
	s_add_i32 s21, s21, 2
	s_add_u32 s11, s11, 0x100
	s_addc_u32 s19, s19, 0
	s_add_u32 s36, s36, 0x100
	s_addc_u32 s37, s37, 0
	s_cmp_gt_u32 s21, 13
	s_cbranch_scc0 .LBB0_561
	s_and_b64 vcc, exec, s[12:13]
	s_cbranch_vccz .LBB0_564
	s_barrier
.LBB0_564:
	s_add_u32 vcc_lo, s5, 0x40080
	s_addc_u32 vcc_hi, s3, 0
	s_add_i32 m0, s52, 0xc000
	v_lshl_add_u64 v[194:195], vcc, 0, v[168:169]
	s_mov_b32 s100, 1
	global_load_lds_dwordx4 v[194:195], off
	v_lshl_add_u64 v[194:195], vcc, 0, v[166:167]
	s_add_i32 m0, s52, 0xe000
	s_nop 0
	global_load_lds_dwordx4 v[194:195], off
	s_lshl_b32 s78, s2, 2
	s_or_b32 s11, s78, s76
	v_mov_b32_e32 v202, v196
	v_mov_b32_e32 v200, v197
	s_cmp_gt_i32 s11, 52
	s_cbranch_scc1 .LBB0_637
	v_readlane_b32 s42, v253, 0
	s_cmpk_lt_i32 s4, 0x80
	v_readlane_b32 s43, v253, 1
	s_cselect_b64 s[38:39], -1, 0
	s_cmpk_gt_i32 s4, 0x7f
	s_mov_b64 s[36:37], -1
	s_cbranch_scc0 .LBB0_567
	s_add_i32 s21, s4, 0xffffff80
	s_mov_b64 s[36:37], 0

; #define LAS __attribute__((address_space(3)))
; __device__ __forceinline__ void stg_line_pair(void* base, unsigned roA, unsigned rowb, const u32x4 w0, const u32x4 w1, bool odd) {
;     u32x4 a, b;
; #pragma unroll
;     for (int c = 0; c < 4; ++c) { const unsigned p1 = (unsigned)__builtin_amdgcn_update_dpp(0, (int)w1[c], 0xB1, 0xF, 0xF, false), p0 = (unsigned)__builtin_amdgcn_update_dpp(0, (int)w0[c], 0xB1, 0xF, 0xF, false);
;         a[c] = odd ? p1 : w0[c]; b[c] = odd ? w1[c] : p0; }
;     stg_u4(base, roA, a); stg_u4(base, roA + rowb, b);
; }
;     __device__ __forceinline__ void operator()(const f32x4 (&acc)[2][2][4][2], const pg8::Unit& u, int wr, int wc, int fr, int fq) const {
;     ...
;         for (int ai = 0; ai < 2; ++ai)
; #pragma unroll
;             for (int m = 0; m < 4; ++m) { const float r = rs[ai][m]; f32x4 v[2][2]; float ss = 0.f;
; #pragma unroll
;                 for (int bj = 0; bj < 2; ++bj)
; #pragma unroll
;                     for (int n = 0; n < 2; ++n) { v[bj][n] = acc[ai][bj][m][n] * r + bv[bj][n]; ss += (v[bj][n][0] * v[bj][n][0] + v[bj][n][1] * v[bj][n][1]) + (v[bj][n][2] * v[bj][n][2] + v[bj][n][3] * v[bj][n][3]); }
;                 const float rn = __builtin_amdgcn_rsqf(red4(ss, fq * 16 + fr) * (1.f / 64.f) + EPS);
; #pragma unroll
;                 for (int bj = 0; bj < 2; ++bj)
; #pragma unroll
;                     for (int n = 0; n < 2; ++n) v[bj][n] = v[bj][n] * rn * g4[bj][n];
;                 if (lat) { const unsigned t = (rbase + ai * 128 + m * 16) & (SEQ - 1);
; #pragma unroll
;                     for (int bj = 0; bj < 2; ++bj) { const unsigned pos = bj ? (t & 63u) : (t >> 6); const f32x4 cs = *(const LAS f32x4*)(ropel + pos * 16u + 4u * fq), sn = *(const LAS f32x4*)(ropel + 1024u + pos * 16u + 4u * fq);
;                         const f32x4 x1 = v[bj][0], x2 = v[bj][1]; v[bj][0] = x1 * cs - x2 * sn; v[bj][1] = x2 * cs + x1 * sn; } }
;                 const unsigned ro = offA + (unsigned)(ai * 8 + m) * 32u * pitch;
;                 u32x4 w[2];
; #pragma unroll
;                 for (int bj = 0; bj < 2; ++bj) { w[bj].x = cvtpk_h(v[bj][0][0], v[bj][0][1]); w[bj].y = cvtpk_h(v[bj][0][2], v[bj][0][3]); w[bj].z = cvtpk_h(v[bj][1][0], v[bj][1][1]); w[bj].w = cvtpk_h(v[bj][1][2], v[bj][1][3]); }
;                 stg_line_pair(wst, ro, 2u * pitch, w[0], w[1], odd);
;                 asm volatile("" ::: "memory"); }
.LBB0_577:
	v_and_b32_e32 v186, 1, v202
	v_lshlrev_b32_e32 v206, 6, v186
	v_add3_u32 v206, v206, v203, v187
	v_add_u32_e32 v187, 16, v202
	v_and_b32_e32 v210, 63, v187
	v_cvt_pk_f16_f32 v152, v152, v153
	v_cvt_pk_f16_f32 v149, v148, v149
	v_mov_b32_e32 v148, v1
	v_mov_b32_e32 v187, v1
	v_cmp_eq_u32_e64 s[2:3], 0, v186
	v_mov_b32_dpp v148, v149 quad_perm:[1,0,3,2] row_mask:0xf bank_mask:0xf
	v_mov_b32_dpp v187, v152 quad_perm:[1,0,3,2] row_mask:0xf bank_mask:0xf
	v_cvt_pk_f16_f32 v153, v154, v155
	v_cvt_pk_f16_f32 v150, v150, v151
	v_cndmask_b32_e64 v148, v148, v152, s[2:3]
	v_cndmask_b32_e64 v152, v149, v187, s[2:3]
	v_mov_b32_e32 v149, v1
	v_mov_b32_e32 v187, v1
	v_cvt_pk_f16_f32 v154, v190, v191
	v_mov_b32_dpp v149, v150 quad_perm:[1,0,3,2] row_mask:0xf bank_mask:0xf
	v_mov_b32_dpp v187, v153 quad_perm:[1,0,3,2] row_mask:0xf bank_mask:0xf
	v_cvt_pk_f16_f32 v151, v194, v195
	v_cndmask_b32_e64 v149, v149, v153, s[2:3]
	v_cndmask_b32_e64 v153, v150, v187, s[2:3]
	v_mov_b32_e32 v150, v1
	v_mov_b32_e32 v187, v1
	v_cvt_pk_f16_f32 v186, v192, v193
	v_mov_b32_dpp v150, v151 quad_perm:[1,0,3,2] row_mask:0xf bank_mask:0xf
	v_mov_b32_dpp v187, v154 quad_perm:[1,0,3,2] row_mask:0xf bank_mask:0xf
	v_cndmask_b32_e64 v150, v150, v154, s[2:3]
	v_cndmask_b32_e64 v154, v151, v187, s[2:3]
	v_mov_b32_e32 v151, v1
	v_cvt_pk_f16_f32 v155, v188, v189
	v_mov_b32_e32 v187, v1
	v_mov_b32_dpp v151, v186 quad_perm:[1,0,3,2] row_mask:0xf bank_mask:0xf
	v_cndmask_b32_e64 v151, v151, v155, s[2:3]
	v_mov_b32_dpp v187, v155 quad_perm:[1,0,3,2] row_mask:0xf bank_mask:0xf
	v_cndmask_b32_e64 v155, v186, v187, s[2:3]
	s_mov_b32 s100, 2
	global_store_dwordx4 v206, v[148:151], s[36:37]
	s_and_b64 vcc, exec, s[4:5]
	v_lshlrev_b32_e32 v213, 6, v210
	v_add_u32_e32 v148, s9, v206
	s_mov_b32 s100, 2
	global_store_dwordx4 v148, v[152:155], s[36:37]
	v_mov_b32_e32 v148, v177
	v_pk_fma_f32 v[150:151], v[52:53], v[148:149], v[138:139] op_sel_hi:[1,0,1]
	v_pk_fma_f32 v[152:153], v[50:51], v[148:149], v[136:137] op_sel_hi:[1,0,1]
	v_mul_f32_e32 v154, v151, v151
	v_mul_f32_e32 v149, v153, v153
	v_fmac_f32_e32 v149, v152, v152
	v_fmac_f32_e32 v154, v150, v150
	v_add_f32_e32 v149, v149, v154
	v_pk_fma_f32 v[186:187], v[48:49], v[148:149], v[134:135] op_sel_hi:[1,0,1]
	v_pk_fma_f32 v[188:189], v[46:47], v[148:149], v[132:133] op_sel_hi:[1,0,1]
	v_mul_f32_e32 v155, v187, v187
	v_mul_f32_e32 v154, v189, v189
	v_fmac_f32_e32 v154, v188, v188
	v_fmac_f32_e32 v155, v186, v186
	v_add_f32_e32 v154, v154, v155
	v_add_f32_e32 v149, v149, v154
	v_pk_fma_f32 v[190:191], v[120:121], v[148:149], v[142:143] op_sel_hi:[1,0,1]
	v_pk_fma_f32 v[192:193], v[118:119], v[148:149], v[140:141] op_sel_hi:[1,0,1]
	v_mul_f32_e32 v155, v191, v191
	v_mul_f32_e32 v154, v193, v193
	v_fmac_f32_e32 v154, v192, v192
	v_fmac_f32_e32 v155, v190, v190
	v_add_f32_e32 v154, v154, v155
	v_add_f32_e32 v149, v149, v154
	v_pk_fma_f32 v[194:195], v[116:117], v[148:149], v[146:147] op_sel_hi:[1,0,1]
	v_pk_fma_f32 v[216:217], v[114:115], v[148:149], v[144:145] op_sel_hi:[1,0,1]
	v_mul_f32_e32 v154, v195, v195
	v_mul_f32_e32 v148, v217, v217
	v_fmac_f32_e32 v148, v216, v216
	v_fmac_f32_e32 v154, v194, v194
	v_add_f32_e32 v148, v148, v154
	v_add_f32_e32 v148, v149, v148
	v_mov_b32_e32 v149, v148
	s_nop 1
	v_permlane16_swap_b32_e32 v148, v149
	v_add_f32_e32 v148, v148, v149
	v_mov_b32_e32 v149, v148
	s_nop 1
	v_permlane32_swap_b32_e32 v148, v149
	v_add_f32_e32 v148, v148, v149
	v_fmamk_f32 v148, v148, 0x3c800000, v229
	v_rsq_f32_e32 v218, v148
	s_nop 0
	v_pk_mul_f32 v[148:149], v[152:153], v[218:219] op_sel_hi:[1,0]
	v_pk_mul_f32 v[150:151], v[150:151], v[218:219] op_sel_hi:[1,0]
	v_pk_mul_f32 v[152:153], v[184:185], v[148:149]
	v_pk_mul_f32 v[154:155], v[182:183], v[150:151]
	v_pk_mul_f32 v[148:149], v[188:189], v[218:219] op_sel_hi:[1,0]
	v_pk_mul_f32 v[150:151], v[186:187], v[218:219] op_sel_hi:[1,0]
	v_pk_mul_f32 v[188:189], v[180:181], v[148:149]
	v_pk_mul_f32 v[186:187], v[178:179], v[150:151]
	v_pk_mul_f32 v[148:149], v[192:193], v[218:219] op_sel_hi:[1,0]
	v_pk_mul_f32 v[150:151], v[190:191], v[218:219] op_sel_hi:[1,0]
	v_pk_mul_f32 v[192:193], v[216:217], v[218:219] op_sel_hi:[1,0]
	v_pk_mul_f32 v[190:191], v[194:195], v[218:219] op_sel_hi:[1,0]
	v_pk_mul_f32 v[150:151], v[160:161], v[150:151]
	v_pk_mul_f32 v[148:149], v[162:163], v[148:149]
	v_pk_mul_f32 v[190:191], v[156:157], v[190:191]
	v_pk_mul_f32 v[192:193], v[158:159], v[192:193]
	s_cbranch_vccnz .LBB0_579
	v_add_u32_e32 v194, 16, v201
	v_and_b32_e32 v194, 0x7c0, v194
	v_add_u32_e32 v195, v205, v194
	v_add_u32_e32 v194, v204, v194
	ds_read_b128 v[216:219], v195
	ds_read_b128 v[220:223], v194
	s_waitcnt lgkmcnt(0)
	v_pk_mul_f32 v[224:225], v[188:189], v[220:221]
	v_pk_mul_f32 v[194:195], v[186:187], v[222:223]
	v_pk_fma_f32 v[224:225], v[152:153], v[216:217], v[224:225] neg_lo:[0,0,1] neg_hi:[0,0,1]
	v_pk_mul_f32 v[152:153], v[152:153], v[220:221]
	v_pk_fma_f32 v[226:227], v[154:155], v[218:219], v[194:195] neg_lo:[0,0,1] neg_hi:[0,0,1]
	v_pk_mul_f32 v[154:155], v[154:155], v[222:223]
	v_pk_fma_f32 v[188:189], v[188:189], v[216:217], v[152:153]
	v_add_u32_e32 v152, v205, v213
	v_add_u32_e32 v194, v204, v213
	v_pk_fma_f32 v[186:187], v[186:187], v[218:219], v[154:155]
	ds_read_b128 v[152:155], v152
	ds_read_b128 v[216:219], v194
	s_waitcnt lgkmcnt(0)
	v_pk_mul_f32 v[194:195], v[190:191], v[218:219]
	v_pk_mul_f32 v[220:221], v[192:193], v[216:217]
	v_pk_fma_f32 v[222:223], v[150:151], v[154:155], v[194:195] neg_lo:[0,0,1] neg_hi:[0,0,1]
	v_pk_fma_f32 v[220:221], v[148:149], v[152:153], v[220:221] neg_lo:[0,0,1] neg_hi:[0,0,1]
	v_pk_mul_f32 v[150:151], v[150:151], v[218:219]
	v_pk_mul_f32 v[148:149], v[148:149], v[216:217]
	v_pk_fma_f32 v[190:191], v[190:191], v[154:155], v[150:151]
	v_pk_fma_f32 v[192:193], v[192:193], v[152:153], v[148:149]
	v_mov_b64_e32 v[148:149], v[220:221]
	v_mov_b64_e32 v[152:153], v[224:225]
	v_mov_b64_e32 v[150:151], v[222:223]
	v_mov_b64_e32 v[154:155], v[226:227]
; #define LAS __attribute__((address_space(3)))
; __device__ __forceinline__ void stg_line_pair(void* base, unsigned roA, unsigned rowb, const u32x4 w0, const u32x4 w1, bool odd) {
;     u32x4 a, b;
; #pragma unroll
;     for (int c = 0; c < 4; ++c) { const unsigned p1 = (unsigned)__builtin_amdgcn_update_dpp(0, (int)w1[c], 0xB1, 0xF, 0xF, false), p0 = (unsigned)__builtin_amdgcn_update_dpp(0, (int)w0[c], 0xB1, 0xF, 0xF, false);
;         a[c] = odd ? p1 : w0[c]; b[c] = odd ? w1[c] : p0; }
;     stg_u4(base, roA, a); stg_u4(base, roA + rowb, b);
; }
;     __device__ __forceinline__ void operator()(const f32x4 (&acc)[2][2][4][2], const pg8::Unit& u, int wr, int wc, int fr, int fq) const {
;     ...
;         for (int ai = 0; ai < 2; ++ai)
; #pragma unroll
;             for (int m = 0; m < 4; ++m) { const float r = rs[ai][m]; f32x4 v[2][2]; float ss = 0.f;
; #pragma unroll
;                 for (int bj = 0; bj < 2; ++bj)
; #pragma unroll
;                     for (int n = 0; n < 2; ++n) { v[bj][n] = acc[ai][bj][m][n] * r + bv[bj][n]; ss += (v[bj][n][0] * v[bj][n][0] + v[bj][n][1] * v[bj][n][1]) + (v[bj][n][2] * v[bj][n][2] + v[bj][n][3] * v[bj][n][3]); }
;                 const float rn = __builtin_amdgcn_rsqf(red4(ss, fq * 16 + fr) * (1.f / 64.f) + EPS);
; #pragma unroll
;                 for (int bj = 0; bj < 2; ++bj)
; #pragma unroll
;                     for (int n = 0; n < 2; ++n) v[bj][n] = v[bj][n] * rn * g4[bj][n];
;                 if (lat) { const unsigned t = (rbase + ai * 128 + m * 16) & (SEQ - 1);
; #pragma unroll
;                     for (int bj = 0; bj < 2; ++bj) { const unsigned pos = bj ? (t & 63u) : (t >> 6); const f32x4 cs = *(const LAS f32x4*)(ropel + pos * 16u + 4u * fq), sn = *(const LAS f32x4*)(ropel + 1024u + pos * 16u + 4u * fq);
;                         const f32x4 x1 = v[bj][0], x2 = v[bj][1]; v[bj][0] = x1 * cs - x2 * sn; v[bj][1] = x2 * cs + x1 * sn; } }
;                 const unsigned ro = offA + (unsigned)(ai * 8 + m) * 32u * pitch;
;                 u32x4 w[2];
; #pragma unroll
;                 for (int bj = 0; bj < 2; ++bj) { w[bj].x = cvtpk_h(v[bj][0][0], v[bj][0][1]); w[bj].y = cvtpk_h(v[bj][0][2], v[bj][0][3]); w[bj].z = cvtpk_h(v[bj][1][0], v[bj][1][1]); w[bj].w = cvtpk_h(v[bj][1][2], v[bj][1][3]); }
;                 stg_line_pair(wst, ro, 2u * pitch, w[0], w[1], odd);
;                 asm volatile("" ::: "memory"); }
.LBB0_579:
	v_cvt_pk_f16_f32 v152, v152, v153
	v_cvt_pk_f16_f32 v153, v154, v155
	v_cvt_pk_f16_f32 v154, v188, v189
	v_cvt_pk_f16_f32 v149, v148, v149
	v_mov_b32_e32 v148, v1
	v_mov_b32_e32 v188, v1
	v_cvt_pk_f16_f32 v150, v150, v151
	v_mov_b32_dpp v148, v149 quad_perm:[1,0,3,2] row_mask:0xf bank_mask:0xf
	v_mov_b32_dpp v188, v152 quad_perm:[1,0,3,2] row_mask:0xf bank_mask:0xf
	v_cndmask_b32_e64 v148, v148, v152, s[2:3]
	v_cndmask_b32_e64 v152, v149, v188, s[2:3]
	v_mov_b32_e32 v149, v1
	v_mov_b32_e32 v188, v1
	v_cvt_pk_f16_f32 v151, v192, v193
	v_mov_b32_dpp v149, v150 quad_perm:[1,0,3,2] row_mask:0xf bank_mask:0xf
	v_mov_b32_dpp v188, v153 quad_perm:[1,0,3,2] row_mask:0xf bank_mask:0xf
	v_cndmask_b32_e64 v149, v149, v153, s[2:3]
	v_cndmask_b32_e64 v153, v150, v188, s[2:3]
	v_mov_b32_e32 v150, v1
	v_mov_b32_e32 v188, v1
	v_cvt_pk_f16_f32 v155, v186, v187
	v_mov_b32_dpp v150, v151 quad_perm:[1,0,3,2] row_mask:0xf bank_mask:0xf
	v_mov_b32_dpp v188, v154 quad_perm:[1,0,3,2] row_mask:0xf bank_mask:0xf
	v_cvt_pk_f16_f32 v186, v190, v191
	v_cndmask_b32_e64 v150, v150, v154, s[2:3]
	v_cndmask_b32_e64 v154, v151, v188, s[2:3]
	v_mov_b32_e32 v151, v1
	v_mov_b32_e32 v188, v1
	v_lshl_add_u32 v187, 32, s42, v206
	v_mov_b32_dpp v151, v186 quad_perm:[1,0,3,2] row_mask:0xf bank_mask:0xf
	v_mov_b32_dpp v188, v155 quad_perm:[1,0,3,2] row_mask:0xf bank_mask:0xf
	v_cndmask_b32_e64 v151, v151, v155, s[2:3]
	v_cndmask_b32_e64 v155, v186, v188, s[2:3]
	s_mov_b32 s100, 2
	global_store_dwordx4 v187, v[148:151], s[36:37]
	v_pk_fma_f32 v[188:189], v[42:43], v[174:175], v[132:133] op_sel_hi:[1,0,1]
	v_pk_fma_f32 v[190:191], v[112:113], v[174:175], v[142:143] op_sel_hi:[1,0,1]
	v_add_u32_e32 v148, s9, v187
	s_mov_b32 s100, 2
	global_store_dwordx4 v148, v[152:155], s[36:37]
	v_pk_fma_f32 v[148:149], v[56:57], v[174:175], v[138:139] op_sel_hi:[1,0,1]
	v_pk_fma_f32 v[150:151], v[54:55], v[174:175], v[136:137] op_sel_hi:[1,0,1]
	v_mul_f32_e32 v153, v149, v149
	v_mul_f32_e32 v152, v151, v151
	v_fmac_f32_e32 v152, v150, v150
	v_fmac_f32_e32 v153, v148, v148
	v_pk_fma_f32 v[186:187], v[44:45], v[174:175], v[134:135] op_sel_hi:[1,0,1]
	v_add_f32_e32 v152, v152, v153
	v_mul_f32_e32 v153, v189, v189
	v_mul_f32_e32 v154, v187, v187
	v_fmac_f32_e32 v153, v188, v188
	v_fmac_f32_e32 v154, v186, v186
	v_add_f32_e32 v153, v153, v154
	v_pk_fma_f32 v[192:193], v[110:111], v[174:175], v[140:141] op_sel_hi:[1,0,1]
	v_add_f32_e32 v152, v152, v153
	v_mul_f32_e32 v153, v193, v193
	v_mul_f32_e32 v154, v191, v191
	v_fmac_f32_e32 v153, v192, v192
	v_fmac_f32_e32 v154, v190, v190
	v_xor_b32_e32 v210, 32, v214
	v_add_f32_e32 v153, v153, v154
	v_pk_fma_f32 v[194:195], v[108:109], v[174:175], v[146:147] op_sel_hi:[1,0,1]
	v_pk_fma_f32 v[214:215], v[106:107], v[174:175], v[144:145] op_sel_hi:[1,0,1]
	v_add_f32_e32 v152, v152, v153
	v_mul_f32_e32 v153, v215, v215
	v_mul_f32_e32 v154, v195, v195
	v_fmac_f32_e32 v153, v214, v214
	v_fmac_f32_e32 v154, v194, v194
	v_add_f32_e32 v153, v153, v154
	v_add_f32_e32 v152, v152, v153
	v_mov_b32_e32 v153, v152
	s_nop 1
	v_permlane16_swap_b32_e32 v152, v153
	v_add_f32_e32 v152, v152, v153
	v_mov_b32_e32 v153, v152
	s_nop 1
	v_permlane32_swap_b32_e32 v152, v153
	v_add_f32_e32 v152, v152, v153
	v_fmamk_f32 v152, v152, 0x3c800000, v229
	v_rsq_f32_e32 v216, v152
	s_and_b64 vcc, exec, s[4:5]
	v_pk_mul_f32 v[150:151], v[150:151], v[216:217] op_sel_hi:[1,0]
	v_pk_mul_f32 v[148:149], v[148:149], v[216:217] op_sel_hi:[1,0]
	v_pk_mul_f32 v[152:153], v[184:185], v[150:151]
	v_pk_mul_f32 v[154:155], v[182:183], v[148:149]
	v_pk_mul_f32 v[148:149], v[188:189], v[216:217] op_sel_hi:[1,0]
	v_pk_mul_f32 v[150:151], v[186:187], v[216:217] op_sel_hi:[1,0]
	v_pk_mul_f32 v[188:189], v[180:181], v[148:149]
	v_pk_mul_f32 v[186:187], v[178:179], v[150:151]
	v_pk_mul_f32 v[148:149], v[192:193], v[216:217] op_sel_hi:[1,0]
	v_pk_mul_f32 v[150:151], v[190:191], v[216:217] op_sel_hi:[1,0]
	v_pk_mul_f32 v[192:193], v[214:215], v[216:217] op_sel_hi:[1,0]
	v_pk_mul_f32 v[190:191], v[194:195], v[216:217] op_sel_hi:[1,0]
	v_pk_mul_f32 v[150:151], v[160:161], v[150:151]
	v_pk_mul_f32 v[148:149], v[162:163], v[148:149]
	v_pk_mul_f32 v[190:191], v[156:157], v[190:191]
	v_pk_mul_f32 v[192:193], v[158:159], v[192:193]
	v_lshlrev_b32_e32 v195, 6, v210
	s_cbranch_vccnz .LBB0_581
	v_add_u32_e32 v194, 32, v201
	v_and_b32_e32 v194, 0x7c0, v194
	v_add_u32_e32 v210, v205, v194
	v_add_u32_e32 v194, v204, v194
	ds_read_b128 v[214:217], v210
	ds_read_b128 v[218:221], v194
	v_add_u32_e32 v194, v204, v195
	s_waitcnt lgkmcnt(0)
	v_pk_mul_f32 v[222:223], v[186:187], v[220:221]
	v_pk_mul_f32 v[226:227], v[188:189], v[218:219]
	v_pk_fma_f32 v[224:225], v[154:155], v[216:217], v[222:223] neg_lo:[0,0,1] neg_hi:[0,0,1]
	v_pk_fma_f32 v[222:223], v[152:153], v[214:215], v[226:227] neg_lo:[0,0,1] neg_hi:[0,0,1]
	v_pk_mul_f32 v[152:153], v[152:153], v[218:219]
	v_pk_mul_f32 v[154:155], v[154:155], v[220:221]
	v_pk_fma_f32 v[188:189], v[188:189], v[214:215], v[152:153]
	v_add_u32_e32 v152, v205, v195
	v_pk_fma_f32 v[186:187], v[186:187], v[216:217], v[154:155]
	ds_read_b128 v[152:155], v152
	ds_read_b128 v[214:217], v194
	s_waitcnt lgkmcnt(0)
	v_pk_mul_f32 v[218:219], v[190:191], v[216:217]
	v_pk_mul_f32 v[226:227], v[192:193], v[214:215]
	v_pk_fma_f32 v[220:221], v[150:151], v[154:155], v[218:219] neg_lo:[0,0,1] neg_hi:[0,0,1]
	v_pk_fma_f32 v[218:219], v[148:149], v[152:153], v[226:227] neg_lo:[0,0,1] neg_hi:[0,0,1]
	v_pk_mul_f32 v[150:151], v[150:151], v[216:217]
	v_pk_mul_f32 v[148:149], v[148:149], v[214:215]
	v_pk_fma_f32 v[190:191], v[190:191], v[154:155], v[150:151]
	v_pk_fma_f32 v[192:193], v[192:193], v[152:153], v[148:149]
	v_mov_b64_e32 v[148:149], v[218:219]
	v_mov_b64_e32 v[152:153], v[222:223]
	v_mov_b64_e32 v[150:151], v[220:221]
	v_mov_b64_e32 v[154:155], v[224:225]
; #define LAS __attribute__((address_space(3)))
; __device__ __forceinline__ void stg_line_pair(void* base, unsigned roA, unsigned rowb, const u32x4 w0, const u32x4 w1, bool odd) {
;     u32x4 a, b;
; #pragma unroll
;     for (int c = 0; c < 4; ++c) { const unsigned p1 = (unsigned)__builtin_amdgcn_update_dpp(0, (int)w1[c], 0xB1, 0xF, 0xF, false), p0 = (unsigned)__builtin_amdgcn_update_dpp(0, (int)w0[c], 0xB1, 0xF, 0xF, false);
;         a[c] = odd ? p1 : w0[c]; b[c] = odd ? w1[c] : p0; }
;     stg_u4(base, roA, a); stg_u4(base, roA + rowb, b);
; }
;     __device__ __forceinline__ void operator()(const f32x4 (&acc)[2][2][4][2], const pg8::Unit& u, int wr, int wc, int fr, int fq) const {
;     ...
;         for (int ai = 0; ai < 2; ++ai)
; #pragma unroll
;             for (int m = 0; m < 4; ++m) { const float r = rs[ai][m]; f32x4 v[2][2]; float ss = 0.f;
; #pragma unroll
;                 for (int bj = 0; bj < 2; ++bj)
; #pragma unroll
;                     for (int n = 0; n < 2; ++n) { v[bj][n] = acc[ai][bj][m][n] * r + bv[bj][n]; ss += (v[bj][n][0] * v[bj][n][0] + v[bj][n][1] * v[bj][n][1]) + (v[bj][n][2] * v[bj][n][2] + v[bj][n][3] * v[bj][n][3]); }
;                 const float rn = __builtin_amdgcn_rsqf(red4(ss, fq * 16 + fr) * (1.f / 64.f) + EPS);
; #pragma unroll
;                 for (int bj = 0; bj < 2; ++bj)
; #pragma unroll
;                     for (int n = 0; n < 2; ++n) v[bj][n] = v[bj][n] * rn * g4[bj][n];
;                 if (lat) { const unsigned t = (rbase + ai * 128 + m * 16) & (SEQ - 1);
; #pragma unroll
;                     for (int bj = 0; bj < 2; ++bj) { const unsigned pos = bj ? (t & 63u) : (t >> 6); const f32x4 cs = *(const LAS f32x4*)(ropel + pos * 16u + 4u * fq), sn = *(const LAS f32x4*)(ropel + 1024u + pos * 16u + 4u * fq);
;                         const f32x4 x1 = v[bj][0], x2 = v[bj][1]; v[bj][0] = x1 * cs - x2 * sn; v[bj][1] = x2 * cs + x1 * sn; } }
;                 const unsigned ro = offA + (unsigned)(ai * 8 + m) * 32u * pitch;
;                 u32x4 w[2];
; #pragma unroll
;                 for (int bj = 0; bj < 2; ++bj) { w[bj].x = cvtpk_h(v[bj][0][0], v[bj][0][1]); w[bj].y = cvtpk_h(v[bj][0][2], v[bj][0][3]); w[bj].z = cvtpk_h(v[bj][1][0], v[bj][1][1]); w[bj].w = cvtpk_h(v[bj][1][2], v[bj][1][3]); }
;                 stg_line_pair(wst, ro, 2u * pitch, w[0], w[1], odd);
;                 asm volatile("" ::: "memory"); }
.LBB0_581:
	v_cvt_pk_f16_f32 v152, v152, v153
	v_cvt_pk_f16_f32 v153, v154, v155
	v_cvt_pk_f16_f32 v154, v188, v189
	v_cvt_pk_f16_f32 v149, v148, v149
	v_mov_b32_e32 v148, v1
	v_mov_b32_e32 v188, v1
	v_cvt_pk_f16_f32 v150, v150, v151
	v_mov_b32_dpp v148, v149 quad_perm:[1,0,3,2] row_mask:0xf bank_mask:0xf
	v_mov_b32_dpp v188, v152 quad_perm:[1,0,3,2] row_mask:0xf bank_mask:0xf
	v_cndmask_b32_e64 v148, v148, v152, s[2:3]
	v_cndmask_b32_e64 v152, v149, v188, s[2:3]
	v_mov_b32_e32 v149, v1
	v_mov_b32_e32 v188, v1
	v_cvt_pk_f16_f32 v151, v192, v193
	v_mov_b32_dpp v149, v150 quad_perm:[1,0,3,2] row_mask:0xf bank_mask:0xf
	v_mov_b32_dpp v188, v153 quad_perm:[1,0,3,2] row_mask:0xf bank_mask:0xf
	v_cndmask_b32_e64 v149, v149, v153, s[2:3]
	v_cndmask_b32_e64 v153, v150, v188, s[2:3]
	v_mov_b32_e32 v150, v1
	v_mov_b32_e32 v188, v1
	v_cvt_pk_f16_f32 v155, v186, v187
	v_mov_b32_dpp v150, v151 quad_perm:[1,0,3,2] row_mask:0xf bank_mask:0xf
	v_mov_b32_dpp v188, v154 quad_perm:[1,0,3,2] row_mask:0xf bank_mask:0xf
	v_cvt_pk_f16_f32 v186, v190, v191
	v_cndmask_b32_e64 v150, v150, v154, s[2:3]
	v_cndmask_b32_e64 v154, v151, v188, s[2:3]
	v_mov_b32_e32 v151, v1
	v_mov_b32_e32 v188, v1
	v_lshl_add_u32 v187, 64, s42, v206
	v_mov_b32_dpp v151, v186 quad_perm:[1,0,3,2] row_mask:0xf bank_mask:0xf
	v_mov_b32_dpp v188, v155 quad_perm:[1,0,3,2] row_mask:0xf bank_mask:0xf
	v_cndmask_b32_e64 v151, v151, v155, s[2:3]
	v_cndmask_b32_e64 v155, v186, v188, s[2:3]
	s_mov_b32 s100, 2
	global_store_dwordx4 v187, v[148:151], s[36:37]
	v_add_u32_e32 v194, 48, v202
	v_and_b32_e32 v210, 63, v194
	v_add_u32_e32 v148, s9, v187
	s_mov_b32 s100, 2
	global_store_dwordx4 v148, v[152:155], s[36:37]
	v_mov_b32_e32 v148, v175
	v_pk_fma_f32 v[150:151], v[40:41], v[148:149], v[138:139] op_sel_hi:[1,0,1]
	v_pk_fma_f32 v[152:153], v[38:39], v[148:149], v[136:137] op_sel_hi:[1,0,1]
	v_mul_f32_e32 v154, v151, v151
	v_mul_f32_e32 v149, v153, v153
	v_fmac_f32_e32 v149, v152, v152
	v_fmac_f32_e32 v154, v150, v150
	v_add_f32_e32 v149, v149, v154
	v_pk_fma_f32 v[186:187], v[36:37], v[148:149], v[134:135] op_sel_hi:[1,0,1]
	v_pk_fma_f32 v[188:189], v[34:35], v[148:149], v[132:133] op_sel_hi:[1,0,1]
	v_mul_f32_e32 v155, v187, v187
	v_mul_f32_e32 v154, v189, v189
	v_fmac_f32_e32 v154, v188, v188
	v_fmac_f32_e32 v155, v186, v186
	v_add_f32_e32 v154, v154, v155
	v_add_f32_e32 v149, v149, v154
	v_pk_fma_f32 v[190:191], v[104:105], v[148:149], v[142:143] op_sel_hi:[1,0,1]
	v_pk_fma_f32 v[192:193], v[102:103], v[148:149], v[140:141] op_sel_hi:[1,0,1]
	v_mul_f32_e32 v155, v191, v191
	v_mul_f32_e32 v154, v193, v193
	v_fmac_f32_e32 v154, v192, v192
	v_fmac_f32_e32 v155, v190, v190
	v_add_f32_e32 v154, v154, v155
	v_add_f32_e32 v149, v149, v154
	v_pk_fma_f32 v[214:215], v[100:101], v[148:149], v[146:147] op_sel_hi:[1,0,1]
	v_pk_fma_f32 v[216:217], v[98:99], v[148:149], v[144:145] op_sel_hi:[1,0,1]
	v_mul_f32_e32 v154, v215, v215
	v_mul_f32_e32 v148, v217, v217
	v_fmac_f32_e32 v148, v216, v216
	v_fmac_f32_e32 v154, v214, v214
	v_add_f32_e32 v148, v148, v154
	v_add_f32_e32 v148, v149, v148
	v_mov_b32_e32 v149, v148
	s_nop 1
	v_permlane16_swap_b32_e32 v148, v149
	v_add_f32_e32 v148, v148, v149
	v_mov_b32_e32 v149, v148
	s_nop 1
	v_permlane32_swap_b32_e32 v148, v149
	v_add_f32_e32 v148, v148, v149
	v_fmamk_f32 v148, v148, 0x3c800000, v229
	v_rsq_f32_e32 v194, v148
	s_and_b64 vcc, exec, s[4:5]
	v_pk_mul_f32 v[148:149], v[152:153], v[194:195] op_sel_hi:[1,0]
	v_pk_mul_f32 v[150:151], v[150:151], v[194:195] op_sel_hi:[1,0]
	v_pk_mul_f32 v[152:153], v[184:185], v[148:149]
	v_pk_mul_f32 v[154:155], v[182:183], v[150:151]
	v_pk_mul_f32 v[148:149], v[188:189], v[194:195] op_sel_hi:[1,0]
	v_pk_mul_f32 v[150:151], v[186:187], v[194:195] op_sel_hi:[1,0]
	v_pk_mul_f32 v[188:189], v[180:181], v[148:149]
	v_pk_mul_f32 v[186:187], v[178:179], v[150:151]
	v_pk_mul_f32 v[148:149], v[192:193], v[194:195] op_sel_hi:[1,0]
	v_pk_mul_f32 v[150:151], v[190:191], v[194:195] op_sel_hi:[1,0]
	v_pk_mul_f32 v[192:193], v[216:217], v[194:195] op_sel_hi:[1,0]
	v_pk_mul_f32 v[190:191], v[214:215], v[194:195] op_sel_hi:[1,0]
	v_pk_mul_f32 v[150:151], v[160:161], v[150:151]
	v_pk_mul_f32 v[148:149], v[162:163], v[148:149]
	v_pk_mul_f32 v[190:191], v[156:157], v[190:191]
	v_pk_mul_f32 v[192:193], v[158:159], v[192:193]
	v_lshlrev_b32_e32 v194, 6, v210
	s_cbranch_vccnz .LBB0_583
	v_add_u32_e32 v210, 48, v201
	v_and_b32_e32 v210, 0x7c0, v210
	v_add_u32_e32 v211, v205, v210
	v_add_u32_e32 v210, v204, v210
	ds_read_b128 v[214:217], v211
	ds_read_b128 v[218:221], v210
	v_add_u32_e32 v210, v204, v194
	s_waitcnt lgkmcnt(0)
	v_pk_mul_f32 v[222:223], v[186:187], v[220:221]
	v_pk_mul_f32 v[226:227], v[188:189], v[218:219]
	v_pk_fma_f32 v[224:225], v[154:155], v[216:217], v[222:223] neg_lo:[0,0,1] neg_hi:[0,0,1]
	v_pk_fma_f32 v[222:223], v[152:153], v[214:215], v[226:227] neg_lo:[0,0,1] neg_hi:[0,0,1]
	v_pk_mul_f32 v[152:153], v[152:153], v[218:219]
	v_pk_mul_f32 v[154:155], v[154:155], v[220:221]
	v_pk_fma_f32 v[188:189], v[188:189], v[214:215], v[152:153]
	v_add_u32_e32 v152, v205, v194
	v_pk_fma_f32 v[186:187], v[186:187], v[216:217], v[154:155]
	ds_read_b128 v[152:155], v152
	ds_read_b128 v[214:217], v210
	s_waitcnt lgkmcnt(0)
	v_pk_mul_f32 v[218:219], v[190:191], v[216:217]
	v_pk_mul_f32 v[226:227], v[192:193], v[214:215]
	v_pk_fma_f32 v[220:221], v[150:151], v[154:155], v[218:219] neg_lo:[0,0,1] neg_hi:[0,0,1]
	v_pk_fma_f32 v[218:219], v[148:149], v[152:153], v[226:227] neg_lo:[0,0,1] neg_hi:[0,0,1]
	v_pk_mul_f32 v[150:151], v[150:151], v[216:217]
	v_pk_mul_f32 v[148:149], v[148:149], v[214:215]
	v_pk_fma_f32 v[190:191], v[190:191], v[154:155], v[150:151]
	v_pk_fma_f32 v[192:193], v[192:193], v[152:153], v[148:149]
	v_mov_b64_e32 v[148:149], v[218:219]
	v_mov_b64_e32 v[152:153], v[222:223]
	v_mov_b64_e32 v[150:151], v[220:221]
	v_mov_b64_e32 v[154:155], v[224:225]
; #define LAS __attribute__((address_space(3)))
; __device__ __forceinline__ void stg_line_pair(void* base, unsigned roA, unsigned rowb, const u32x4 w0, const u32x4 w1, bool odd) {
;     u32x4 a, b;
; #pragma unroll
;     for (int c = 0; c < 4; ++c) { const unsigned p1 = (unsigned)__builtin_amdgcn_update_dpp(0, (int)w1[c], 0xB1, 0xF, 0xF, false), p0 = (unsigned)__builtin_amdgcn_update_dpp(0, (int)w0[c], 0xB1, 0xF, 0xF, false);
;         a[c] = odd ? p1 : w0[c]; b[c] = odd ? w1[c] : p0; }
;     stg_u4(base, roA, a); stg_u4(base, roA + rowb, b);
; }
;     __device__ __forceinline__ void operator()(const f32x4 (&acc)[2][2][4][2], const pg8::Unit& u, int wr, int wc, int fr, int fq) const {
;     ...
;         for (int ai = 0; ai < 2; ++ai)
; #pragma unroll
;             for (int m = 0; m < 4; ++m) { const float r = rs[ai][m]; f32x4 v[2][2]; float ss = 0.f;
; #pragma unroll
;                 for (int bj = 0; bj < 2; ++bj)
; #pragma unroll
;                     for (int n = 0; n < 2; ++n) { v[bj][n] = acc[ai][bj][m][n] * r + bv[bj][n]; ss += (v[bj][n][0] * v[bj][n][0] + v[bj][n][1] * v[bj][n][1]) + (v[bj][n][2] * v[bj][n][2] + v[bj][n][3] * v[bj][n][3]); }
;                 const float rn = __builtin_amdgcn_rsqf(red4(ss, fq * 16 + fr) * (1.f / 64.f) + EPS);
; #pragma unroll
;                 for (int bj = 0; bj < 2; ++bj)
; #pragma unroll
;                     for (int n = 0; n < 2; ++n) v[bj][n] = v[bj][n] * rn * g4[bj][n];
;                 if (lat) { const unsigned t = (rbase + ai * 128 + m * 16) & (SEQ - 1);
; #pragma unroll
;                     for (int bj = 0; bj < 2; ++bj) { const unsigned pos = bj ? (t & 63u) : (t >> 6); const f32x4 cs = *(const LAS f32x4*)(ropel + pos * 16u + 4u * fq), sn = *(const LAS f32x4*)(ropel + 1024u + pos * 16u + 4u * fq);
;                         const f32x4 x1 = v[bj][0], x2 = v[bj][1]; v[bj][0] = x1 * cs - x2 * sn; v[bj][1] = x2 * cs + x1 * sn; } }
;                 const unsigned ro = offA + (unsigned)(ai * 8 + m) * 32u * pitch;
;                 u32x4 w[2];
; #pragma unroll
;                 for (int bj = 0; bj < 2; ++bj) { w[bj].x = cvtpk_h(v[bj][0][0], v[bj][0][1]); w[bj].y = cvtpk_h(v[bj][0][2], v[bj][0][3]); w[bj].z = cvtpk_h(v[bj][1][0], v[bj][1][1]); w[bj].w = cvtpk_h(v[bj][1][2], v[bj][1][3]); }
;                 stg_line_pair(wst, ro, 2u * pitch, w[0], w[1], odd);
;                 asm volatile("" ::: "memory"); }
.LBB0_583:
	v_cvt_pk_f16_f32 v152, v152, v153
	v_cvt_pk_f16_f32 v153, v154, v155
	v_cvt_pk_f16_f32 v154, v188, v189
	v_cvt_pk_f16_f32 v149, v148, v149
	v_mov_b32_e32 v148, v1
	v_mov_b32_e32 v188, v1
	v_cvt_pk_f16_f32 v150, v150, v151
	v_mov_b32_dpp v148, v149 quad_perm:[1,0,3,2] row_mask:0xf bank_mask:0xf
	v_mov_b32_dpp v188, v152 quad_perm:[1,0,3,2] row_mask:0xf bank_mask:0xf
	v_cndmask_b32_e64 v148, v148, v152, s[2:3]
	v_cndmask_b32_e64 v152, v149, v188, s[2:3]
	v_mov_b32_e32 v149, v1
	v_mov_b32_e32 v188, v1
	v_cvt_pk_f16_f32 v151, v192, v193
	v_mov_b32_dpp v149, v150 quad_perm:[1,0,3,2] row_mask:0xf bank_mask:0xf
	v_mov_b32_dpp v188, v153 quad_perm:[1,0,3,2] row_mask:0xf bank_mask:0xf
	v_cndmask_b32_e64 v149, v149, v153, s[2:3]
	v_cndmask_b32_e64 v153, v150, v188, s[2:3]
	v_mov_b32_e32 v150, v1
	v_mov_b32_e32 v188, v1
	v_cvt_pk_f16_f32 v155, v186, v187
	v_mov_b32_dpp v150, v151 quad_perm:[1,0,3,2] row_mask:0xf bank_mask:0xf
	v_mov_b32_dpp v188, v154 quad_perm:[1,0,3,2] row_mask:0xf bank_mask:0xf
	v_cvt_pk_f16_f32 v186, v190, v191
	v_cndmask_b32_e64 v150, v150, v154, s[2:3]
	v_cndmask_b32_e64 v154, v151, v188, s[2:3]
	v_mov_b32_e32 v151, v1
	s_lshl_b32 s38, 0x60, s42
	v_mov_b32_e32 v188, v1
	v_mov_b32_dpp v151, v186 quad_perm:[1,0,3,2] row_mask:0xf bank_mask:0xf
	v_add_u32_e32 v187, s38, v206
	v_mov_b32_dpp v188, v155 quad_perm:[1,0,3,2] row_mask:0xf bank_mask:0xf
	v_cndmask_b32_e64 v151, v151, v155, s[2:3]
	v_cndmask_b32_e64 v155, v186, v188, s[2:3]
	s_mov_b32 s100, 2
	global_store_dwordx4 v187, v[148:151], s[36:37]
	v_pk_fma_f32 v[188:189], v[26:27], v[172:173], v[132:133] op_sel_hi:[1,0,1]
	v_pk_fma_f32 v[190:191], v[96:97], v[172:173], v[142:143] op_sel_hi:[1,0,1]
	v_add_u32_e32 v148, s9, v187
	s_mov_b32 s100, 2
	global_store_dwordx4 v148, v[152:155], s[36:37]
	v_pk_fma_f32 v[148:149], v[32:33], v[172:173], v[138:139] op_sel_hi:[1,0,1]
	v_pk_fma_f32 v[150:151], v[30:31], v[172:173], v[136:137] op_sel_hi:[1,0,1]
	v_mul_f32_e32 v153, v149, v149
	v_mul_f32_e32 v152, v151, v151
	v_fmac_f32_e32 v152, v150, v150
	v_fmac_f32_e32 v153, v148, v148
	v_pk_fma_f32 v[186:187], v[28:29], v[172:173], v[134:135] op_sel_hi:[1,0,1]
	v_add_f32_e32 v152, v152, v153
	v_mul_f32_e32 v153, v189, v189
	v_mul_f32_e32 v154, v187, v187
	v_fmac_f32_e32 v153, v188, v188
	v_fmac_f32_e32 v154, v186, v186
	v_add_f32_e32 v153, v153, v154
	v_pk_fma_f32 v[192:193], v[94:95], v[172:173], v[140:141] op_sel_hi:[1,0,1]
	v_add_f32_e32 v152, v152, v153
	v_mul_f32_e32 v153, v193, v193
	v_mul_f32_e32 v154, v191, v191
	v_fmac_f32_e32 v153, v192, v192
	v_fmac_f32_e32 v154, v190, v190
	v_add_f32_e32 v153, v153, v154
	v_pk_fma_f32 v[214:215], v[92:93], v[172:173], v[146:147] op_sel_hi:[1,0,1]
	v_pk_fma_f32 v[216:217], v[90:91], v[172:173], v[144:145] op_sel_hi:[1,0,1]
	v_add_f32_e32 v152, v153, v152
	v_mul_f32_e32 v153, v217, v217
	v_mul_f32_e32 v154, v215, v215
	v_fmac_f32_e32 v153, v216, v216
	v_fmac_f32_e32 v154, v214, v214
	v_add_f32_e32 v153, v153, v154
	v_add_f32_e32 v152, v153, v152
	v_mov_b32_e32 v153, v152
	s_nop 1
	v_permlane16_swap_b32_e32 v152, v153
	v_add_f32_e32 v152, v152, v153
	v_mov_b32_e32 v153, v152
	s_nop 1
	v_permlane32_swap_b32_e32 v152, v153
	v_add_f32_e32 v152, v152, v153
	v_fmamk_f32 v152, v152, 0x3c800000, v229
	v_rsq_f32_e32 v218, v152
	s_and_b64 vcc, exec, s[4:5]
	v_pk_mul_f32 v[150:151], v[150:151], v[218:219] op_sel_hi:[1,0]
	v_pk_mul_f32 v[148:149], v[148:149], v[218:219] op_sel_hi:[1,0]
	v_pk_mul_f32 v[152:153], v[184:185], v[150:151]
	v_pk_mul_f32 v[154:155], v[182:183], v[148:149]
	v_pk_mul_f32 v[148:149], v[188:189], v[218:219] op_sel_hi:[1,0]
	v_pk_mul_f32 v[150:151], v[186:187], v[218:219] op_sel_hi:[1,0]
	v_pk_mul_f32 v[188:189], v[180:181], v[148:149]
	v_pk_mul_f32 v[186:187], v[178:179], v[150:151]
	v_pk_mul_f32 v[148:149], v[192:193], v[218:219] op_sel_hi:[1,0]
	v_pk_mul_f32 v[150:151], v[190:191], v[218:219] op_sel_hi:[1,0]
	v_pk_mul_f32 v[192:193], v[216:217], v[218:219] op_sel_hi:[1,0]
	v_pk_mul_f32 v[190:191], v[214:215], v[218:219] op_sel_hi:[1,0]
	v_pk_mul_f32 v[150:151], v[160:161], v[150:151]
	v_pk_mul_f32 v[148:149], v[162:163], v[148:149]
	v_pk_mul_f32 v[190:191], v[156:157], v[190:191]
	v_pk_mul_f32 v[192:193], v[158:159], v[192:193]
	s_cbranch_vccnz .LBB0_585
	v_add_u32_e32 v210, 0x80, v201
	v_and_b32_e32 v210, 0x7c0, v210
	v_add_u32_e32 v211, v205, v210
	v_add_u32_e32 v210, v204, v210
	ds_read_b128 v[214:217], v211
	ds_read_b128 v[218:221], v210
	s_waitcnt lgkmcnt(0)
	v_pk_mul_f32 v[222:223], v[186:187], v[220:221]
	v_pk_mul_f32 v[226:227], v[188:189], v[218:219]
	v_pk_fma_f32 v[224:225], v[154:155], v[216:217], v[222:223] neg_lo:[0,0,1] neg_hi:[0,0,1]
	v_pk_fma_f32 v[222:223], v[152:153], v[214:215], v[226:227] neg_lo:[0,0,1] neg_hi:[0,0,1]
	v_pk_mul_f32 v[152:153], v[152:153], v[218:219]
	v_pk_mul_f32 v[154:155], v[154:155], v[220:221]
	v_pk_fma_f32 v[188:189], v[188:189], v[214:215], v[152:153]
	v_add_u32_e32 v152, v205, v207
	v_add_u32_e32 v207, v204, v207
	v_pk_fma_f32 v[186:187], v[186:187], v[216:217], v[154:155]
	ds_read_b128 v[152:155], v152
	ds_read_b128 v[214:217], v207
	s_waitcnt lgkmcnt(0)
	v_pk_mul_f32 v[218:219], v[190:191], v[216:217]
	v_pk_mul_f32 v[226:227], v[192:193], v[214:215]
	v_pk_fma_f32 v[220:221], v[150:151], v[154:155], v[218:219] neg_lo:[0,0,1] neg_hi:[0,0,1]
	v_pk_fma_f32 v[218:219], v[148:149], v[152:153], v[226:227] neg_lo:[0,0,1] neg_hi:[0,0,1]
	v_pk_mul_f32 v[150:151], v[150:151], v[216:217]
	v_pk_mul_f32 v[148:149], v[148:149], v[214:215]
	v_pk_fma_f32 v[190:191], v[190:191], v[154:155], v[150:151]
	v_pk_fma_f32 v[192:193], v[192:193], v[152:153], v[148:149]
	v_mov_b64_e32 v[148:149], v[218:219]
	v_mov_b64_e32 v[152:153], v[222:223]
	v_mov_b64_e32 v[150:151], v[220:221]
	v_mov_b64_e32 v[154:155], v[224:225]
; #define LAS __attribute__((address_space(3)))
; __device__ __forceinline__ void stg_line_pair(void* base, unsigned roA, unsigned rowb, const u32x4 w0, const u32x4 w1, bool odd) {
;     u32x4 a, b;
; #pragma unroll
;     for (int c = 0; c < 4; ++c) { const unsigned p1 = (unsigned)__builtin_amdgcn_update_dpp(0, (int)w1[c], 0xB1, 0xF, 0xF, false), p0 = (unsigned)__builtin_amdgcn_update_dpp(0, (int)w0[c], 0xB1, 0xF, 0xF, false);
;         a[c] = odd ? p1 : w0[c]; b[c] = odd ? w1[c] : p0; }
;     stg_u4(base, roA, a); stg_u4(base, roA + rowb, b);
; }
;     __device__ __forceinline__ void operator()(const f32x4 (&acc)[2][2][4][2], const pg8::Unit& u, int wr, int wc, int fr, int fq) const {
;     ...
;         for (int ai = 0; ai < 2; ++ai)
; #pragma unroll
;             for (int m = 0; m < 4; ++m) { const float r = rs[ai][m]; f32x4 v[2][2]; float ss = 0.f;
; #pragma unroll
;                 for (int bj = 0; bj < 2; ++bj)
; #pragma unroll
;                     for (int n = 0; n < 2; ++n) { v[bj][n] = acc[ai][bj][m][n] * r + bv[bj][n]; ss += (v[bj][n][0] * v[bj][n][0] + v[bj][n][1] * v[bj][n][1]) + (v[bj][n][2] * v[bj][n][2] + v[bj][n][3] * v[bj][n][3]); }
;                 const float rn = __builtin_amdgcn_rsqf(red4(ss, fq * 16 + fr) * (1.f / 64.f) + EPS);
; #pragma unroll
;                 for (int bj = 0; bj < 2; ++bj)
; #pragma unroll
;                     for (int n = 0; n < 2; ++n) v[bj][n] = v[bj][n] * rn * g4[bj][n];
;                 if (lat) { const unsigned t = (rbase + ai * 128 + m * 16) & (SEQ - 1);
; #pragma unroll
;                     for (int bj = 0; bj < 2; ++bj) { const unsigned pos = bj ? (t & 63u) : (t >> 6); const f32x4 cs = *(const LAS f32x4*)(ropel + pos * 16u + 4u * fq), sn = *(const LAS f32x4*)(ropel + 1024u + pos * 16u + 4u * fq);
;                         const f32x4 x1 = v[bj][0], x2 = v[bj][1]; v[bj][0] = x1 * cs - x2 * sn; v[bj][1] = x2 * cs + x1 * sn; } }
;                 const unsigned ro = offA + (unsigned)(ai * 8 + m) * 32u * pitch;
;                 u32x4 w[2];
; #pragma unroll
;                 for (int bj = 0; bj < 2; ++bj) { w[bj].x = cvtpk_h(v[bj][0][0], v[bj][0][1]); w[bj].y = cvtpk_h(v[bj][0][2], v[bj][0][3]); w[bj].z = cvtpk_h(v[bj][1][0], v[bj][1][1]); w[bj].w = cvtpk_h(v[bj][1][2], v[bj][1][3]); }
;                 stg_line_pair(wst, ro, 2u * pitch, w[0], w[1], odd);
;                 asm volatile("" ::: "memory"); }
.LBB0_585:
	v_cvt_pk_f16_f32 v152, v152, v153
	v_cvt_pk_f16_f32 v153, v154, v155
	v_cvt_pk_f16_f32 v154, v188, v189
	v_cvt_pk_f16_f32 v149, v148, v149
	v_mov_b32_e32 v148, v1
	v_mov_b32_e32 v188, v1
	v_cvt_pk_f16_f32 v150, v150, v151
	v_mov_b32_dpp v148, v149 quad_perm:[1,0,3,2] row_mask:0xf bank_mask:0xf
	v_mov_b32_dpp v188, v152 quad_perm:[1,0,3,2] row_mask:0xf bank_mask:0xf
	v_cndmask_b32_e64 v148, v148, v152, s[2:3]
	v_cndmask_b32_e64 v152, v149, v188, s[2:3]
	v_mov_b32_e32 v149, v1
	v_mov_b32_e32 v188, v1
	v_cvt_pk_f16_f32 v151, v192, v193
	v_mov_b32_dpp v149, v150 quad_perm:[1,0,3,2] row_mask:0xf bank_mask:0xf
	v_mov_b32_dpp v188, v153 quad_perm:[1,0,3,2] row_mask:0xf bank_mask:0xf
	v_cndmask_b32_e64 v149, v149, v153, s[2:3]
	v_cndmask_b32_e64 v153, v150, v188, s[2:3]
	v_mov_b32_e32 v150, v1
	v_mov_b32_e32 v188, v1
	v_cvt_pk_f16_f32 v155, v186, v187
	v_mov_b32_dpp v150, v151 quad_perm:[1,0,3,2] row_mask:0xf bank_mask:0xf
	v_mov_b32_dpp v188, v154 quad_perm:[1,0,3,2] row_mask:0xf bank_mask:0xf
	v_cvt_pk_f16_f32 v186, v190, v191
	v_cndmask_b32_e64 v150, v150, v154, s[2:3]
	v_cndmask_b32_e64 v154, v151, v188, s[2:3]
	v_mov_b32_e32 v151, v1
	s_lshl_b32 s38, 0x100, s42
	v_mov_b32_e32 v188, v1
	v_mov_b32_dpp v151, v186 quad_perm:[1,0,3,2] row_mask:0xf bank_mask:0xf
	v_add_u32_e32 v187, s38, v206
	v_mov_b32_dpp v188, v155 quad_perm:[1,0,3,2] row_mask:0xf bank_mask:0xf
	v_cndmask_b32_e64 v151, v151, v155, s[2:3]
	v_cndmask_b32_e64 v155, v186, v188, s[2:3]
	s_mov_b32 s100, 2
	global_store_dwordx4 v187, v[148:151], s[36:37]
	s_and_b64 vcc, exec, s[4:5]
	s_nop 0
	v_add_u32_e32 v148, s9, v187
	s_mov_b32 s100, 2
	global_store_dwordx4 v148, v[152:155], s[36:37]
	v_mov_b32_e32 v148, v173
	v_pk_fma_f32 v[150:151], v[24:25], v[148:149], v[138:139] op_sel_hi:[1,0,1]
	v_pk_fma_f32 v[152:153], v[22:23], v[148:149], v[136:137] op_sel_hi:[1,0,1]
	v_mul_f32_e32 v154, v151, v151
	v_mul_f32_e32 v149, v153, v153
	v_fmac_f32_e32 v149, v152, v152
	v_fmac_f32_e32 v154, v150, v150
	v_add_f32_e32 v149, v149, v154
	v_pk_fma_f32 v[186:187], v[20:21], v[148:149], v[134:135] op_sel_hi:[1,0,1]
	v_pk_fma_f32 v[188:189], v[18:19], v[148:149], v[132:133] op_sel_hi:[1,0,1]
	v_mul_f32_e32 v155, v187, v187
	v_mul_f32_e32 v154, v189, v189
	v_fmac_f32_e32 v154, v188, v188
	v_fmac_f32_e32 v155, v186, v186
	v_add_f32_e32 v154, v154, v155
	v_add_f32_e32 v149, v149, v154
	v_pk_fma_f32 v[190:191], v[88:89], v[148:149], v[142:143] op_sel_hi:[1,0,1]
	v_pk_fma_f32 v[192:193], v[86:87], v[148:149], v[140:141] op_sel_hi:[1,0,1]
	v_mul_f32_e32 v155, v191, v191
	v_mul_f32_e32 v154, v193, v193
	v_fmac_f32_e32 v154, v192, v192
	v_fmac_f32_e32 v155, v190, v190
	v_add_f32_e32 v154, v154, v155
	v_add_f32_e32 v149, v154, v149
	v_pk_fma_f32 v[214:215], v[84:85], v[148:149], v[146:147] op_sel_hi:[1,0,1]
	v_pk_fma_f32 v[216:217], v[82:83], v[148:149], v[144:145] op_sel_hi:[1,0,1]
	v_mul_f32_e32 v154, v215, v215
	v_mul_f32_e32 v148, v217, v217
	v_fmac_f32_e32 v148, v216, v216
	v_fmac_f32_e32 v154, v214, v214
	v_add_f32_e32 v148, v148, v154
	v_add_f32_e32 v148, v148, v149
	v_mov_b32_e32 v149, v148
	s_nop 1
	v_permlane16_swap_b32_e32 v148, v149
	v_add_f32_e32 v148, v148, v149
	v_mov_b32_e32 v149, v148
	s_nop 1
	v_permlane32_swap_b32_e32 v148, v149
	v_add_f32_e32 v148, v148, v149
	v_fmamk_f32 v148, v148, 0x3c800000, v229
	v_rsq_f32_e32 v218, v148
	s_nop 0
	v_pk_mul_f32 v[148:149], v[152:153], v[218:219] op_sel_hi:[1,0]
	v_pk_mul_f32 v[150:151], v[150:151], v[218:219] op_sel_hi:[1,0]
	v_pk_mul_f32 v[152:153], v[184:185], v[148:149]
	v_pk_mul_f32 v[154:155], v[182:183], v[150:151]
	v_pk_mul_f32 v[148:149], v[188:189], v[218:219] op_sel_hi:[1,0]
	v_pk_mul_f32 v[150:151], v[186:187], v[218:219] op_sel_hi:[1,0]
	v_pk_mul_f32 v[188:189], v[180:181], v[148:149]
	v_pk_mul_f32 v[186:187], v[178:179], v[150:151]
	v_pk_mul_f32 v[148:149], v[192:193], v[218:219] op_sel_hi:[1,0]
	v_pk_mul_f32 v[150:151], v[190:191], v[218:219] op_sel_hi:[1,0]
	v_pk_mul_f32 v[192:193], v[216:217], v[218:219] op_sel_hi:[1,0]
	v_pk_mul_f32 v[190:191], v[214:215], v[218:219] op_sel_hi:[1,0]
	v_pk_mul_f32 v[150:151], v[160:161], v[150:151]
	v_pk_mul_f32 v[148:149], v[162:163], v[148:149]
	v_pk_mul_f32 v[190:191], v[156:157], v[190:191]
	v_pk_mul_f32 v[192:193], v[158:159], v[192:193]
	s_cbranch_vccnz .LBB0_587
	v_add_u32_e32 v207, 0x90, v201
	v_and_b32_e32 v207, 0x7c0, v207
	v_add_u32_e32 v210, v205, v207
	v_add_u32_e32 v207, v204, v207
	ds_read_b128 v[214:217], v210
	ds_read_b128 v[218:221], v207
	v_add_u32_e32 v207, v204, v213
	s_waitcnt lgkmcnt(0)
	v_pk_mul_f32 v[222:223], v[186:187], v[220:221]
	v_pk_mul_f32 v[226:227], v[188:189], v[218:219]
	v_pk_fma_f32 v[224:225], v[154:155], v[216:217], v[222:223] neg_lo:[0,0,1] neg_hi:[0,0,1]
	v_pk_fma_f32 v[222:223], v[152:153], v[214:215], v[226:227] neg_lo:[0,0,1] neg_hi:[0,0,1]
	v_pk_mul_f32 v[152:153], v[152:153], v[218:219]
	v_pk_mul_f32 v[154:155], v[154:155], v[220:221]
	v_pk_fma_f32 v[188:189], v[188:189], v[214:215], v[152:153]
	v_add_u32_e32 v152, v205, v213
	v_pk_fma_f32 v[186:187], v[186:187], v[216:217], v[154:155]
	ds_read_b128 v[152:155], v152
	ds_read_b128 v[214:217], v207
	s_waitcnt lgkmcnt(0)
	v_pk_mul_f32 v[218:219], v[190:191], v[216:217]
	v_pk_mul_f32 v[226:227], v[192:193], v[214:215]
	v_pk_fma_f32 v[220:221], v[150:151], v[154:155], v[218:219] neg_lo:[0,0,1] neg_hi:[0,0,1]
	v_pk_fma_f32 v[218:219], v[148:149], v[152:153], v[226:227] neg_lo:[0,0,1] neg_hi:[0,0,1]
	v_pk_mul_f32 v[150:151], v[150:151], v[216:217]
	v_pk_mul_f32 v[148:149], v[148:149], v[214:215]
	v_pk_fma_f32 v[190:191], v[190:191], v[154:155], v[150:151]
	v_pk_fma_f32 v[192:193], v[192:193], v[152:153], v[148:149]
	v_mov_b64_e32 v[148:149], v[218:219]
	v_mov_b64_e32 v[152:153], v[222:223]
	v_mov_b64_e32 v[150:151], v[220:221]
	v_mov_b64_e32 v[154:155], v[224:225]
; #define LAS __attribute__((address_space(3)))
; __device__ __forceinline__ void stg_line_pair(void* base, unsigned roA, unsigned rowb, const u32x4 w0, const u32x4 w1, bool odd) {
;     u32x4 a, b;
; #pragma unroll
;     for (int c = 0; c < 4; ++c) { const unsigned p1 = (unsigned)__builtin_amdgcn_update_dpp(0, (int)w1[c], 0xB1, 0xF, 0xF, false), p0 = (unsigned)__builtin_amdgcn_update_dpp(0, (int)w0[c], 0xB1, 0xF, 0xF, false);
;         a[c] = odd ? p1 : w0[c]; b[c] = odd ? w1[c] : p0; }
;     stg_u4(base, roA, a); stg_u4(base, roA + rowb, b);
; }
;     __device__ __forceinline__ void operator()(const f32x4 (&acc)[2][2][4][2], const pg8::Unit& u, int wr, int wc, int fr, int fq) const {
;     ...
;         for (int ai = 0; ai < 2; ++ai)
; #pragma unroll
;             for (int m = 0; m < 4; ++m) { const float r = rs[ai][m]; f32x4 v[2][2]; float ss = 0.f;
; #pragma unroll
;                 for (int bj = 0; bj < 2; ++bj)
; #pragma unroll
;                     for (int n = 0; n < 2; ++n) { v[bj][n] = acc[ai][bj][m][n] * r + bv[bj][n]; ss += (v[bj][n][0] * v[bj][n][0] + v[bj][n][1] * v[bj][n][1]) + (v[bj][n][2] * v[bj][n][2] + v[bj][n][3] * v[bj][n][3]); }
;                 const float rn = __builtin_amdgcn_rsqf(red4(ss, fq * 16 + fr) * (1.f / 64.f) + EPS);
; #pragma unroll
;                 for (int bj = 0; bj < 2; ++bj)
; #pragma unroll
;                     for (int n = 0; n < 2; ++n) v[bj][n] = v[bj][n] * rn * g4[bj][n];
;                 if (lat) { const unsigned t = (rbase + ai * 128 + m * 16) & (SEQ - 1);
; #pragma unroll
;                     for (int bj = 0; bj < 2; ++bj) { const unsigned pos = bj ? (t & 63u) : (t >> 6); const f32x4 cs = *(const LAS f32x4*)(ropel + pos * 16u + 4u * fq), sn = *(const LAS f32x4*)(ropel + 1024u + pos * 16u + 4u * fq);
;                         const f32x4 x1 = v[bj][0], x2 = v[bj][1]; v[bj][0] = x1 * cs - x2 * sn; v[bj][1] = x2 * cs + x1 * sn; } }
;                 const unsigned ro = offA + (unsigned)(ai * 8 + m) * 32u * pitch;
;                 u32x4 w[2];
; #pragma unroll
;                 for (int bj = 0; bj < 2; ++bj) { w[bj].x = cvtpk_h(v[bj][0][0], v[bj][0][1]); w[bj].y = cvtpk_h(v[bj][0][2], v[bj][0][3]); w[bj].z = cvtpk_h(v[bj][1][0], v[bj][1][1]); w[bj].w = cvtpk_h(v[bj][1][2], v[bj][1][3]); }
;                 stg_line_pair(wst, ro, 2u * pitch, w[0], w[1], odd);
;                 asm volatile("" ::: "memory"); }
.LBB0_587:
	v_cvt_pk_f16_f32 v152, v152, v153
	v_cvt_pk_f16_f32 v153, v154, v155
	v_cvt_pk_f16_f32 v154, v188, v189
	v_cvt_pk_f16_f32 v149, v148, v149
	v_mov_b32_e32 v148, v1
	v_mov_b32_e32 v188, v1
	v_cvt_pk_f16_f32 v150, v150, v151
	v_mov_b32_dpp v148, v149 quad_perm:[1,0,3,2] row_mask:0xf bank_mask:0xf
	v_mov_b32_dpp v188, v152 quad_perm:[1,0,3,2] row_mask:0xf bank_mask:0xf
	v_cndmask_b32_e64 v148, v148, v152, s[2:3]
	v_cndmask_b32_e64 v152, v149, v188, s[2:3]
	v_mov_b32_e32 v149, v1
	v_mov_b32_e32 v188, v1
	v_cvt_pk_f16_f32 v151, v192, v193
	v_mov_b32_dpp v149, v150 quad_perm:[1,0,3,2] row_mask:0xf bank_mask:0xf
	v_mov_b32_dpp v188, v153 quad_perm:[1,0,3,2] row_mask:0xf bank_mask:0xf
	v_cndmask_b32_e64 v149, v149, v153, s[2:3]
	v_cndmask_b32_e64 v153, v150, v188, s[2:3]
	v_mov_b32_e32 v150, v1
	v_mov_b32_e32 v188, v1
	v_cvt_pk_f16_f32 v155, v186, v187
	v_mov_b32_dpp v150, v151 quad_perm:[1,0,3,2] row_mask:0xf bank_mask:0xf
	v_mov_b32_dpp v188, v154 quad_perm:[1,0,3,2] row_mask:0xf bank_mask:0xf
	v_cvt_pk_f16_f32 v186, v190, v191
	v_cndmask_b32_e64 v150, v150, v154, s[2:3]
	v_cndmask_b32_e64 v154, v151, v188, s[2:3]
	v_mov_b32_e32 v151, v1
	s_lshl_b32 s38, 0x120, s42
	v_mov_b32_e32 v188, v1
	v_mov_b32_dpp v151, v186 quad_perm:[1,0,3,2] row_mask:0xf bank_mask:0xf
	v_add_u32_e32 v187, s38, v206
	v_mov_b32_dpp v188, v155 quad_perm:[1,0,3,2] row_mask:0xf bank_mask:0xf
	v_cndmask_b32_e64 v151, v151, v155, s[2:3]
	v_cndmask_b32_e64 v155, v186, v188, s[2:3]
	s_mov_b32 s100, 2
	global_store_dwordx4 v187, v[148:151], s[36:37]
	v_pk_fma_f32 v[188:189], v[10:11], v[170:171], v[132:133] op_sel_hi:[1,0,1]
	v_pk_fma_f32 v[190:191], v[80:81], v[170:171], v[142:143] op_sel_hi:[1,0,1]
	v_add_u32_e32 v148, s9, v187
	s_mov_b32 s100, 2
	global_store_dwordx4 v148, v[152:155], s[36:37]
	v_pk_fma_f32 v[148:149], v[16:17], v[170:171], v[138:139] op_sel_hi:[1,0,1]
	v_pk_fma_f32 v[150:151], v[14:15], v[170:171], v[136:137] op_sel_hi:[1,0,1]
	v_mul_f32_e32 v153, v149, v149
	v_mul_f32_e32 v152, v151, v151
	v_fmac_f32_e32 v152, v150, v150
	v_fmac_f32_e32 v153, v148, v148
	v_pk_fma_f32 v[186:187], v[12:13], v[170:171], v[134:135] op_sel_hi:[1,0,1]
	v_add_f32_e32 v152, v152, v153
	v_mul_f32_e32 v153, v189, v189
	v_mul_f32_e32 v154, v187, v187
	v_fmac_f32_e32 v153, v188, v188
	v_fmac_f32_e32 v154, v186, v186
	v_add_f32_e32 v153, v153, v154
	v_pk_fma_f32 v[192:193], v[78:79], v[170:171], v[140:141] op_sel_hi:[1,0,1]
	v_add_f32_e32 v152, v152, v153
	v_mul_f32_e32 v153, v193, v193
	v_mul_f32_e32 v154, v191, v191
	v_fmac_f32_e32 v153, v192, v192
	v_fmac_f32_e32 v154, v190, v190
	v_add_f32_e32 v153, v153, v154
	v_pk_fma_f32 v[214:215], v[76:77], v[170:171], v[146:147] op_sel_hi:[1,0,1]
	v_pk_fma_f32 v[216:217], v[74:75], v[170:171], v[144:145] op_sel_hi:[1,0,1]
	v_add_f32_e32 v152, v153, v152
	v_mul_f32_e32 v153, v217, v217
	v_mul_f32_e32 v154, v215, v215
	v_fmac_f32_e32 v153, v216, v216
	v_fmac_f32_e32 v154, v214, v214
	v_add_f32_e32 v153, v153, v154
	v_add_f32_e32 v152, v153, v152
	v_mov_b32_e32 v153, v152
	s_nop 1
	v_permlane16_swap_b32_e32 v152, v153
	v_add_f32_e32 v152, v152, v153
	v_mov_b32_e32 v153, v152
	s_nop 1
	v_permlane32_swap_b32_e32 v152, v153
	v_add_f32_e32 v152, v152, v153
	v_fmamk_f32 v152, v152, 0x3c800000, v229
	v_rsq_f32_e32 v218, v152
	s_and_b64 vcc, exec, s[4:5]
	v_pk_mul_f32 v[150:151], v[150:151], v[218:219] op_sel_hi:[1,0]
	v_pk_mul_f32 v[148:149], v[148:149], v[218:219] op_sel_hi:[1,0]
	v_pk_mul_f32 v[152:153], v[184:185], v[150:151]
	v_pk_mul_f32 v[154:155], v[182:183], v[148:149]
	v_pk_mul_f32 v[148:149], v[188:189], v[218:219] op_sel_hi:[1,0]
	v_pk_mul_f32 v[150:151], v[186:187], v[218:219] op_sel_hi:[1,0]
	v_pk_mul_f32 v[188:189], v[180:181], v[148:149]
	v_pk_mul_f32 v[186:187], v[178:179], v[150:151]
	v_pk_mul_f32 v[148:149], v[192:193], v[218:219] op_sel_hi:[1,0]
	v_pk_mul_f32 v[150:151], v[190:191], v[218:219] op_sel_hi:[1,0]
	v_pk_mul_f32 v[192:193], v[216:217], v[218:219] op_sel_hi:[1,0]
	v_pk_mul_f32 v[190:191], v[214:215], v[218:219] op_sel_hi:[1,0]
	v_pk_mul_f32 v[150:151], v[160:161], v[150:151]
	v_pk_mul_f32 v[148:149], v[162:163], v[148:149]
	v_pk_mul_f32 v[190:191], v[156:157], v[190:191]
	v_pk_mul_f32 v[192:193], v[158:159], v[192:193]
	s_cbranch_vccnz .LBB0_589
	v_add_u32_e32 v207, 0xa0, v201
	v_and_b32_e32 v207, 0x7c0, v207
	v_add_u32_e32 v210, v205, v207
	v_add_u32_e32 v207, v204, v207
	ds_read_b128 v[214:217], v210
	ds_read_b128 v[218:221], v207
	s_waitcnt lgkmcnt(0)
	v_pk_mul_f32 v[222:223], v[186:187], v[220:221]
	v_pk_mul_f32 v[226:227], v[188:189], v[218:219]
	v_pk_fma_f32 v[224:225], v[154:155], v[216:217], v[222:223] neg_lo:[0,0,1] neg_hi:[0,0,1]
	v_pk_fma_f32 v[222:223], v[152:153], v[214:215], v[226:227] neg_lo:[0,0,1] neg_hi:[0,0,1]
	v_pk_mul_f32 v[152:153], v[152:153], v[218:219]
	v_pk_mul_f32 v[154:155], v[154:155], v[220:221]
	v_pk_fma_f32 v[188:189], v[188:189], v[214:215], v[152:153]
	v_add_u32_e32 v152, v205, v195
	v_add_u32_e32 v195, v204, v195
	v_pk_fma_f32 v[186:187], v[186:187], v[216:217], v[154:155]
	ds_read_b128 v[152:155], v152
	ds_read_b128 v[214:217], v195
	s_waitcnt lgkmcnt(0)
	v_pk_mul_f32 v[218:219], v[190:191], v[216:217]
	v_pk_mul_f32 v[226:227], v[192:193], v[214:215]
	v_pk_fma_f32 v[220:221], v[150:151], v[154:155], v[218:219] neg_lo:[0,0,1] neg_hi:[0,0,1]
	v_pk_fma_f32 v[218:219], v[148:149], v[152:153], v[226:227] neg_lo:[0,0,1] neg_hi:[0,0,1]
	v_pk_mul_f32 v[150:151], v[150:151], v[216:217]
	v_pk_mul_f32 v[148:149], v[148:149], v[214:215]
	v_pk_fma_f32 v[190:191], v[190:191], v[154:155], v[150:151]
	v_pk_fma_f32 v[192:193], v[192:193], v[152:153], v[148:149]
	v_mov_b64_e32 v[148:149], v[218:219]
	v_mov_b64_e32 v[152:153], v[222:223]
	v_mov_b64_e32 v[150:151], v[220:221]
	v_mov_b64_e32 v[154:155], v[224:225]
; #define LAS __attribute__((address_space(3)))
; __device__ __forceinline__ void stg_line_pair(void* base, unsigned roA, unsigned rowb, const u32x4 w0, const u32x4 w1, bool odd) {
;     u32x4 a, b;
; #pragma unroll
;     for (int c = 0; c < 4; ++c) { const unsigned p1 = (unsigned)__builtin_amdgcn_update_dpp(0, (int)w1[c], 0xB1, 0xF, 0xF, false), p0 = (unsigned)__builtin_amdgcn_update_dpp(0, (int)w0[c], 0xB1, 0xF, 0xF, false);
;         a[c] = odd ? p1 : w0[c]; b[c] = odd ? w1[c] : p0; }
;     stg_u4(base, roA, a); stg_u4(base, roA + rowb, b);
; }
;     __device__ __forceinline__ void operator()(const f32x4 (&acc)[2][2][4][2], const pg8::Unit& u, int wr, int wc, int fr, int fq) const {
;     ...
;         for (int ai = 0; ai < 2; ++ai)
; #pragma unroll
;             for (int m = 0; m < 4; ++m) { const float r = rs[ai][m]; f32x4 v[2][2]; float ss = 0.f;
; #pragma unroll
;                 for (int bj = 0; bj < 2; ++bj)
; #pragma unroll
;                     for (int n = 0; n < 2; ++n) { v[bj][n] = acc[ai][bj][m][n] * r + bv[bj][n]; ss += (v[bj][n][0] * v[bj][n][0] + v[bj][n][1] * v[bj][n][1]) + (v[bj][n][2] * v[bj][n][2] + v[bj][n][3] * v[bj][n][3]); }
;                 const float rn = __builtin_amdgcn_rsqf(red4(ss, fq * 16 + fr) * (1.f / 64.f) + EPS);
; #pragma unroll
;                 for (int bj = 0; bj < 2; ++bj)
; #pragma unroll
;                     for (int n = 0; n < 2; ++n) v[bj][n] = v[bj][n] * rn * g4[bj][n];
;                 if (lat) { const unsigned t = (rbase + ai * 128 + m * 16) & (SEQ - 1);
; #pragma unroll
;                     for (int bj = 0; bj < 2; ++bj) { const unsigned pos = bj ? (t & 63u) : (t >> 6); const f32x4 cs = *(const LAS f32x4*)(ropel + pos * 16u + 4u * fq), sn = *(const LAS f32x4*)(ropel + 1024u + pos * 16u + 4u * fq);
;                         const f32x4 x1 = v[bj][0], x2 = v[bj][1]; v[bj][0] = x1 * cs - x2 * sn; v[bj][1] = x2 * cs + x1 * sn; } }
;                 const unsigned ro = offA + (unsigned)(ai * 8 + m) * 32u * pitch;
;                 u32x4 w[2];
; #pragma unroll
;                 for (int bj = 0; bj < 2; ++bj) { w[bj].x = cvtpk_h(v[bj][0][0], v[bj][0][1]); w[bj].y = cvtpk_h(v[bj][0][2], v[bj][0][3]); w[bj].z = cvtpk_h(v[bj][1][0], v[bj][1][1]); w[bj].w = cvtpk_h(v[bj][1][2], v[bj][1][3]); }
;                 stg_line_pair(wst, ro, 2u * pitch, w[0], w[1], odd);
;                 asm volatile("" ::: "memory"); }
.LBB0_589:
	v_cvt_pk_f16_f32 v152, v152, v153
	v_cvt_pk_f16_f32 v153, v154, v155
	v_cvt_pk_f16_f32 v154, v188, v189
	v_cvt_pk_f16_f32 v149, v148, v149
	v_mov_b32_e32 v148, v1
	v_mov_b32_e32 v188, v1
	v_cvt_pk_f16_f32 v150, v150, v151
	v_mov_b32_dpp v148, v149 quad_perm:[1,0,3,2] row_mask:0xf bank_mask:0xf
	v_mov_b32_dpp v188, v152 quad_perm:[1,0,3,2] row_mask:0xf bank_mask:0xf
	v_cndmask_b32_e64 v148, v148, v152, s[2:3]
	v_cndmask_b32_e64 v152, v149, v188, s[2:3]
	v_mov_b32_e32 v149, v1
	v_mov_b32_e32 v188, v1
	v_cvt_pk_f16_f32 v151, v192, v193
	v_mov_b32_dpp v149, v150 quad_perm:[1,0,3,2] row_mask:0xf bank_mask:0xf
	v_mov_b32_dpp v188, v153 quad_perm:[1,0,3,2] row_mask:0xf bank_mask:0xf
	v_cndmask_b32_e64 v149, v149, v153, s[2:3]
	v_cndmask_b32_e64 v153, v150, v188, s[2:3]
	v_mov_b32_e32 v150, v1
	v_mov_b32_e32 v188, v1
	v_cvt_pk_f16_f32 v155, v186, v187
	v_mov_b32_dpp v150, v151 quad_perm:[1,0,3,2] row_mask:0xf bank_mask:0xf
	v_mov_b32_dpp v188, v154 quad_perm:[1,0,3,2] row_mask:0xf bank_mask:0xf
	v_cvt_pk_f16_f32 v186, v190, v191
	v_cndmask_b32_e64 v150, v150, v154, s[2:3]
	v_cndmask_b32_e64 v154, v151, v188, s[2:3]
	v_mov_b32_e32 v151, v1
	s_lshl_b32 s38, 0x140, s42
	v_mov_b32_e32 v188, v1
	v_mov_b32_dpp v151, v186 quad_perm:[1,0,3,2] row_mask:0xf bank_mask:0xf
	v_add_u32_e32 v187, s38, v206
	v_mov_b32_dpp v188, v155 quad_perm:[1,0,3,2] row_mask:0xf bank_mask:0xf
	v_cndmask_b32_e64 v151, v151, v155, s[2:3]
	v_cndmask_b32_e64 v155, v186, v188, s[2:3]
	s_mov_b32 s100, 2
	global_store_dwordx4 v187, v[148:151], s[36:37]
	s_and_b64 vcc, exec, s[4:5]
	s_nop 0
	v_add_u32_e32 v148, s9, v187
	s_mov_b32 s100, 2
	global_store_dwordx4 v148, v[152:155], s[36:37]
	v_mov_b32_e32 v148, v171
	v_pk_fma_f32 v[150:151], v[8:9], v[148:149], v[138:139] op_sel_hi:[1,0,1]
	v_pk_fma_f32 v[152:153], v[6:7], v[148:149], v[136:137] op_sel_hi:[1,0,1]
	v_mul_f32_e32 v154, v151, v151
	v_mul_f32_e32 v149, v153, v153
	v_fmac_f32_e32 v149, v152, v152
	v_fmac_f32_e32 v154, v150, v150
	v_add_f32_e32 v149, v149, v154
	v_pk_fma_f32 v[186:187], v[4:5], v[148:149], v[134:135] op_sel_hi:[1,0,1]
	v_pk_fma_f32 v[188:189], v[2:3], v[148:149], v[132:133] op_sel_hi:[1,0,1]
	v_mul_f32_e32 v155, v187, v187
	v_mul_f32_e32 v154, v189, v189
	v_fmac_f32_e32 v154, v188, v188
	v_fmac_f32_e32 v155, v186, v186
	v_add_f32_e32 v154, v154, v155
	v_add_f32_e32 v149, v149, v154
	v_pk_fma_f32 v[190:191], v[64:65], v[148:149], v[142:143] op_sel_hi:[1,0,1]
	v_pk_fma_f32 v[192:193], v[62:63], v[148:149], v[140:141] op_sel_hi:[1,0,1]
	v_mul_f32_e32 v155, v191, v191
	v_mul_f32_e32 v154, v193, v193
	v_fmac_f32_e32 v154, v192, v192
	v_fmac_f32_e32 v155, v190, v190
	v_add_f32_e32 v154, v154, v155
	v_add_f32_e32 v149, v154, v149
	v_pk_fma_f32 v[214:215], v[60:61], v[148:149], v[146:147] op_sel_hi:[1,0,1]
	v_pk_fma_f32 v[216:217], v[58:59], v[148:149], v[144:145] op_sel_hi:[1,0,1]
	v_mul_f32_e32 v154, v215, v215
	v_mul_f32_e32 v148, v217, v217
	v_fmac_f32_e32 v148, v216, v216
	v_fmac_f32_e32 v154, v214, v214
	v_add_f32_e32 v148, v148, v154
	v_add_f32_e32 v148, v148, v149
	v_mov_b32_e32 v149, v148
	s_nop 1
	v_permlane16_swap_b32_e32 v148, v149
	v_add_f32_e32 v148, v148, v149
	v_mov_b32_e32 v149, v148
	s_nop 1
	v_permlane32_swap_b32_e32 v148, v149
	v_add_f32_e32 v148, v148, v149
	v_fmamk_f32 v148, v148, 0x3c800000, v229
	v_rsq_f32_e32 v218, v148
	s_nop 0
	v_pk_mul_f32 v[148:149], v[152:153], v[218:219] op_sel_hi:[1,0]
	v_pk_mul_f32 v[150:151], v[150:151], v[218:219] op_sel_hi:[1,0]
	v_pk_mul_f32 v[152:153], v[184:185], v[148:149]
	v_pk_mul_f32 v[154:155], v[182:183], v[150:151]
	v_pk_mul_f32 v[148:149], v[188:189], v[218:219] op_sel_hi:[1,0]
	v_pk_mul_f32 v[150:151], v[186:187], v[218:219] op_sel_hi:[1,0]
	v_pk_mul_f32 v[180:181], v[180:181], v[148:149]
	v_pk_mul_f32 v[178:179], v[178:179], v[150:151]
	v_pk_mul_f32 v[148:149], v[192:193], v[218:219] op_sel_hi:[1,0]
	v_pk_mul_f32 v[150:151], v[190:191], v[218:219] op_sel_hi:[1,0]
	v_pk_mul_f32 v[148:149], v[162:163], v[148:149]
	v_pk_mul_f32 v[150:151], v[160:161], v[150:151]
	v_pk_mul_f32 v[160:161], v[216:217], v[218:219] op_sel_hi:[1,0]
	v_pk_mul_f32 v[162:163], v[214:215], v[218:219] op_sel_hi:[1,0]
	v_pk_mul_f32 v[158:159], v[158:159], v[160:161]
	v_pk_mul_f32 v[156:157], v[156:157], v[162:163]
	s_cbranch_vccnz .LBB0_591
	v_add_u32_e32 v160, 0xb0, v201
	v_and_b32_e32 v182, 0x7c0, v160
	v_add_u32_e32 v160, v205, v182
	v_add_u32_e32 v182, v204, v182
	ds_read_b128 v[160:163], v160
	ds_read_b128 v[182:185], v182
	s_waitcnt lgkmcnt(0)
	v_pk_mul_f32 v[186:187], v[178:179], v[184:185]
	v_pk_mul_f32 v[190:191], v[180:181], v[182:183]
	v_pk_fma_f32 v[188:189], v[154:155], v[162:163], v[186:187] neg_lo:[0,0,1] neg_hi:[0,0,1]
	v_pk_fma_f32 v[186:187], v[152:153], v[160:161], v[190:191] neg_lo:[0,0,1] neg_hi:[0,0,1]
	v_pk_mul_f32 v[152:153], v[152:153], v[182:183]
	v_pk_mul_f32 v[154:155], v[154:155], v[184:185]
	v_pk_fma_f32 v[180:181], v[180:181], v[160:161], v[152:153]
	v_add_u32_e32 v152, v205, v194
	v_add_u32_e32 v160, v204, v194
	v_pk_fma_f32 v[178:179], v[178:179], v[162:163], v[154:155]
	ds_read_b128 v[152:155], v152
	ds_read_b128 v[160:163], v160
	s_waitcnt lgkmcnt(0)
	v_pk_mul_f32 v[182:183], v[156:157], v[162:163]
	v_pk_mul_f32 v[190:191], v[158:159], v[160:161]
	v_pk_fma_f32 v[184:185], v[150:151], v[154:155], v[182:183] neg_lo:[0,0,1] neg_hi:[0,0,1]
	v_pk_fma_f32 v[182:183], v[148:149], v[152:153], v[190:191] neg_lo:[0,0,1] neg_hi:[0,0,1]
	v_pk_mul_f32 v[150:151], v[150:151], v[162:163]
	v_pk_mul_f32 v[148:149], v[148:149], v[160:161]
	v_pk_fma_f32 v[156:157], v[156:157], v[154:155], v[150:151]
	v_pk_fma_f32 v[158:159], v[158:159], v[152:153], v[148:149]
	v_mov_b64_e32 v[148:149], v[182:183]
	v_mov_b64_e32 v[152:153], v[186:187]
	v_mov_b64_e32 v[150:151], v[184:185]
	v_mov_b64_e32 v[154:155], v[188:189]
; __device__ __forceinline__ unsigned cvtpk_h(float lo, float hi) { f32x2 v = {lo, hi}; h16x2 b = __builtin_convertvector(v, h16x2); return __builtin_bit_cast(unsigned, b); }
; __device__ __forceinline__ void stg_line_pair(void* base, unsigned roA, unsigned rowb, const u32x4 w0, const u32x4 w1, bool odd) {
;     u32x4 a, b;
; #pragma unroll
;     for (int c = 0; c < 4; ++c) { const unsigned p1 = (unsigned)__builtin_amdgcn_update_dpp(0, (int)w1[c], 0xB1, 0xF, 0xF, false), p0 = (unsigned)__builtin_amdgcn_update_dpp(0, (int)w0[c], 0xB1, 0xF, 0xF, false);
;         a[c] = odd ? p1 : w0[c]; b[c] = odd ? w1[c] : p0; }
;     stg_u4(base, roA, a); stg_u4(base, roA + rowb, b);
; }
;     __device__ __forceinline__ void operator()(const f32x4 (&acc)[2][2][4][2], const pg8::Unit& u, int wr, int wc, int fr, int fq) const {
;     ...
;                 for (int bj = 0; bj < 2; ++bj) { w[bj].x = cvtpk_h(v[bj][0][0], v[bj][0][1]); w[bj].y = cvtpk_h(v[bj][0][2], v[bj][0][3]); w[bj].z = cvtpk_h(v[bj][1][0], v[bj][1][1]); w[bj].w = cvtpk_h(v[bj][1][2], v[bj][1][3]); }
;                 stg_line_pair(wst, ro, 2u * pitch, w[0], w[1], odd);
;                 asm volatile("" ::: "memory"); }
.LBB0_591:
	v_cvt_pk_f16_f32 v152, v152, v153
	v_cvt_pk_f16_f32 v149, v148, v149
	v_cvt_pk_f16_f32 v150, v150, v151
	v_cvt_pk_f16_f32 v151, v158, v159
	v_mov_b32_e32 v148, v1
	v_mov_b32_e32 v158, v1
	v_cvt_pk_f16_f32 v153, v154, v155
	v_mov_b32_dpp v148, v149 quad_perm:[1,0,3,2] row_mask:0xf bank_mask:0xf
	v_mov_b32_dpp v158, v152 quad_perm:[1,0,3,2] row_mask:0xf bank_mask:0xf
	v_cndmask_b32_e64 v148, v148, v152, s[2:3]
	v_cndmask_b32_e64 v152, v149, v158, s[2:3]
	v_mov_b32_e32 v149, v1
	v_mov_b32_e32 v158, v1
	v_cvt_pk_f16_f32 v154, v180, v181
	v_mov_b32_dpp v149, v150 quad_perm:[1,0,3,2] row_mask:0xf bank_mask:0xf
	v_mov_b32_dpp v158, v153 quad_perm:[1,0,3,2] row_mask:0xf bank_mask:0xf
	v_cndmask_b32_e64 v149, v149, v153, s[2:3]
	v_cndmask_b32_e64 v153, v150, v158, s[2:3]
	v_mov_b32_e32 v150, v1
	v_mov_b32_e32 v158, v1
	v_cvt_pk_f16_f32 v156, v156, v157
	v_mov_b32_dpp v150, v151 quad_perm:[1,0,3,2] row_mask:0xf bank_mask:0xf
	v_mov_b32_dpp v158, v154 quad_perm:[1,0,3,2] row_mask:0xf bank_mask:0xf
	v_cndmask_b32_e64 v150, v150, v154, s[2:3]
	v_cndmask_b32_e64 v154, v151, v158, s[2:3]
	v_mov_b32_e32 v151, v1
	s_lshl_b32 s4, 0x160, s42
	v_cvt_pk_f16_f32 v155, v178, v179
	v_mov_b32_dpp v151, v156 quad_perm:[1,0,3,2] row_mask:0xf bank_mask:0xf
	v_mov_b32_e32 v158, v1
	v_add_u32_e32 v157, s4, v206
	v_cndmask_b32_e64 v151, v151, v155, s[2:3]
	v_mov_b32_dpp v158, v155 quad_perm:[1,0,3,2] row_mask:0xf bank_mask:0xf
	v_cndmask_b32_e64 v155, v156, v158, s[2:3]
	s_mov_b32 s100, 2
	global_store_dwordx4 v157, v[148:151], s[36:37]
	s_mov_b64 s[2:3], 0
	s_nop 0
	v_add_u32_e32 v148, s9, v157
	s_mov_b32 s100, 2
	global_store_dwordx4 v148, v[152:155], s[36:37]

; __device__ __forceinline__ unsigned cvtpk_h(float lo, float hi) { f32x2 v = {lo, hi}; h16x2 b = __builtin_convertvector(v, h16x2); return __builtin_bit_cast(unsigned, b); }
; __device__ __forceinline__ void stg_line_pair(void* base, unsigned roA, unsigned rowb, const u32x4 w0, const u32x4 w1, bool odd) {
;     u32x4 a, b;
; #pragma unroll
;     for (int c = 0; c < 4; ++c) { const unsigned p1 = (unsigned)__builtin_amdgcn_update_dpp(0, (int)w1[c], 0xB1, 0xF, 0xF, false), p0 = (unsigned)__builtin_amdgcn_update_dpp(0, (int)w0[c], 0xB1, 0xF, 0xF, false);
;         a[c] = odd ? p1 : w0[c]; b[c] = odd ? w1[c] : p0; }
;     stg_u4(base, roA, a); stg_u4(base, roA + rowb, b);
; }
;     __device__ __forceinline__ void operator()(const f32x4 (&acc)[2][2][4][2], const pg8::Unit& u, int wr, int wc, int fr, int fq) const {
;     ...
;             const bool odd = (fr & 1) != 0;
;             const unsigned offA = base + ((row0 + (unsigned)(wr * 64 + (fr & ~1))) * pitch + coff) * 2u + (odd ? 64u : 0u) + 16u * fq;
; #pragma unroll
;             for (int ai = 0; ai < 2; ++ai)
; #pragma unroll
;                 for (int m = 0; m < 4; ++m) { const unsigned ro = offA + (unsigned)(ai * 8 + m) * rowstep; const float r = rs[ai][m];
;                     u32x4 w[2];
; #pragma unroll
;                     for (int bj = 0; bj < 2; ++bj) { const f32x4 v0 = acc[ai][bj][m][0] * r + bv[bj][0], v1 = acc[ai][bj][m][1] * r + bv[bj][1];
;                         w[bj].x = cvtpk_h(v0[0], v0[1]); w[bj].y = cvtpk_h(v0[2], v0[3]); w[bj].z = cvtpk_h(v1[0], v1[1]); w[bj].w = cvtpk_h(v1[2], v1[3]); }
;                     stg_line_pair(wst, ro, 2u * pitch, w[0], w[1], odd);
;                     asm volatile("" ::: "memory"); }
.LBB0_632:
	v_and_b32_e32 v178, 0x7ffffffe, v202
	s_add_i32 s2, s42, s77
	v_add_u32_e32 v178, s2, v178
	v_and_b32_e32 v186, 1, v202
	v_mul_lo_u32 v178, s9, v178
	v_add_lshl_u32 v178, v178, s38, 1
	v_lshl_add_u32 v179, v186, 6, v203
	v_pk_fma_f32 v[180:181], v[70:71], v[162:163], v[148:149] op_sel_hi:[1,0,1]
	s_waitcnt vmcnt(1)
	v_pk_fma_f32 v[128:129], v[128:129], v[162:163], v[142:143] op_sel_hi:[1,0,1]
	v_pk_fma_f32 v[126:127], v[126:127], v[162:163], v[140:141] op_sel_hi:[1,0,1]
	s_waitcnt vmcnt(0)
	v_pk_fma_f32 v[122:123], v[122:123], v[162:163], v[144:145] op_sel_hi:[1,0,1]
	v_add3_u32 v187, v179, s39, v178
	v_pk_fma_f32 v[178:179], v[72:73], v[162:163], v[150:151] op_sel_hi:[1,0,1]
	v_cvt_pk_f16_f32 v180, v180, v181
	v_pk_fma_f32 v[124:125], v[124:125], v[162:163], v[146:147] op_sel_hi:[1,0,1]
	v_cvt_pk_f16_f32 v126, v126, v127
	v_cvt_pk_f16_f32 v127, v128, v129
	v_cvt_pk_f16_f32 v128, v122, v123
	v_mov_b32_e32 v123, v1
	v_pk_fma_f32 v[184:185], v[66:67], v[162:163], v[152:153] op_sel_hi:[1,0,1]
	v_cvt_pk_f16_f32 v178, v178, v179
	v_cvt_pk_f16_f32 v129, v124, v125
	v_mov_b32_e32 v122, v1
	v_mov_b32_dpp v123, v180 quad_perm:[1,0,3,2] row_mask:0xf bank_mask:0xf
	v_cmp_eq_u32_e32 vcc, 0, v186
	v_mov_b32_e32 v124, v1
	v_cvt_pk_f16_f32 v179, v184, v185
	v_mov_b32_dpp v122, v126 quad_perm:[1,0,3,2] row_mask:0xf bank_mask:0xf
	v_cndmask_b32_e32 v126, v126, v123, vcc
	v_mov_b32_e32 v123, v1
	v_mov_b32_dpp v124, v178 quad_perm:[1,0,3,2] row_mask:0xf bank_mask:0xf
	v_mov_b32_e32 v125, v1
	v_mov_b32_dpp v123, v127 quad_perm:[1,0,3,2] row_mask:0xf bank_mask:0xf
	v_cndmask_b32_e32 v127, v127, v124, vcc
	v_mov_b32_e32 v124, v1
	v_mov_b32_dpp v125, v179 quad_perm:[1,0,3,2] row_mask:0xf bank_mask:0xf
	v_pk_fma_f32 v[182:183], v[68:69], v[162:163], v[154:155] op_sel_hi:[1,0,1]
	v_mov_b32_dpp v124, v128 quad_perm:[1,0,3,2] row_mask:0xf bank_mask:0xf
	v_cndmask_b32_e32 v128, v128, v125, vcc
	v_mov_b32_e32 v125, v1
	v_cvt_pk_f16_f32 v181, v182, v183
	v_cndmask_b32_e32 v123, v123, v178, vcc
	v_mov_b32_dpp v125, v129 quad_perm:[1,0,3,2] row_mask:0xf bank_mask:0xf
	v_mov_b32_e32 v178, v1
	s_lshl_b32 s2, s9, 1
	v_cndmask_b32_e32 v122, v122, v180, vcc
	v_cndmask_b32_e32 v124, v124, v179, vcc
	v_mov_b32_dpp v178, v181 quad_perm:[1,0,3,2] row_mask:0xf bank_mask:0xf
	v_cndmask_b32_e32 v125, v125, v181, vcc
	v_cndmask_b32_e32 v129, v129, v178, vcc
	s_mov_b32 s100, 2
	global_store_dwordx4 v187, v[122:125], s[36:37]
	v_pk_fma_f32 v[120:121], v[120:121], v[162:163], v[142:143] op_sel:[0,1,0]
	v_pk_fma_f32 v[118:119], v[118:119], v[162:163], v[140:141] op_sel:[0,1,0]
	v_add_u32_e32 v122, s2, v187
	s_mov_b32 s100, 2
	global_store_dwordx4 v122, v[126:129], s[36:37]
	v_pk_fma_f32 v[114:115], v[114:115], v[162:163], v[144:145] op_sel:[0,1,0]
	v_pk_fma_f32 v[124:125], v[52:53], v[162:163], v[150:151] op_sel:[0,1,0]
	v_pk_fma_f32 v[126:127], v[50:51], v[162:163], v[148:149] op_sel:[0,1,0]
	v_pk_fma_f32 v[116:117], v[116:117], v[162:163], v[146:147] op_sel:[0,1,0]
	v_cvt_pk_f16_f32 v126, v126, v127
	v_cvt_pk_f16_f32 v118, v118, v119
	v_cvt_pk_f16_f32 v119, v120, v121
	v_cvt_pk_f16_f32 v120, v114, v115
	v_mov_b32_e32 v115, v1
	v_pk_fma_f32 v[178:179], v[46:47], v[162:163], v[152:153] op_sel:[0,1,0]
	v_cvt_pk_f16_f32 v124, v124, v125
	v_cvt_pk_f16_f32 v121, v116, v117
	v_mov_b32_e32 v114, v1
	v_mov_b32_dpp v115, v126 quad_perm:[1,0,3,2] row_mask:0xf bank_mask:0xf
	v_mov_b32_e32 v116, v1
	v_cvt_pk_f16_f32 v125, v178, v179
	v_mov_b32_dpp v114, v118 quad_perm:[1,0,3,2] row_mask:0xf bank_mask:0xf
	v_cndmask_b32_e32 v118, v118, v115, vcc
	v_mov_b32_e32 v115, v1
	v_mov_b32_dpp v116, v124 quad_perm:[1,0,3,2] row_mask:0xf bank_mask:0xf
	v_mov_b32_e32 v117, v1
	v_mov_b32_dpp v115, v119 quad_perm:[1,0,3,2] row_mask:0xf bank_mask:0xf
	v_cndmask_b32_e32 v119, v119, v116, vcc
	v_mov_b32_e32 v116, v1
	v_mov_b32_dpp v117, v125 quad_perm:[1,0,3,2] row_mask:0xf bank_mask:0xf
	v_pk_fma_f32 v[128:129], v[48:49], v[162:163], v[154:155] op_sel:[0,1,0]
	v_mad_u64_u32 v[122:123], s[4:5], s9, 30, v[122:123]
	v_mov_b32_dpp v116, v120 quad_perm:[1,0,3,2] row_mask:0xf bank_mask:0xf
	v_cndmask_b32_e32 v120, v120, v117, vcc
	v_mov_b32_e32 v117, v1
	v_cvt_pk_f16_f32 v127, v128, v129
	v_mov_b32_e32 v123, v1
	v_mov_b32_dpp v117, v121 quad_perm:[1,0,3,2] row_mask:0xf bank_mask:0xf
	v_cndmask_b32_e32 v114, v114, v126, vcc
	v_cndmask_b32_e32 v115, v115, v124, vcc
	v_cndmask_b32_e32 v116, v116, v125, vcc
	v_mov_b32_dpp v123, v127 quad_perm:[1,0,3,2] row_mask:0xf bank_mask:0xf
	v_cndmask_b32_e32 v117, v117, v127, vcc
	v_cndmask_b32_e32 v121, v121, v123, vcc
	s_mov_b32 s100, 2
	global_store_dwordx4 v122, v[114:117], s[36:37]
	v_pk_fma_f32 v[112:113], v[112:113], v[160:161], v[142:143] op_sel_hi:[1,0,1]
	v_pk_fma_f32 v[110:111], v[110:111], v[160:161], v[140:141] op_sel_hi:[1,0,1]
	v_add_u32_e32 v114, s2, v122
	v_pk_fma_f32 v[116:117], v[54:55], v[160:161], v[148:149] op_sel_hi:[1,0,1]
	v_pk_fma_f32 v[106:107], v[106:107], v[160:161], v[144:145] op_sel_hi:[1,0,1]
	s_mov_b32 s100, 2
	global_store_dwordx4 v114, v[118:121], s[36:37]
	v_pk_fma_f32 v[114:115], v[56:57], v[160:161], v[150:151] op_sel_hi:[1,0,1]
	v_cvt_pk_f16_f32 v116, v116, v117
	v_pk_fma_f32 v[108:109], v[108:109], v[160:161], v[146:147] op_sel_hi:[1,0,1]
	v_cvt_pk_f16_f32 v110, v110, v111
	v_cvt_pk_f16_f32 v111, v112, v113
	v_cvt_pk_f16_f32 v112, v106, v107
	v_mov_b32_e32 v107, v1
	v_pk_fma_f32 v[120:121], v[42:43], v[160:161], v[152:153] op_sel_hi:[1,0,1]
	v_cvt_pk_f16_f32 v114, v114, v115
	v_cvt_pk_f16_f32 v113, v108, v109
	v_mov_b32_e32 v106, v1
	v_mov_b32_dpp v107, v116 quad_perm:[1,0,3,2] row_mask:0xf bank_mask:0xf
	v_mov_b32_e32 v108, v1
; __device__ __forceinline__ unsigned cvtpk_h(float lo, float hi) { f32x2 v = {lo, hi}; h16x2 b = __builtin_convertvector(v, h16x2); return __builtin_bit_cast(unsigned, b); }
; __device__ __forceinline__ void stg_line_pair(void* base, unsigned roA, unsigned rowb, const u32x4 w0, const u32x4 w1, bool odd) {
;     u32x4 a, b;
; #pragma unroll
;     for (int c = 0; c < 4; ++c) { const unsigned p1 = (unsigned)__builtin_amdgcn_update_dpp(0, (int)w1[c], 0xB1, 0xF, 0xF, false), p0 = (unsigned)__builtin_amdgcn_update_dpp(0, (int)w0[c], 0xB1, 0xF, 0xF, false);
;         a[c] = odd ? p1 : w0[c]; b[c] = odd ? w1[c] : p0; }
;     stg_u4(base, roA, a); stg_u4(base, roA + rowb, b);
;     __device__ __forceinline__ void operator()(const f32x4 (&acc)[2][2][4][2], const pg8::Unit& u, int wr, int wc, int fr, int fq) const {
;     ...
;             const bool odd = (fr & 1) != 0;
;             const unsigned offA = base + ((row0 + (unsigned)(wr * 64 + (fr & ~1))) * pitch + coff) * 2u + (odd ? 64u : 0u) + 16u * fq;
; #pragma unroll
;             for (int ai = 0; ai < 2; ++ai)
; #pragma unroll
;                 for (int m = 0; m < 4; ++m) { const unsigned ro = offA + (unsigned)(ai * 8 + m) * rowstep; const float r = rs[ai][m];
;                     u32x4 w[2];
; #pragma unroll
;                     for (int bj = 0; bj < 2; ++bj) { const f32x4 v0 = acc[ai][bj][m][0] * r + bv[bj][0], v1 = acc[ai][bj][m][1] * r + bv[bj][1];
;                         w[bj].x = cvtpk_h(v0[0], v0[1]); w[bj].y = cvtpk_h(v0[2], v0[3]); w[bj].z = cvtpk_h(v1[0], v1[1]); w[bj].w = cvtpk_h(v1[2], v1[3]); }
;                     stg_line_pair(wst, ro, 2u * pitch, w[0], w[1], odd);
;                     asm volatile("" ::: "memory"); }
	v_cvt_pk_f16_f32 v115, v120, v121
	v_mov_b32_dpp v106, v110 quad_perm:[1,0,3,2] row_mask:0xf bank_mask:0xf
	v_cndmask_b32_e32 v110, v110, v107, vcc
	v_mov_b32_e32 v107, v1
	v_mov_b32_dpp v108, v114 quad_perm:[1,0,3,2] row_mask:0xf bank_mask:0xf
	v_mov_b32_e32 v109, v1
	v_mov_b32_dpp v107, v111 quad_perm:[1,0,3,2] row_mask:0xf bank_mask:0xf
	v_cndmask_b32_e32 v111, v111, v108, vcc
	v_mov_b32_e32 v108, v1
	v_mov_b32_dpp v109, v115 quad_perm:[1,0,3,2] row_mask:0xf bank_mask:0xf
	v_pk_fma_f32 v[118:119], v[44:45], v[160:161], v[154:155] op_sel_hi:[1,0,1]
	v_mov_b32_dpp v108, v112 quad_perm:[1,0,3,2] row_mask:0xf bank_mask:0xf
	v_cndmask_b32_e32 v112, v112, v109, vcc
	v_mov_b32_e32 v109, v1
	v_cvt_pk_f16_f32 v117, v118, v119
	s_lshl_b32 s3, s9, 5
	v_cndmask_b32_e32 v107, v107, v114, vcc
	v_mov_b32_dpp v109, v113 quad_perm:[1,0,3,2] row_mask:0xf bank_mask:0xf
	v_mov_b32_e32 v114, v1
	v_add_u32_e32 v118, s3, v122
	v_cndmask_b32_e32 v106, v106, v116, vcc
	v_cndmask_b32_e32 v108, v108, v115, vcc
	v_mov_b32_dpp v114, v117 quad_perm:[1,0,3,2] row_mask:0xf bank_mask:0xf
	v_cndmask_b32_e32 v109, v109, v117, vcc
	v_cndmask_b32_e32 v113, v113, v114, vcc
	s_mov_b32 s100, 2
	global_store_dwordx4 v118, v[106:109], s[36:37]
	v_pk_fma_f32 v[104:105], v[104:105], v[160:161], v[142:143] op_sel:[0,1,0]
	v_pk_fma_f32 v[102:103], v[102:103], v[160:161], v[140:141] op_sel:[0,1,0]
	v_add_u32_e32 v106, s2, v118
	v_pk_fma_f32 v[108:109], v[38:39], v[160:161], v[148:149] op_sel:[0,1,0]
	v_pk_fma_f32 v[98:99], v[98:99], v[160:161], v[144:145] op_sel:[0,1,0]
	s_mov_b32 s100, 2
	global_store_dwordx4 v106, v[110:113], s[36:37]
	v_pk_fma_f32 v[106:107], v[40:41], v[160:161], v[150:151] op_sel:[0,1,0]
	v_cvt_pk_f16_f32 v108, v108, v109
	v_pk_fma_f32 v[100:101], v[100:101], v[160:161], v[146:147] op_sel:[0,1,0]
	v_cvt_pk_f16_f32 v102, v102, v103
	v_cvt_pk_f16_f32 v103, v104, v105
	v_cvt_pk_f16_f32 v104, v98, v99
	v_mov_b32_e32 v99, v1
	v_pk_fma_f32 v[112:113], v[34:35], v[160:161], v[152:153] op_sel:[0,1,0]
	v_cvt_pk_f16_f32 v106, v106, v107
	v_cvt_pk_f16_f32 v105, v100, v101
	v_mov_b32_e32 v98, v1
	v_mov_b32_dpp v99, v108 quad_perm:[1,0,3,2] row_mask:0xf bank_mask:0xf
	v_mov_b32_e32 v100, v1
	v_cvt_pk_f16_f32 v107, v112, v113
	v_mov_b32_dpp v98, v102 quad_perm:[1,0,3,2] row_mask:0xf bank_mask:0xf
	v_cndmask_b32_e32 v102, v102, v99, vcc
	v_mov_b32_e32 v99, v1
	v_mov_b32_dpp v100, v106 quad_perm:[1,0,3,2] row_mask:0xf bank_mask:0xf
	v_mov_b32_e32 v101, v1
	v_mov_b32_dpp v99, v103 quad_perm:[1,0,3,2] row_mask:0xf bank_mask:0xf
	v_cndmask_b32_e32 v103, v103, v100, vcc
	v_mov_b32_e32 v100, v1
	v_mov_b32_dpp v101, v107 quad_perm:[1,0,3,2] row_mask:0xf bank_mask:0xf
	v_pk_fma_f32 v[110:111], v[36:37], v[160:161], v[154:155] op_sel:[0,1,0]
	v_mov_b32_dpp v100, v104 quad_perm:[1,0,3,2] row_mask:0xf bank_mask:0xf
	v_cndmask_b32_e32 v104, v104, v101, vcc
	v_mov_b32_e32 v101, v1
	v_cvt_pk_f16_f32 v109, v110, v111
	v_cndmask_b32_e32 v99, v99, v106, vcc
	v_mov_b32_dpp v101, v105 quad_perm:[1,0,3,2] row_mask:0xf bank_mask:0xf
	v_mov_b32_e32 v106, v1
	v_add_u32_e32 v110, s3, v118
	v_cndmask_b32_e32 v98, v98, v108, vcc
	v_cndmask_b32_e32 v100, v100, v107, vcc
	v_mov_b32_dpp v106, v109 quad_perm:[1,0,3,2] row_mask:0xf bank_mask:0xf
	v_cndmask_b32_e32 v101, v101, v109, vcc
	v_cndmask_b32_e32 v105, v105, v106, vcc
	s_mov_b32 s100, 2
	global_store_dwordx4 v110, v[98:101], s[36:37]
	v_pk_fma_f32 v[96:97], v[96:97], v[158:159], v[142:143] op_sel_hi:[1,0,1]
	v_pk_fma_f32 v[94:95], v[94:95], v[158:159], v[140:141] op_sel_hi:[1,0,1]
	v_add_u32_e32 v98, s2, v110
	v_pk_fma_f32 v[100:101], v[30:31], v[158:159], v[148:149] op_sel_hi:[1,0,1]
	v_pk_fma_f32 v[90:91], v[90:91], v[158:159], v[144:145] op_sel_hi:[1,0,1]
	s_mov_b32 s100, 2
	global_store_dwordx4 v98, v[102:105], s[36:37]
	v_pk_fma_f32 v[98:99], v[32:33], v[158:159], v[150:151] op_sel_hi:[1,0,1]
	v_cvt_pk_f16_f32 v100, v100, v101
	v_pk_fma_f32 v[92:93], v[92:93], v[158:159], v[146:147] op_sel_hi:[1,0,1]
	v_cvt_pk_f16_f32 v94, v94, v95
	v_cvt_pk_f16_f32 v95, v96, v97
	v_cvt_pk_f16_f32 v96, v90, v91
	v_mov_b32_e32 v91, v1
	v_pk_fma_f32 v[104:105], v[26:27], v[158:159], v[152:153] op_sel_hi:[1,0,1]
	v_cvt_pk_f16_f32 v98, v98, v99
	v_cvt_pk_f16_f32 v97, v92, v93
	v_mov_b32_e32 v90, v1
	v_mov_b32_dpp v91, v100 quad_perm:[1,0,3,2] row_mask:0xf bank_mask:0xf
	v_mov_b32_e32 v92, v1
	v_cvt_pk_f16_f32 v99, v104, v105
	v_mov_b32_dpp v90, v94 quad_perm:[1,0,3,2] row_mask:0xf bank_mask:0xf
	v_cndmask_b32_e32 v94, v94, v91, vcc
	v_mov_b32_e32 v91, v1
	v_mov_b32_dpp v92, v98 quad_perm:[1,0,3,2] row_mask:0xf bank_mask:0xf
	v_mov_b32_e32 v93, v1
	v_mov_b32_dpp v91, v95 quad_perm:[1,0,3,2] row_mask:0xf bank_mask:0xf
	v_cndmask_b32_e32 v95, v95, v92, vcc
	v_mov_b32_e32 v92, v1
	v_mov_b32_dpp v93, v99 quad_perm:[1,0,3,2] row_mask:0xf bank_mask:0xf
	v_pk_fma_f32 v[102:103], v[28:29], v[158:159], v[154:155] op_sel_hi:[1,0,1]
	v_mov_b32_dpp v92, v96 quad_perm:[1,0,3,2] row_mask:0xf bank_mask:0xf
	v_cndmask_b32_e32 v96, v96, v93, vcc
	v_mov_b32_e32 v93, v1
	v_cvt_pk_f16_f32 v101, v102, v103
	s_mul_i32 s4, s9, 0xa0
	v_cndmask_b32_e32 v91, v91, v98, vcc
	v_mov_b32_dpp v93, v97 quad_perm:[1,0,3,2] row_mask:0xf bank_mask:0xf
	v_mov_b32_e32 v98, v1
	v_add_u32_e32 v102, s4, v110
	v_cndmask_b32_e32 v90, v90, v100, vcc
	v_cndmask_b32_e32 v92, v92, v99, vcc
	v_mov_b32_dpp v98, v101 quad_perm:[1,0,3,2] row_mask:0xf bank_mask:0xf
	v_cndmask_b32_e32 v93, v93, v101, vcc
	v_cndmask_b32_e32 v97, v97, v98, vcc
	s_mov_b32 s100, 2
	global_store_dwordx4 v102, v[90:93], s[36:37]
	v_pk_fma_f32 v[88:89], v[88:89], v[158:159], v[142:143] op_sel:[0,1,0]
; __device__ __forceinline__ unsigned cvtpk_h(float lo, float hi) { f32x2 v = {lo, hi}; h16x2 b = __builtin_convertvector(v, h16x2); return __builtin_bit_cast(unsigned, b); }
; __device__ __forceinline__ void stg_line_pair(void* base, unsigned roA, unsigned rowb, const u32x4 w0, const u32x4 w1, bool odd) {
;     u32x4 a, b;
; #pragma unroll
;     for (int c = 0; c < 4; ++c) { const unsigned p1 = (unsigned)__builtin_amdgcn_update_dpp(0, (int)w1[c], 0xB1, 0xF, 0xF, false), p0 = (unsigned)__builtin_amdgcn_update_dpp(0, (int)w0[c], 0xB1, 0xF, 0xF, false);
;         a[c] = odd ? p1 : w0[c]; b[c] = odd ? w1[c] : p0; }
;     stg_u4(base, roA, a); stg_u4(base, roA + rowb, b);
;     __device__ __forceinline__ void operator()(const f32x4 (&acc)[2][2][4][2], const pg8::Unit& u, int wr, int wc, int fr, int fq) const {
;     ...
;             const bool odd = (fr & 1) != 0;
;             const unsigned offA = base + ((row0 + (unsigned)(wr * 64 + (fr & ~1))) * pitch + coff) * 2u + (odd ? 64u : 0u) + 16u * fq;
; #pragma unroll
;             for (int ai = 0; ai < 2; ++ai)
; #pragma unroll
;                 for (int m = 0; m < 4; ++m) { const unsigned ro = offA + (unsigned)(ai * 8 + m) * rowstep; const float r = rs[ai][m];
;                     u32x4 w[2];
; #pragma unroll
;                     for (int bj = 0; bj < 2; ++bj) { const f32x4 v0 = acc[ai][bj][m][0] * r + bv[bj][0], v1 = acc[ai][bj][m][1] * r + bv[bj][1];
;                         w[bj].x = cvtpk_h(v0[0], v0[1]); w[bj].y = cvtpk_h(v0[2], v0[3]); w[bj].z = cvtpk_h(v1[0], v1[1]); w[bj].w = cvtpk_h(v1[2], v1[3]); }
;                     stg_line_pair(wst, ro, 2u * pitch, w[0], w[1], odd);
;                     asm volatile("" ::: "memory"); }
	v_pk_fma_f32 v[86:87], v[86:87], v[158:159], v[140:141] op_sel:[0,1,0]
	v_add_u32_e32 v90, s2, v102
	v_pk_fma_f32 v[92:93], v[22:23], v[158:159], v[148:149] op_sel:[0,1,0]
	v_pk_fma_f32 v[82:83], v[82:83], v[158:159], v[144:145] op_sel:[0,1,0]
	s_mov_b32 s100, 2
	global_store_dwordx4 v90, v[94:97], s[36:37]
	v_pk_fma_f32 v[90:91], v[24:25], v[158:159], v[150:151] op_sel:[0,1,0]
	v_cvt_pk_f16_f32 v92, v92, v93
	v_pk_fma_f32 v[84:85], v[84:85], v[158:159], v[146:147] op_sel:[0,1,0]
	v_cvt_pk_f16_f32 v86, v86, v87
	v_cvt_pk_f16_f32 v87, v88, v89
	v_cvt_pk_f16_f32 v88, v82, v83
	v_mov_b32_e32 v83, v1
	v_pk_fma_f32 v[96:97], v[18:19], v[158:159], v[152:153] op_sel:[0,1,0]
	v_cvt_pk_f16_f32 v90, v90, v91
	v_cvt_pk_f16_f32 v89, v84, v85
	v_mov_b32_e32 v82, v1
	v_mov_b32_dpp v83, v92 quad_perm:[1,0,3,2] row_mask:0xf bank_mask:0xf
	v_mov_b32_e32 v84, v1
	v_cvt_pk_f16_f32 v91, v96, v97
	v_mov_b32_dpp v82, v86 quad_perm:[1,0,3,2] row_mask:0xf bank_mask:0xf
	v_cndmask_b32_e32 v86, v86, v83, vcc
	v_mov_b32_e32 v83, v1
	v_mov_b32_dpp v84, v90 quad_perm:[1,0,3,2] row_mask:0xf bank_mask:0xf
	v_mov_b32_e32 v85, v1
	v_mov_b32_dpp v83, v87 quad_perm:[1,0,3,2] row_mask:0xf bank_mask:0xf
	v_cndmask_b32_e32 v87, v87, v84, vcc
	v_mov_b32_e32 v84, v1
	v_mov_b32_dpp v85, v91 quad_perm:[1,0,3,2] row_mask:0xf bank_mask:0xf
	v_pk_fma_f32 v[94:95], v[20:21], v[158:159], v[154:155] op_sel:[0,1,0]
	v_mov_b32_dpp v84, v88 quad_perm:[1,0,3,2] row_mask:0xf bank_mask:0xf
	v_cndmask_b32_e32 v88, v88, v85, vcc
	v_mov_b32_e32 v85, v1
	v_cvt_pk_f16_f32 v93, v94, v95
	v_cndmask_b32_e32 v83, v83, v90, vcc
	v_mov_b32_dpp v85, v89 quad_perm:[1,0,3,2] row_mask:0xf bank_mask:0xf
	v_mov_b32_e32 v90, v1
	v_add_u32_e32 v94, s3, v102
	v_cndmask_b32_e32 v82, v82, v92, vcc
	v_cndmask_b32_e32 v84, v84, v91, vcc
	v_mov_b32_dpp v90, v93 quad_perm:[1,0,3,2] row_mask:0xf bank_mask:0xf
	v_cndmask_b32_e32 v85, v85, v93, vcc
	v_cndmask_b32_e32 v89, v89, v90, vcc
	s_mov_b32 s100, 2
	global_store_dwordx4 v94, v[82:85], s[36:37]
	v_pk_fma_f32 v[80:81], v[80:81], v[156:157], v[142:143] op_sel_hi:[1,0,1]
	v_pk_fma_f32 v[78:79], v[78:79], v[156:157], v[140:141] op_sel_hi:[1,0,1]
	v_add_u32_e32 v82, s2, v94
	v_pk_fma_f32 v[84:85], v[14:15], v[156:157], v[148:149] op_sel_hi:[1,0,1]
	v_pk_fma_f32 v[74:75], v[74:75], v[156:157], v[144:145] op_sel_hi:[1,0,1]
	s_mov_b32 s100, 2
	global_store_dwordx4 v82, v[86:89], s[36:37]
	v_pk_fma_f32 v[82:83], v[16:17], v[156:157], v[150:151] op_sel_hi:[1,0,1]
	v_cvt_pk_f16_f32 v84, v84, v85
	v_pk_fma_f32 v[76:77], v[76:77], v[156:157], v[146:147] op_sel_hi:[1,0,1]
	v_cvt_pk_f16_f32 v78, v78, v79
	v_cvt_pk_f16_f32 v79, v80, v81
	v_cvt_pk_f16_f32 v80, v74, v75
	v_mov_b32_e32 v75, v1
	v_pk_fma_f32 v[88:89], v[10:11], v[156:157], v[152:153] op_sel_hi:[1,0,1]
	v_cvt_pk_f16_f32 v82, v82, v83
	v_cvt_pk_f16_f32 v81, v76, v77
	v_mov_b32_e32 v74, v1
	v_mov_b32_dpp v75, v84 quad_perm:[1,0,3,2] row_mask:0xf bank_mask:0xf
	v_mov_b32_e32 v76, v1
	v_cvt_pk_f16_f32 v83, v88, v89
	v_mov_b32_dpp v74, v78 quad_perm:[1,0,3,2] row_mask:0xf bank_mask:0xf
	v_cndmask_b32_e32 v78, v78, v75, vcc
	v_mov_b32_e32 v75, v1
	v_mov_b32_dpp v76, v82 quad_perm:[1,0,3,2] row_mask:0xf bank_mask:0xf
	v_mov_b32_e32 v77, v1
	v_mov_b32_dpp v75, v79 quad_perm:[1,0,3,2] row_mask:0xf bank_mask:0xf
	v_cndmask_b32_e32 v79, v79, v76, vcc
	v_mov_b32_e32 v76, v1
	v_mov_b32_dpp v77, v83 quad_perm:[1,0,3,2] row_mask:0xf bank_mask:0xf
	v_pk_fma_f32 v[86:87], v[12:13], v[156:157], v[154:155] op_sel_hi:[1,0,1]
	v_mov_b32_dpp v76, v80 quad_perm:[1,0,3,2] row_mask:0xf bank_mask:0xf
	v_cndmask_b32_e32 v80, v80, v77, vcc
	v_mov_b32_e32 v77, v1
	v_cvt_pk_f16_f32 v85, v86, v87
	v_cndmask_b32_e32 v75, v75, v82, vcc
	v_mov_b32_dpp v77, v81 quad_perm:[1,0,3,2] row_mask:0xf bank_mask:0xf
	v_mov_b32_e32 v82, v1
	v_add_u32_e32 v86, s3, v94
	v_cndmask_b32_e32 v74, v74, v84, vcc
	v_cndmask_b32_e32 v76, v76, v83, vcc
	v_mov_b32_dpp v82, v85 quad_perm:[1,0,3,2] row_mask:0xf bank_mask:0xf
	v_cndmask_b32_e32 v77, v77, v85, vcc
	v_cndmask_b32_e32 v81, v81, v82, vcc
	s_mov_b32 s100, 2
	global_store_dwordx4 v86, v[74:77], s[36:37]
	v_pk_fma_f32 v[64:65], v[64:65], v[156:157], v[142:143] op_sel:[0,1,0]
	v_pk_fma_f32 v[62:63], v[62:63], v[156:157], v[140:141] op_sel:[0,1,0]
	v_add_u32_e32 v74, s2, v86
	v_pk_fma_f32 v[76:77], v[6:7], v[156:157], v[148:149] op_sel:[0,1,0]
	v_pk_fma_f32 v[58:59], v[58:59], v[156:157], v[144:145] op_sel:[0,1,0]
	s_mov_b32 s100, 2
	global_store_dwordx4 v74, v[78:81], s[36:37]
	v_pk_fma_f32 v[74:75], v[8:9], v[156:157], v[150:151] op_sel:[0,1,0]
	v_cvt_pk_f16_f32 v76, v76, v77
	v_pk_fma_f32 v[60:61], v[60:61], v[156:157], v[146:147] op_sel:[0,1,0]
	v_cvt_pk_f16_f32 v62, v62, v63
	v_cvt_pk_f16_f32 v63, v64, v65
	v_cvt_pk_f16_f32 v64, v58, v59
	v_mov_b32_e32 v59, v1
	v_pk_fma_f32 v[80:81], v[2:3], v[156:157], v[152:153] op_sel:[0,1,0]
	v_cvt_pk_f16_f32 v74, v74, v75
	v_cvt_pk_f16_f32 v65, v60, v61
	v_mov_b32_e32 v58, v1
	v_mov_b32_dpp v59, v76 quad_perm:[1,0,3,2] row_mask:0xf bank_mask:0xf
	v_mov_b32_e32 v60, v1
	v_cvt_pk_f16_f32 v75, v80, v81
	v_mov_b32_dpp v58, v62 quad_perm:[1,0,3,2] row_mask:0xf bank_mask:0xf
	v_cndmask_b32_e32 v62, v62, v59, vcc
	v_mov_b32_e32 v59, v1
	v_mov_b32_dpp v60, v74 quad_perm:[1,0,3,2] row_mask:0xf bank_mask:0xf
	v_mov_b32_e32 v61, v1
	v_mov_b32_dpp v59, v63 quad_perm:[1,0,3,2] row_mask:0xf bank_mask:0xf
	v_cndmask_b32_e32 v63, v63, v60, vcc
	v_mov_b32_e32 v60, v1
	v_mov_b32_dpp v61, v75 quad_perm:[1,0,3,2] row_mask:0xf bank_mask:0xf
	v_pk_fma_f32 v[78:79], v[4:5], v[156:157], v[154:155] op_sel:[0,1,0]
	v_mov_b32_dpp v60, v64 quad_perm:[1,0,3,2] row_mask:0xf bank_mask:0xf
	v_cndmask_b32_e32 v64, v64, v61, vcc
	v_mov_b32_e32 v61, v1
	v_cvt_pk_f16_f32 v77, v78, v79
	v_cndmask_b32_e32 v59, v59, v74, vcc
	v_mov_b32_dpp v61, v65 quad_perm:[1,0,3,2] row_mask:0xf bank_mask:0xf
	v_mov_b32_e32 v74, v1
	v_add_u32_e32 v78, s3, v86
	v_cndmask_b32_e32 v58, v58, v76, vcc
	v_cndmask_b32_e32 v60, v60, v75, vcc
	v_mov_b32_dpp v74, v77 quad_perm:[1,0,3,2] row_mask:0xf bank_mask:0xf
	v_cndmask_b32_e32 v61, v61, v77, vcc
	v_cndmask_b32_e32 v65, v65, v74, vcc
	s_mov_b32 s100, 2
	global_store_dwordx4 v78, v[58:61], s[36:37]
	s_nop 1
	v_add_u32_e32 v58, s2, v78
	s_mov_b32 s100, 2
	global_store_dwordx4 v58, v[62:65], s[36:37]
	s_mov_b64 s[2:3], 0
; #define GAS __attribute__((address_space(1)))
; __device__ __forceinline__ float logsigf(float x) { return fminf(x, 0.f) - 0.6931471805599453f * __builtin_amdgcn_logf(1.f + __builtin_amdgcn_exp2f(-1.4426950408889634f * fabsf(x))); }
;     __device__ __forceinline__ void operator()(const f32x4 (&acc)[2][2][4][2], const pg8::Unit& u, int wr, int wc, int fr, int fq) const {
;     ...
;             if (s == 52) {
;                 if (fq < 2) { const f32x4 g0 = *(const GAS f32x4*)(bg + 8 * fq), g1 = *(const GAS f32x4*)(bg + 8 * fq + 4);
; #pragma unroll
;                     for (int ai = 0; ai < 2; ++ai)
; #pragma unroll
;                         for (int m = 0; m < 4; ++m) { const float r = rs[ai][m]; const f32x4 vi = acc[ai][0][m][0] * r + bv[0][0] + g0; f32x4 vf = acc[ai][0][m][1] * r + bv[0][1] + g1;
;                             vf = (f32x4){logsigf(vf[0]), logsigf(vf[1]), logsigf(vf[2]), logsigf(vf[3])};
;                             const unsigned go = (unsigned)WS_G + (rbase + ai * 128 + m * 16) * 64u + 32u * fq; stg_f4(wst, go, vi); stg_f4(wst, go + 16u, vf); } }
;                 return;
.LBB0_633:
	s_and_b64 vcc, exec, s[2:3]
	s_cbranch_vccz .LBB0_637
	v_cmp_gt_i32_e32 vcc, 2, v200
	s_and_saveexec_b64 s[2:3], vcc
	s_cbranch_execz .LBB0_636
	v_lshlrev_b32_e32 v58, 3, v200
	v_readlane_b32 s4, v253, 5
	v_ashrrev_i32_e32 v59, 31, v58
	v_readlane_b32 s5, v253, 6
	v_lshlrev_b32_e32 v75, 6, v201
	s_waitcnt vmcnt(2)
	v_pk_fma_f32 v[68:69], v[68:69], v[176:177], v[134:135] op_sel_hi:[1,0,1]
	v_lshl_add_u64 v[58:59], v[58:59], 2, s[4:5]
	global_load_dwordx4 v[62:65], v[58:59], off
	s_nop 0
	global_load_dwordx4 v[58:61], v[58:59], off offset:16
	v_pk_fma_f32 v[66:67], v[66:67], v[176:177], v[132:133] op_sel_hi:[1,0,1]
	v_mov_b32_e32 v74, v177
	v_pk_fma_f32 v[72:73], v[72:73], v[176:177], v[138:139] op_sel_hi:[1,0,1]
	v_pk_fma_f32 v[70:71], v[70:71], v[176:177], v[136:137] op_sel_hi:[1,0,1]
	v_pk_fma_f32 v[56:57], v[56:57], v[174:175], v[138:139] op_sel_hi:[1,0,1]
	v_pk_fma_f32 v[54:55], v[54:55], v[174:175], v[136:137] op_sel_hi:[1,0,1]
	v_pk_fma_f32 v[76:77], v[44:45], v[174:175], v[134:135] op_sel_hi:[1,0,1]
	v_pk_fma_f32 v[78:79], v[42:43], v[174:175], v[132:133] op_sel_hi:[1,0,1]
	v_lshl_add_u32 v82, v200, 5, v75
	v_pk_fma_f32 v[52:53], v[52:53], v[74:75], v[138:139] op_sel_hi:[1,0,1]
	v_pk_fma_f32 v[50:51], v[50:51], v[74:75], v[136:137] op_sel_hi:[1,0,1]
	v_pk_fma_f32 v[80:81], v[48:49], v[74:75], v[134:135] op_sel_hi:[1,0,1]
	v_pk_fma_f32 v[74:75], v[46:47], v[74:75], v[132:133] op_sel_hi:[1,0,1]
	s_mov_b32 s4, 0xbfb8aa3b
	v_add_u32_e32 v83, 0x2b00000, v82
	v_add_u32_e32 v84, 0x2b00400, v82
	s_mov_b32 s8, 0x3f317218
	v_pk_fma_f32 v[26:27], v[26:27], v[172:173], v[132:133] op_sel_hi:[1,0,1]
	v_pk_fma_f32 v[28:29], v[28:29], v[172:173], v[134:135] op_sel_hi:[1,0,1]
	v_pk_fma_f32 v[32:33], v[32:33], v[172:173], v[138:139] op_sel_hi:[1,0,1]
	v_pk_fma_f32 v[30:31], v[30:31], v[172:173], v[136:137] op_sel_hi:[1,0,1]
	v_pk_fma_f32 v[10:11], v[10:11], v[170:171], v[132:133] op_sel_hi:[1,0,1]
	v_pk_fma_f32 v[12:13], v[12:13], v[170:171], v[134:135] op_sel_hi:[1,0,1]
	v_pk_fma_f32 v[16:17], v[16:17], v[170:171], v[138:139] op_sel_hi:[1,0,1]
	v_pk_fma_f32 v[14:15], v[14:15], v[170:171], v[136:137] op_sel_hi:[1,0,1]
	s_waitcnt vmcnt(1)
	v_pk_add_f32 v[44:45], v[72:73], v[64:65]
	s_waitcnt vmcnt(0)
	v_pk_add_f32 v[68:69], v[68:69], v[60:61]
	v_pk_add_f32 v[66:67], v[66:67], v[58:59]
	v_pk_add_f32 v[42:43], v[70:71], v[62:63]
	v_pk_add_f32 v[48:49], v[52:53], v[64:65]
	v_pk_add_f32 v[46:47], v[50:51], v[62:63]
	v_pk_add_f32 v[70:71], v[80:81], v[60:61]
	v_pk_add_f32 v[72:73], v[74:75], v[58:59]
	v_pk_add_f32 v[52:53], v[56:57], v[64:65]
	v_pk_add_f32 v[50:51], v[54:55], v[62:63]
	v_pk_add_f32 v[54:55], v[76:77], v[60:61]
	v_pk_add_f32 v[56:57], v[78:79], v[58:59]
	v_mul_f32_e64 v76, |v66|, s4
	v_mul_f32_e64 v77, |v67|, s4
	v_mul_f32_e64 v78, |v68|, s4
	v_mul_f32_e64 v79, |v69|, s4
	v_min_f32_e32 v74, 0, v66
	v_min_f32_e32 v66, 0, v68
	s_mov_b32 s100, 2
	global_store_dwordx4 v83, v[42:45], s[36:37]
	v_min_f32_e32 v68, 0, v72
	s_mov_b32 s100, 2
	global_store_dwordx4 v84, v[46:49], s[36:37]
	v_mul_f32_e64 v42, |v72|, s4
	v_mul_f32_e64 v43, |v73|, s4
	v_min_f32_e32 v72, 0, v70
	v_mul_f32_e64 v44, |v70|, s4
	v_mul_f32_e64 v45, |v71|, s4
	v_min_f32_e32 v70, 0, v56
	v_mul_f32_e64 v46, |v56|, s4
	v_exp_f32_e32 v47, v76
	v_exp_f32_e32 v48, v77
	v_exp_f32_e32 v49, v78
	v_exp_f32_e32 v56, v79
	v_exp_f32_e32 v42, v42
	v_exp_f32_e32 v43, v43
	v_exp_f32_e32 v44, v44
	v_exp_f32_e32 v45, v45
	v_exp_f32_e32 v46, v46
	v_add_f32_e32 v47, 1.0, v47
	v_add_f32_e32 v48, 1.0, v48
	v_add_f32_e32 v49, 1.0, v49
	v_add_f32_e32 v56, 1.0, v56
	v_min_f32_e32 v75, 0, v67
	v_min_f32_e32 v67, 0, v69
	v_min_f32_e32 v69, 0, v73
	v_min_f32_e32 v73, 0, v71
	v_min_f32_e32 v71, 0, v57
	v_mul_f32_e64 v80, |v57|, s4
	v_add_f32_e32 v42, 1.0, v42
	v_add_f32_e32 v43, 1.0, v43
	v_add_f32_e32 v44, 1.0, v44
	v_add_f32_e32 v45, 1.0, v45
	v_log_f32_e32 v57, v47
	v_log_f32_e32 v47, v48
	v_log_f32_e32 v48, v49
	v_log_f32_e32 v49, v56
	v_log_f32_e32 v56, v42
	v_log_f32_e32 v76, v43
	v_log_f32_e32 v44, v44
	v_log_f32_e32 v45, v45
	v_add_f32_e32 v46, 1.0, v46
	v_log_f32_e32 v77, v46
	v_xor_b32_e32 v43, 0x80000000, v49
	v_xor_b32_e32 v42, 0x80000000, v48
	v_xor_b32_e32 v47, 0x80000000, v47
	v_xor_b32_e32 v46, 0x80000000, v57
	v_xor_b32_e32 v49, 0x80000000, v45
	v_xor_b32_e32 v48, 0x80000000, v44
	v_xor_b32_e32 v57, 0x80000000, v76
	v_xor_b32_e32 v56, 0x80000000, v56
	v_pk_fma_f32 v[44:45], v[42:43], s[8:9], v[66:67] op_sel_hi:[1,0,1]
	v_pk_fma_f32 v[42:43], v[46:47], s[8:9], v[74:75] op_sel_hi:[1,0,1]
	v_pk_fma_f32 v[48:49], v[48:49], s[8:9], v[72:73] op_sel_hi:[1,0,1]
	v_pk_fma_f32 v[46:47], v[56:57], s[8:9], v[68:69] op_sel_hi:[1,0,1]
	s_mov_b32 s100, 2
	global_store_dwordx4 v83, v[42:45], s[36:37] offset:16
	s_mov_b32 s100, 2
	global_store_dwordx4 v84, v[46:49], s[36:37] offset:16
	v_pk_add_f32 v[26:27], v[26:27], v[58:59]
	v_exp_f32_e32 v42, v80
	v_mul_f32_e64 v43, |v54|, s4
	v_mul_f32_e64 v44, |v55|, s4
	v_exp_f32_e32 v43, v43
	v_exp_f32_e32 v44, v44
	v_add_f32_e32 v42, 1.0, v42
	v_log_f32_e32 v46, v42
	v_add_f32_e32 v42, 1.0, v43
	v_add_f32_e32 v43, 1.0, v44
	v_log_f32_e32 v44, v43
	v_log_f32_e32 v47, v42
	v_min_f32_e32 v42, 0, v54
	v_min_f32_e32 v43, 0, v55
	v_xor_b32_e32 v45, 0x80000000, v44
	v_xor_b32_e32 v44, 0x80000000, v47
	v_pk_fma_f32 v[44:45], v[44:45], s[8:9], v[42:43] op_sel_hi:[1,0,1]
	v_xor_b32_e32 v43, 0x80000000, v46
	v_xor_b32_e32 v42, 0x80000000, v77
	v_pk_fma_f32 v[42:43], v[42:43], s[8:9], v[70:71] op_sel_hi:[1,0,1]
	v_add_u32_e32 v46, 0x2b00800, v82
	s_mov_b32 s100, 2
	global_store_dwordx4 v46, v[50:53], s[36:37]
	s_mov_b32 s100, 2
	global_store_dwordx4 v46, v[42:45], s[36:37] offset:16
; __device__ __forceinline__ float logsigf(float x) { return fminf(x, 0.f) - 0.6931471805599453f * __builtin_amdgcn_logf(1.f + __builtin_amdgcn_exp2f(-1.4426950408889634f * fabsf(x))); }
;     __device__ __forceinline__ void operator()(const f32x4 (&acc)[2][2][4][2], const pg8::Unit& u, int wr, int wc, int fr, int fq) const {
;     ...
; #pragma unroll
;                     for (int ai = 0; ai < 2; ++ai)
; #pragma unroll
;                         for (int m = 0; m < 4; ++m) { const float r = rs[ai][m]; const f32x4 vi = acc[ai][0][m][0] * r + bv[0][0] + g0; f32x4 vf = acc[ai][0][m][1] * r + bv[0][1] + g1;
;                             vf = (f32x4){logsigf(vf[0]), logsigf(vf[1]), logsigf(vf[2]), logsigf(vf[3])};
;                             const unsigned go = (unsigned)WS_G + (rbase + ai * 128 + m * 16) * 64u + 32u * fq; stg_f4(wst, go, vi); stg_f4(wst, go + 16u, vf); } }
;                 return;
	v_pk_add_f32 v[28:29], v[28:29], v[60:61]
	v_pk_add_f32 v[32:33], v[32:33], v[64:65]
	v_mov_b32_e32 v42, v175
	v_pk_fma_f32 v[34:35], v[34:35], v[42:43], v[132:133] op_sel_hi:[1,0,1]
	v_pk_fma_f32 v[40:41], v[40:41], v[42:43], v[138:139] op_sel_hi:[1,0,1]
	v_pk_add_f32 v[34:35], v[34:35], v[58:59]
	v_pk_fma_f32 v[38:39], v[38:39], v[42:43], v[136:137] op_sel_hi:[1,0,1]
	v_mul_f32_e64 v43, |v34|, s4
	v_exp_f32_e32 v43, v43
	v_pk_add_f32 v[40:41], v[40:41], v[64:65]
	v_pk_add_f32 v[38:39], v[38:39], v[62:63]
	v_pk_add_f32 v[30:31], v[30:31], v[62:63]
	v_pk_fma_f32 v[36:37], v[36:37], v[42:43], v[134:135] op_sel_hi:[1,0,1]
	v_min_f32_e32 v42, 0, v34
	v_add_f32_e32 v34, 1.0, v43
	v_pk_add_f32 v[36:37], v[36:37], v[60:61]
	v_log_f32_e32 v44, v34
	v_mul_f32_e64 v34, |v35|, s4
	v_min_f32_e32 v43, 0, v35
	v_exp_f32_e32 v34, v34
	v_mul_f32_e64 v35, |v36|, s4
	v_mul_f32_e64 v45, |v37|, s4
	v_exp_f32_e32 v35, v35
	v_exp_f32_e32 v45, v45
	v_add_f32_e32 v34, 1.0, v34
	v_log_f32_e32 v46, v34
	v_add_f32_e32 v34, 1.0, v35
	v_add_f32_e32 v35, 1.0, v45
	v_log_f32_e32 v45, v35
	v_log_f32_e32 v47, v34
	v_min_f32_e32 v34, 0, v36
	v_min_f32_e32 v35, 0, v37
	v_xor_b32_e32 v37, 0x80000000, v45
	v_xor_b32_e32 v36, 0x80000000, v47
	v_pk_fma_f32 v[36:37], v[36:37], s[8:9], v[34:35] op_sel_hi:[1,0,1]
	v_xor_b32_e32 v35, 0x80000000, v46
	v_xor_b32_e32 v34, 0x80000000, v44
	v_pk_fma_f32 v[34:35], v[34:35], s[8:9], v[42:43] op_sel_hi:[1,0,1]
	v_add_u32_e32 v42, 0x2b00c00, v82
	s_mov_b32 s100, 2
	global_store_dwordx4 v42, v[38:41], s[36:37]
	s_mov_b32 s100, 2
	global_store_dwordx4 v42, v[34:37], s[36:37] offset:16
	v_pk_add_f32 v[10:11], v[10:11], v[58:59]
	v_mul_f32_e64 v38, |v29|, s4
	v_mul_f32_e64 v34, |v26|, s4
	v_exp_f32_e32 v35, v34
	v_min_f32_e32 v34, 0, v26
	v_exp_f32_e32 v38, v38
	v_add_u32_e32 v36, 0x2b02000, v82
	v_add_f32_e32 v26, 1.0, v35
	v_log_f32_e32 v37, v26
	v_mul_f32_e64 v26, |v27|, s4
	v_min_f32_e32 v35, 0, v27
	v_exp_f32_e32 v26, v26
	v_mul_f32_e64 v27, |v28|, s4
	v_exp_f32_e32 v27, v27
	v_pk_add_f32 v[12:13], v[12:13], v[60:61]
	v_add_f32_e32 v26, 1.0, v26
	v_log_f32_e32 v39, v26
	v_add_f32_e32 v26, 1.0, v27
	v_add_f32_e32 v27, 1.0, v38
	v_log_f32_e32 v38, v27
	v_log_f32_e32 v40, v26
	v_min_f32_e32 v26, 0, v28
	v_min_f32_e32 v27, 0, v29
	v_xor_b32_e32 v29, 0x80000000, v38
	v_xor_b32_e32 v28, 0x80000000, v40
	v_pk_fma_f32 v[28:29], v[28:29], s[8:9], v[26:27] op_sel_hi:[1,0,1]
	v_xor_b32_e32 v27, 0x80000000, v39
	v_xor_b32_e32 v26, 0x80000000, v37
	v_pk_fma_f32 v[26:27], v[26:27], s[8:9], v[34:35] op_sel_hi:[1,0,1]
	s_mov_b32 s100, 2
	global_store_dwordx4 v36, v[30:33], s[36:37]
	s_mov_b32 s100, 2
	global_store_dwordx4 v36, v[26:29], s[36:37] offset:16
	v_pk_add_f32 v[16:17], v[16:17], v[64:65]
	v_pk_add_f32 v[14:15], v[14:15], v[62:63]
	v_mov_b32_e32 v26, v173
	v_pk_fma_f32 v[18:19], v[18:19], v[26:27], v[132:133] op_sel_hi:[1,0,1]
	v_pk_fma_f32 v[24:25], v[24:25], v[26:27], v[138:139] op_sel_hi:[1,0,1]
	v_pk_add_f32 v[18:19], v[18:19], v[58:59]
	v_pk_fma_f32 v[22:23], v[22:23], v[26:27], v[136:137] op_sel_hi:[1,0,1]
	v_mul_f32_e64 v27, |v18|, s4
	v_exp_f32_e32 v27, v27
	v_pk_add_f32 v[24:25], v[24:25], v[64:65]
	v_pk_add_f32 v[22:23], v[22:23], v[62:63]
	v_pk_fma_f32 v[20:21], v[20:21], v[26:27], v[134:135] op_sel_hi:[1,0,1]
	v_min_f32_e32 v26, 0, v18
	v_add_f32_e32 v18, 1.0, v27
	v_pk_add_f32 v[20:21], v[20:21], v[60:61]
	v_log_f32_e32 v28, v18
	v_mul_f32_e64 v18, |v19|, s4
	v_min_f32_e32 v27, 0, v19
	v_exp_f32_e32 v18, v18
	v_mul_f32_e64 v19, |v20|, s4
	v_mul_f32_e64 v29, |v21|, s4
	v_exp_f32_e32 v19, v19
	v_exp_f32_e32 v29, v29
	v_add_f32_e32 v18, 1.0, v18
	v_log_f32_e32 v30, v18
	v_add_f32_e32 v18, 1.0, v19
	v_add_f32_e32 v19, 1.0, v29
	v_log_f32_e32 v29, v19
	v_log_f32_e32 v31, v18
	v_min_f32_e32 v18, 0, v20
	v_min_f32_e32 v19, 0, v21
	v_xor_b32_e32 v21, 0x80000000, v29
	v_xor_b32_e32 v20, 0x80000000, v31
	v_pk_fma_f32 v[20:21], v[20:21], s[8:9], v[18:19] op_sel_hi:[1,0,1]
	v_xor_b32_e32 v19, 0x80000000, v30
	v_xor_b32_e32 v18, 0x80000000, v28
	v_pk_fma_f32 v[18:19], v[18:19], s[8:9], v[26:27] op_sel_hi:[1,0,1]
	v_add_u32_e32 v26, 0x2b02400, v82
	s_mov_b32 s100, 2
	global_store_dwordx4 v26, v[22:25], s[36:37]
	s_mov_b32 s100, 2
	global_store_dwordx4 v26, v[18:21], s[36:37] offset:16
	s_nop 1
	v_mul_f32_e64 v18, |v10|, s4
	v_exp_f32_e32 v19, v18
	v_min_f32_e32 v18, 0, v10
	v_mul_f32_e64 v21, |v13|, s4
	v_exp_f32_e32 v21, v21
	v_add_f32_e32 v10, 1.0, v19
	v_log_f32_e32 v20, v10
	v_mul_f32_e64 v10, |v11|, s4
	v_min_f32_e32 v19, 0, v11
	v_exp_f32_e32 v10, v10
	v_mul_f32_e64 v11, |v12|, s4
	v_exp_f32_e32 v11, v11
	v_add_f32_e32 v10, 1.0, v10
	v_log_f32_e32 v22, v10
	v_add_f32_e32 v10, 1.0, v11
	v_add_f32_e32 v11, 1.0, v21
	v_log_f32_e32 v21, v11
	v_log_f32_e32 v23, v10
	v_min_f32_e32 v10, 0, v12
	v_min_f32_e32 v11, 0, v13
	v_xor_b32_e32 v13, 0x80000000, v21
	v_xor_b32_e32 v12, 0x80000000, v23
	v_pk_fma_f32 v[12:13], v[12:13], s[8:9], v[10:11] op_sel_hi:[1,0,1]
	v_xor_b32_e32 v11, 0x80000000, v22
	v_xor_b32_e32 v10, 0x80000000, v20
	v_pk_fma_f32 v[10:11], v[10:11], s[8:9], v[18:19] op_sel_hi:[1,0,1]
	v_add_u32_e32 v18, 0x2b02800, v82
	s_mov_b32 s100, 2
	global_store_dwordx4 v18, v[14:17], s[36:37]
	s_mov_b32 s100, 2
	global_store_dwordx4 v18, v[10:13], s[36:37] offset:16
	s_nop 1
	v_mov_b32_e32 v10, v171
	v_pk_fma_f32 v[2:3], v[2:3], v[10:11], v[132:133] op_sel_hi:[1,0,1]
	v_pk_fma_f32 v[8:9], v[8:9], v[10:11], v[138:139] op_sel_hi:[1,0,1]
	v_pk_add_f32 v[2:3], v[2:3], v[58:59]
	v_pk_fma_f32 v[6:7], v[6:7], v[10:11], v[136:137] op_sel_hi:[1,0,1]
	v_mul_f32_e64 v11, |v2|, s4
	v_exp_f32_e32 v11, v11
	v_pk_add_f32 v[8:9], v[8:9], v[64:65]
	v_pk_add_f32 v[6:7], v[6:7], v[62:63]
	v_pk_fma_f32 v[4:5], v[4:5], v[10:11], v[134:135] op_sel_hi:[1,0,1]
	v_min_f32_e32 v10, 0, v2
	v_add_f32_e32 v2, 1.0, v11
	v_pk_add_f32 v[4:5], v[4:5], v[60:61]
	v_log_f32_e32 v12, v2
	v_mul_f32_e64 v2, |v3|, s4
	v_min_f32_e32 v11, 0, v3
	v_exp_f32_e32 v2, v2
	v_mul_f32_e64 v3, |v4|, s4
	v_mul_f32_e64 v13, |v5|, s4
	v_exp_f32_e32 v3, v3
	v_exp_f32_e32 v13, v13
	v_add_f32_e32 v2, 1.0, v2
	v_log_f32_e32 v14, v2
	v_add_f32_e32 v2, 1.0, v3
	v_add_f32_e32 v3, 1.0, v13
	v_log_f32_e32 v13, v3
	v_log_f32_e32 v15, v2
	v_min_f32_e32 v2, 0, v4
	v_min_f32_e32 v3, 0, v5
	v_xor_b32_e32 v5, 0x80000000, v13
	v_xor_b32_e32 v4, 0x80000000, v15
	v_pk_fma_f32 v[4:5], v[4:5], s[8:9], v[2:3] op_sel_hi:[1,0,1]
	v_xor_b32_e32 v3, 0x80000000, v14
	v_xor_b32_e32 v2, 0x80000000, v12
	v_pk_fma_f32 v[2:3], v[2:3], s[8:9], v[10:11] op_sel_hi:[1,0,1]
	v_add_u32_e32 v10, 0x2b02c00, v82
	s_mov_b32 s100, 2
	global_store_dwordx4 v10, v[6:9], s[36:37]
	s_mov_b32 s100, 2
	global_store_dwordx4 v10, v[2:5], s[36:37] offset:16

; __global__ void __launch_bounds__(NTHREADS, 2) mega(Args a) {
	.amdhsa_kernel _Z4mega4Args
		.amdhsa_group_segment_fixed_size 0
		.amdhsa_private_segment_fixed_size 0
		.amdhsa_kernarg_size 416
		.amdhsa_user_sgpr_count 2
		.amdhsa_user_sgpr_dispatch_ptr 0
		.amdhsa_user_sgpr_queue_ptr 0
		.amdhsa_user_sgpr_kernarg_segment_ptr 1
		.amdhsa_user_sgpr_dispatch_id 0
		.amdhsa_user_sgpr_kernarg_preload_length 0
		.amdhsa_user_sgpr_kernarg_preload_offset 0
		.amdhsa_user_sgpr_private_segment_size 0
		.amdhsa_uses_dynamic_stack 0
		.amdhsa_enable_private_segment 0
		.amdhsa_system_sgpr_workgroup_id_x 1
		.amdhsa_system_sgpr_workgroup_id_y 0
		.amdhsa_system_sgpr_workgroup_id_z 0
		.amdhsa_system_sgpr_workgroup_info 0
		.amdhsa_system_vgpr_workitem_id 0
		.amdhsa_next_free_vgpr 256
		.amdhsa_next_free_sgpr 102
		.amdhsa_accum_offset 256
		.amdhsa_reserve_vcc 1
		.amdhsa_float_round_mode_32 0
		.amdhsa_float_round_mode_16_64 0
		.amdhsa_float_denorm_mode_32 3
		.amdhsa_float_denorm_mode_16_64 3
		.amdhsa_dx10_clamp 1
		.amdhsa_ieee_mode 1
		.amdhsa_fp16_overflow 0
		.amdhsa_tg_split 0
		.amdhsa_exception_fp_ieee_invalid_op 0
		.amdhsa_exception_fp_denorm_src 0
		.amdhsa_exception_fp_ieee_div_zero 0
		.amdhsa_exception_fp_ieee_overflow 0
		.amdhsa_exception_fp_ieee_underflow 0
		.amdhsa_exception_fp_ieee_inexact 0
		.amdhsa_exception_int_div_zero 0
	.end_amdhsa_kernel

; __global__ void __launch_bounds__(NTHREADS, 2) mega(Args a) {
amdhsa.kernels:
  - .agpr_count:     0
    .args:
      - .offset:         0
        .size:           160
        .value_kind:     by_value
      - .offset:         160
        .size:           4
        .value_kind:     hidden_block_count_x
      - .offset:         164
        .size:           4
        .value_kind:     hidden_block_count_y
      - .offset:         168
        .size:           4
        .value_kind:     hidden_block_count_z
      - .offset:         172
        .size:           2
        .value_kind:     hidden_group_size_x
      - .offset:         174
        .size:           2
        .value_kind:     hidden_group_size_y
      - .offset:         176
        .size:           2
        .value_kind:     hidden_group_size_z
      - .offset:         178
        .size:           2
        .value_kind:     hidden_remainder_x
      - .offset:         180
        .size:           2
        .value_kind:     hidden_remainder_y
      - .offset:         182
        .size:           2
        .value_kind:     hidden_remainder_z
      - .offset:         200
        .size:           8
        .value_kind:     hidden_global_offset_x
      - .offset:         208
        .size:           8
        .value_kind:     hidden_global_offset_y
      - .offset:         216
        .size:           8
        .value_kind:     hidden_global_offset_z
      - .offset:         224
        .size:           2
        .value_kind:     hidden_grid_dims
      - .offset:         280
        .size:           4
        .value_kind:     hidden_dynamic_lds_size
    .group_segment_fixed_size: 0
    .kernarg_segment_align: 8
    .kernarg_segment_size: 416
    .language:       OpenCL C
    .language_version:
      - 2
      - 0
    .max_flat_workgroup_size: 512
    .name:           _Z4mega4Args
    .private_segment_fixed_size: 0
    .sgpr_count:     108
    .sgpr_spill_count: 295
    .symbol:         _Z4mega4Args.kd
    .uniform_work_group_size: 1
    .uses_dynamic_stack: false
    .vgpr_count:     256
    .vgpr_spill_count: 0
    .wavefront_size: 64
